# GEMM K loops: first two load segments after a tile epilogue wait with vmcnt relaxed by the 16 result stores (peeled copy); NA attention conflict-free K swizzle
# speedup vs baseline: 1.0011x; 1.0011x over previous
; #define PG8_STAGE(bufoff, gbase, voff) do { _Pragma("unroll") for (int _i = 0; _i < 2; ++_i) \
;     __builtin_amdgcn_global_load_lds((const unsigned*)((const char*)(gbase) + (voff)[_i]), (LAS unsigned*)(lds + (bufoff) + ldsw + _i * 8192), 16, 0, 0); } while (0)
; #define PG8_WAIT_V(n) asm volatile("s_waitcnt vmcnt(" #n ")" ::: "memory")
; #define PG8_BAR __builtin_amdgcn_s_barrier()
; template <class Epi, class Sched, bool ALIGN_EPI = true>
; __device__ __forceinline__ void gemm_phase(LAS unsigned char* lds, const Gemm g, const Sched& S, const Epi& E) {
;     ...
;   for (int i = 0; i < 2; ++i) { int R, C; stage_rc(tid * 16 + i * 8192, R, C); const int Rb = Epi::PERM ? ((R & ~31) + perm32(R & 31)) : R;
;     voffA[i] = (unsigned)(R * g.lda + C) * 2u; voffB[i] = (unsigned)(Rb * g.ldb + C) * 2u; }
;   const size_t koffL = (size_t)(nt - 1) * (BK * 2);
;   const size_t hstepA = (size_t)HALF * g.lda * 2, hstepB = (size_t)HALF * g.ldb * 2;
;   const size_t tstepA = 2 * hstepA, tstepB = 2 * hstepB;
;   const unsigned ldsw = (unsigned)wid * 1024u;
;   const int aoff = lds_byte(wr * 64 + fr, fq * 8), boff = lds_byte(wc * 32 + fr, fq * 8);
;     ...
;   Unit cur, nxt; int ui = 0;
;   if (!S.next(0, cur)) return;
;   f32x4 acc[2][2][4][2];
; #pragma unroll
;   for (int a = 0; a < 2; ++a)
; #pragma unroll
;     for (int b = 0; b < 2; ++b)
; #pragma unroll
;       for (int m = 0; m < 4; ++m)
; #pragma unroll
;         for (int n = 0; n < 2; ++n) acc[a][b][m][n] = (f32x4){0.f, 0.f, 0.f, 0.f};
;   bf16x8 At[4][2], B0[2][2], B1[2][2];
;   ptrdiff_t kstep = cur.kr ? -(ptrdiff_t)(BK * 2) : (ptrdiff_t)(BK * 2);
;   const char* cA = (const char*)g.A + (size_t)cur.pm * tstepA + cur.kb + (cur.kr ? koffL : 0); const char* cB = (const char*)g.Bt + (size_t)cur.pn * tstepB + cur.kb + (cur.kr ? koffL : 0);
;   PG8_STAGE(PG8_SB(0, 0), cB, voffB); PG8_STAGE(PG8_SB(0, 1), cB + hstepB, voffB); PG8_STAGE(PG8_SA(0, 0), cA, voffA); PG8_STAGE(PG8_SA(0, 1), cA + hstepA, voffA);
;   if (wr == 1) PG8_BAR;
;   PG8_WAIT_V(2); PG8_BAR;
;   PG8_STAGE(PG8_SB(1, 0), cB + kstep, voffB); PG8_STAGE(PG8_SA(1, 0), cA + kstep, voffA); PG8_STAGE(PG8_SB(1, 1), cB + hstepB + kstep, voffB);
;   PG8_WAIT_V(6); PG8_BAR;
.LBB0_195:
	s_lshl_b32 s8, s8, 5
	s_and_b32 s14, s8, 0x60
	s_mov_b64 s[8:9], 0x80
	s_add_i32 m0, s3, 0x18000
	v_lshl_add_u64 v[6:7], v[6:7], 0, s[8:9]
	s_lshl_b32 s11, s10, 13
	s_lshl_b32 s15, s14, 7
	s_waitcnt vmcnt(2)
	s_barrier
	global_load_lds_dwordx4 v[6:7], off
	v_lshl_add_u64 v[4:5], v[4:5], 0, s[8:9]
	s_add_i32 m0, s3, 0x1a000
	s_add_i32 s31, s3, 0x8000
	s_add_i32 s33, s3, 0xa000
	global_load_lds_dwordx4 v[4:5], off
	v_lshl_add_u64 v[0:1], v[0:1], 0, s[8:9]
	s_mov_b32 m0, s31
	s_add_u32 s12, s24, 0x80080
	global_load_lds_dwordx4 v[0:1], off
	v_lshl_add_u64 v[0:1], v[2:3], 0, s[8:9]
	s_mov_b32 m0, s33
	s_addc_u32 s13, s25, 0
	global_load_lds_dwordx4 v[0:1], off
	s_add_i32 m0, s3, 0x1c000
	v_lshl_add_u64 v[0:1], s[12:13], 0, v[132:133]
	global_load_lds_dwordx4 v[0:1], off
	v_lshl_add_u64 v[0:1], s[12:13], 0, v[128:129]
	s_add_i32 m0, s3, 0x1e000
	s_cmpk_lt_u32 s5, 0x100
	global_load_lds_dwordx4 v[0:1], off
	v_lshrrev_b32_e32 v1, 1, v10
	v_and_b32_e32 v1, 24, v1
	v_and_b32_e32 v0, 15, v10
	v_lshlrev_b32_e32 v2, 1, v1
	v_lshl_or_b32 v148, s10, 6, v0
	v_lshl_or_b32 v0, v0, 6, v2
	v_lshlrev_b32_e32 v2, 2, v10
	v_and_b32_e32 v2, 32, v2
	v_bitop3_b32 v3, v0, s11, v2 bitop3:0xde
	v_bitop3_b32 v149, v0, s15, v2 bitop3:0xde
	v_lshlrev_b32_e32 v0, 15, v13
	v_and_b32_e32 v0, 0xffff0000, v0
	v_or_b32_e32 v150, s14, v1
	v_lshl_add_u32 v0, v12, 12, v0
	v_and_b32_e32 v1, 1, v13
	v_lshl_or_b32 v0, v1, 6, v0
	v_lshl_add_u32 v136, v14, 1, v0
	v_lshlrev_b32_e32 v0, 15, v8
	v_and_b32_e32 v0, 0xffff0000, v0
	s_waitcnt vmcnt(6)
	v_lshl_add_u32 v0, v9, 12, v0
	v_and_b32_e32 v1, 1, v8
	s_cselect_b64 s[10:11], -1, 0
	v_lshl_or_b32 v0, v1, 6, v0
	s_add_i32 s36, 0, 0x10000
	s_add_i32 s37, 0, 0x14000
	s_sext_i32_i16 s39, s4
	s_ashr_i32 s34, s86, 31
	s_mov_b32 s35, s86
	v_mov_b32_e32 v137, v133
	v_lshl_add_u32 v138, v11, 1, v0
	v_mov_b32_e32 v139, v133
	v_mov_b64_e32 v[140:141], 0x5a0
	v_mov_b64_e32 v[142:143], 0x59f
	v_add_u32_e32 v151, s36, v149
	v_add_u32_e32 v152, s37, v149
	v_add_u32_e32 v153, 0, v3
	s_movk_i32 s38, 0x2800
	s_barrier
	s_mov_b32 s98, 0
	s_branch .LBB0_198

; #define PG8_STAGE(bufoff, gbase, voff) do { _Pragma("unroll") for (int _i = 0; _i < 2; ++_i) \
;     __builtin_amdgcn_global_load_lds((const unsigned*)((const char*)(gbase) + (voff)[_i]), (LAS unsigned*)(lds + (bufoff) + ldsw + _i * 8192), 16, 0, 0); } while (0)
; #define PG8_LDA(dst, b, h) do { _Pragma("unroll") for (int m = 0; m < 4; ++m) _Pragma("unroll") for (int k = 0; k < 2; ++k) dst[m][k] = *(const LAS bf16x8*)(lds + PG8_SA(b, h) + aoff + m * 2048 + k * 1024); } while (0)
; #define PG8_LDB(dst, b, h) do { _Pragma("unroll") for (int n = 0; n < 2; ++n) _Pragma("unroll") for (int k = 0; k < 2; ++k) dst[n][k] = *(const LAS bf16x8*)(lds + PG8_SB(b, h) + boff + n * 2048 + k * 1024); } while (0)
; #define PG8_WAIT_V(n) asm volatile("s_waitcnt vmcnt(" #n ")" ::: "memory")
; #define PG8_WAIT_L(n) asm volatile("s_waitcnt lgkmcnt(" #n ")" ::: "memory")
; #define PG8_BAR __builtin_amdgcn_s_barrier()
; template <class Epi, class Sched, bool ALIGN_EPI = true>
; __device__ __forceinline__ void gemm_phase(LAS unsigned char* lds, const Gemm g, const Sched& S, const Epi& E) {
;     ...
;     const bool has_next = S.next(ui + 1, nxt);
;     const ptrdiff_t kstepN = has_next ? (nxt.kr ? -(ptrdiff_t)(BK * 2) : (ptrdiff_t)(BK * 2)) : kstep;
;     const char* nA = has_next ? (const char*)g.A + (size_t)nxt.pm * tstepA + nxt.kb + (nxt.kr ? koffL : 0) : cA; const char* nB = has_next ? (const char*)g.Bt + (size_t)nxt.pn * tstepB + nxt.kb + (nxt.kr ? koffL : 0) : cB;
;     for (int t = 0; t < nt; t += 2) {
;       const bool last = (t == nt - 2);
;       const char* a1 = cA + (ptrdiff_t)(t + 1) * kstep;
;       const char* a2 = last ? nA : cA + (ptrdiff_t)(t + 2) * kstep; const char* b2 = last ? nB : cB + (ptrdiff_t)(t + 2) * kstep;
;       const char* a3 = a2 + (last ? kstepN : kstep); const char* b3 = b2 + (last ? kstepN : kstep);
;       PG8_LDB(B0, 0, 0); PG8_LDB(B1, 0, 1); PG8_SCHED; PG8_LDA(At, 0, 0); PG8_STAGE(PG8_SA(1, 1), a1 + hstepA, voffA);
;       PG8_WAIT_V(8); PG8_WAIT_L(0); PG8_BAR; PG8_MMA(0, 0, At, B0); PG8_MMA(0, 1, At, B1); PG8_BAR; PG8_SCHED;
;     ...
; #pragma unroll
;     for (int a = 0; a < 2; ++a)
; #pragma unroll
;       for (int b = 0; b < 2; ++b)
; #pragma unroll
;         for (int m = 0; m < 4; ++m)
; #pragma unroll
;           for (int n = 0; n < 2; ++n) acc[a][b][m][n] = (f32x4){0.f, 0.f, 0.f, 0.f};
;     cur = nxt; cA = nA; cB = nB; kstep = kstepN; ++ui;
.LBB0_200:
	s_ashr_i32 s15, s14, 31
	s_lshl_b64 s[16:17], s[14:15], 20
	v_readlane_b32 s18, v248, 10
	v_readlane_b32 s19, v248, 11
	s_add_u32 s16, s18, s16
	s_addc_u32 s17, s19, s17
	s_and_b64 s[18:19], s[4:5], exec
	s_cselect_b32 s15, s17, s23
	s_cselect_b32 s40, s16, s22
	s_ashr_i32 s13, s12, 31
	s_lshl_b64 s[18:19], s[12:13], 20
	s_add_u32 s18, s80, s18
	s_addc_u32 s19, s81, s19
	s_and_b64 s[26:27], s[4:5], exec
	s_cselect_b32 s13, s19, s25
	s_cselect_b32 s41, s18, s24
	s_add_u32 s22, s22, 0x80080
	s_addc_u32 s23, s23, 0
	s_add_u32 s42, s24, 0x100
	v_mov_b32_e32 v0, 0
	s_addc_u32 s43, s25, 0
	s_mov_b32 s44, -2
	v_mov_b32_e32 v1, v0
	v_mov_b32_e32 v2, v0
	v_mov_b32_e32 v3, v0
	v_mov_b32_e32 v4, v0
	v_mov_b32_e32 v5, v0
	v_mov_b32_e32 v6, v0
	v_mov_b32_e32 v7, v0
	v_mov_b32_e32 v8, v0
	v_mov_b32_e32 v9, v0
	v_mov_b32_e32 v10, v0
	v_mov_b32_e32 v11, v0
	v_mov_b32_e32 v16, v0
	v_mov_b32_e32 v17, v0
	v_mov_b32_e32 v18, v0
	v_mov_b32_e32 v19, v0
	v_mov_b32_e32 v24, v0
	v_mov_b32_e32 v25, v0
	v_mov_b32_e32 v26, v0
	v_mov_b32_e32 v27, v0
	v_mov_b32_e32 v32, v0
	v_mov_b32_e32 v33, v0
	v_mov_b32_e32 v34, v0
	v_mov_b32_e32 v35, v0
	v_mov_b32_e32 v40, v0
	v_mov_b32_e32 v41, v0
	v_mov_b32_e32 v42, v0
	v_mov_b32_e32 v43, v0
	v_mov_b32_e32 v48, v0
	v_mov_b32_e32 v49, v0
	v_mov_b32_e32 v50, v0
	v_mov_b32_e32 v51, v0
	v_mov_b32_e32 v12, v0
	v_mov_b32_e32 v13, v0
	v_mov_b32_e32 v14, v0
	v_mov_b32_e32 v15, v0
	v_mov_b32_e32 v20, v0
	v_mov_b32_e32 v21, v0
	v_mov_b32_e32 v22, v0
	v_mov_b32_e32 v23, v0
	v_mov_b32_e32 v28, v0
	v_mov_b32_e32 v29, v0
	v_mov_b32_e32 v30, v0
	v_mov_b32_e32 v31, v0
	v_mov_b32_e32 v36, v0
	v_mov_b32_e32 v37, v0
	v_mov_b32_e32 v38, v0
	v_mov_b32_e32 v39, v0
	v_mov_b32_e32 v44, v0
	v_mov_b32_e32 v45, v0
	v_mov_b32_e32 v46, v0
	v_mov_b32_e32 v47, v0
	v_mov_b32_e32 v52, v0
	v_mov_b32_e32 v53, v0
	v_mov_b32_e32 v54, v0
	v_mov_b32_e32 v55, v0
	v_mov_b32_e32 v56, v0
	v_mov_b32_e32 v57, v0
	v_mov_b32_e32 v58, v0
	v_mov_b32_e32 v59, v0
	v_mov_b32_e32 v60, v0
	v_mov_b32_e32 v61, v0
	v_mov_b32_e32 v62, v0
	v_mov_b32_e32 v63, v0
	v_mov_b32_e32 v64, v0
	v_mov_b32_e32 v65, v0
	v_mov_b32_e32 v66, v0
	v_mov_b32_e32 v67, v0
	v_mov_b32_e32 v68, v0
	v_mov_b32_e32 v69, v0
	v_mov_b32_e32 v70, v0
	v_mov_b32_e32 v71, v0
	v_mov_b32_e32 v72, v0
	v_mov_b32_e32 v73, v0
	v_mov_b32_e32 v74, v0
	v_mov_b32_e32 v75, v0
	v_mov_b32_e32 v80, v0
	v_mov_b32_e32 v81, v0
	v_mov_b32_e32 v82, v0
	v_mov_b32_e32 v83, v0
	v_mov_b32_e32 v88, v0
	v_mov_b32_e32 v89, v0
	v_mov_b32_e32 v90, v0
	v_mov_b32_e32 v91, v0
	v_mov_b32_e32 v96, v0
	v_mov_b32_e32 v97, v0
	v_mov_b32_e32 v98, v0
	v_mov_b32_e32 v99, v0
	v_mov_b32_e32 v104, v0
	v_mov_b32_e32 v105, v0
	v_mov_b32_e32 v106, v0
	v_mov_b32_e32 v107, v0
	v_mov_b32_e32 v112, v0
	v_mov_b32_e32 v113, v0
	v_mov_b32_e32 v114, v0
	v_mov_b32_e32 v115, v0
	v_mov_b32_e32 v76, v0
	v_mov_b32_e32 v77, v0
	v_mov_b32_e32 v78, v0
	v_mov_b32_e32 v79, v0
	v_mov_b32_e32 v84, v0
	v_mov_b32_e32 v85, v0
	v_mov_b32_e32 v86, v0
	v_mov_b32_e32 v87, v0
	v_mov_b32_e32 v92, v0
	v_mov_b32_e32 v93, v0
	v_mov_b32_e32 v94, v0
	v_mov_b32_e32 v95, v0
	v_mov_b32_e32 v100, v0
	v_mov_b32_e32 v101, v0
	v_mov_b32_e32 v102, v0
	v_mov_b32_e32 v103, v0
	v_mov_b32_e32 v108, v0
	v_mov_b32_e32 v109, v0
	v_mov_b32_e32 v110, v0
	v_mov_b32_e32 v111, v0
	v_mov_b32_e32 v116, v0
	v_mov_b32_e32 v117, v0
	v_mov_b32_e32 v118, v0
	v_mov_b32_e32 v119, v0
	v_mov_b32_e32 v120, v0
	v_mov_b32_e32 v121, v0
	v_mov_b32_e32 v122, v0
	v_mov_b32_e32 v123, v0
	v_mov_b32_e32 v124, v0
	v_mov_b32_e32 v125, v0
	v_mov_b32_e32 v126, v0
	v_mov_b32_e32 v127, v0
	s_cmp_eq_u32 s98, 0
	s_cbranch_scc1 .LBB0_201
	ds_read_b128 v[144:147], v151
	ds_read_b128 v[154:157], v151 offset:1024
	ds_read_b128 v[158:161], v151 offset:2048
	ds_read_b128 v[162:165], v151 offset:3072
	ds_read_b128 v[166:169], v152
	ds_read_b128 v[172:175], v152 offset:1024
	ds_read_b128 v[176:179], v152 offset:2048
	ds_read_b128 v[180:183], v152 offset:3072
	s_add_u32 s24, s22, 0xfff80080
	s_addc_u32 s25, s23, -1
	s_cmp_eq_u32 s44, 28
	s_cselect_b32 s27, s15, s25
	s_cselect_b32 s26, s40, s24
	s_cselect_b32 s25, s13, s43
	s_cselect_b32 s24, s41, s42
	v_lshl_add_u64 v[216:217], s[22:23], 0, v[136:137]
	s_add_i32 m0, s3, 0xc000
	ds_read_b128 v[184:187], v153
	ds_read_b128 v[188:191], v153 offset:1024
	ds_read_b128 v[192:195], v153 offset:2048
	ds_read_b128 v[196:199], v153 offset:3072
	ds_read_b128 v[200:203], v153 offset:4096
	ds_read_b128 v[204:207], v153 offset:5120
	ds_read_b128 v[208:211], v153 offset:6144
	ds_read_b128 v[212:215], v153 offset:7168
	global_load_lds_dwordx4 v[216:217], off
	v_lshl_add_u64 v[216:217], s[22:23], 0, v[138:139]
	s_add_i32 m0, s3, 0xe000
	s_nop 0
	global_load_lds_dwordx4 v[216:217], off
	s_waitcnt vmcnt(24)
	s_waitcnt lgkmcnt(0)
	s_barrier
; #define PG8_STAGE(bufoff, gbase, voff) do { _Pragma("unroll") for (int _i = 0; _i < 2; ++_i) \
;     __builtin_amdgcn_global_load_lds((const unsigned*)((const char*)(gbase) + (voff)[_i]), (LAS unsigned*)(lds + (bufoff) + ldsw + _i * 8192), 16, 0, 0); } while (0)
; #define PG8_LDA(dst, b, h) do { _Pragma("unroll") for (int m = 0; m < 4; ++m) _Pragma("unroll") for (int k = 0; k < 2; ++k) dst[m][k] = *(const LAS bf16x8*)(lds + PG8_SA(b, h) + aoff + m * 2048 + k * 1024); } while (0)
; #define PG8_MMA(ai, bj, At, Bt) do { __builtin_amdgcn_s_setprio(1); _Pragma("unroll") for (int m = 0; m < 4; ++m) _Pragma("unroll") for (int n = 0; n < 2; ++n) _Pragma("unroll") for (int k = 0; k < 2; ++k) \
;     acc[ai][bj][m][n] = __builtin_amdgcn_mfma_f32_16x16x32_bf16(Bt[n][k], At[m][k], acc[ai][bj][m][n], 0, 0, 0); __builtin_amdgcn_s_setprio(0); } while (0)
; #define PG8_WAIT_V(n) asm volatile("s_waitcnt vmcnt(" #n ")" ::: "memory")
; #define PG8_WAIT_L(n) asm volatile("s_waitcnt lgkmcnt(" #n ")" ::: "memory")
; #define PG8_BAR __builtin_amdgcn_s_barrier()
; #define PG8_SCHED __builtin_amdgcn_sched_barrier(0)
; template <class Epi, class Sched, bool ALIGN_EPI = true>
; __device__ __forceinline__ void gemm_phase(LAS unsigned char* lds, const Gemm g, const Sched& S, const Epi& E) {
;     ...
;       PG8_WAIT_V(8); PG8_WAIT_L(0); PG8_BAR; PG8_MMA(0, 0, At, B0); PG8_MMA(0, 1, At, B1); PG8_BAR; PG8_SCHED;
;       PG8_LDA(At, 0, 1); PG8_STAGE(PG8_SB(0, 0), b2, voffB); PG8_STAGE(PG8_SB(0, 1), b2 + hstepB, voffB); PG8_STAGE(PG8_SA(0, 0), a2, voffA);
;       PG8_WAIT_V(8); PG8_WAIT_L(0); PG8_BAR; PG8_MMA(1, 0, At, B0); PG8_MMA(1, 1, At, B1); PG8_BAR; PG8_SCHED;
	s_setprio 1
	s_waitcnt lgkmcnt(0)
	v_mfma_f32_16x16x32_bf16 v[124:127], v[144:147], v[184:187], v[124:127]
	v_mfma_f32_16x16x32_bf16 v[120:123], v[158:161], v[184:187], v[120:123]
	v_mfma_f32_16x16x32_bf16 v[116:119], v[144:147], v[192:195], v[116:119]
	v_mfma_f32_16x16x32_bf16 v[108:111], v[158:161], v[192:195], v[108:111]
	v_mfma_f32_16x16x32_bf16 v[100:103], v[144:147], v[200:203], v[100:103]
	v_mfma_f32_16x16x32_bf16 v[92:95], v[158:161], v[200:203], v[92:95]
	v_mfma_f32_16x16x32_bf16 v[84:87], v[144:147], v[208:211], v[84:87]
	v_mfma_f32_16x16x32_bf16 v[76:79], v[158:161], v[208:211], v[76:79]
	v_mfma_f32_16x16x32_bf16 v[124:127], v[154:157], v[188:191], v[124:127]
	v_mfma_f32_16x16x32_bf16 v[120:123], v[162:165], v[188:191], v[120:123]
	v_mfma_f32_16x16x32_bf16 v[116:119], v[154:157], v[196:199], v[116:119]
	v_mfma_f32_16x16x32_bf16 v[108:111], v[162:165], v[196:199], v[108:111]
	v_mfma_f32_16x16x32_bf16 v[100:103], v[154:157], v[204:207], v[100:103]
	v_mfma_f32_16x16x32_bf16 v[92:95], v[162:165], v[204:207], v[92:95]
	v_mfma_f32_16x16x32_bf16 v[84:87], v[154:157], v[212:215], v[84:87]
	v_mfma_f32_16x16x32_bf16 v[76:79], v[162:165], v[212:215], v[76:79]
	s_setprio 0
	s_setprio 1
	v_mfma_f32_16x16x32_bf16 v[112:115], v[166:169], v[184:187], v[112:115]
	v_mfma_f32_16x16x32_bf16 v[104:107], v[176:179], v[184:187], v[104:107]
	v_mfma_f32_16x16x32_bf16 v[96:99], v[166:169], v[192:195], v[96:99]
	v_mfma_f32_16x16x32_bf16 v[88:91], v[176:179], v[192:195], v[88:91]
	v_mfma_f32_16x16x32_bf16 v[80:83], v[166:169], v[200:203], v[80:83]
	v_mfma_f32_16x16x32_bf16 v[72:75], v[176:179], v[200:203], v[72:75]
	v_mfma_f32_16x16x32_bf16 v[68:71], v[166:169], v[208:211], v[68:71]
	v_mfma_f32_16x16x32_bf16 v[64:67], v[176:179], v[208:211], v[64:67]
	v_mfma_f32_16x16x32_bf16 v[112:115], v[172:175], v[188:191], v[112:115]
	v_mfma_f32_16x16x32_bf16 v[104:107], v[180:183], v[188:191], v[104:107]
	v_mfma_f32_16x16x32_bf16 v[96:99], v[172:175], v[196:199], v[96:99]
	v_mfma_f32_16x16x32_bf16 v[88:91], v[180:183], v[196:199], v[88:91]
	v_mfma_f32_16x16x32_bf16 v[80:83], v[172:175], v[204:207], v[80:83]
	v_mfma_f32_16x16x32_bf16 v[72:75], v[180:183], v[204:207], v[72:75]
	v_mfma_f32_16x16x32_bf16 v[68:71], v[172:175], v[212:215], v[68:71]
	v_mfma_f32_16x16x32_bf16 v[64:67], v[180:183], v[212:215], v[64:67]
	s_setprio 0
	s_barrier
	s_add_i32 s45, s36, s0
	v_lshl_add_u64 v[216:217], s[24:25], 0, v[132:133]
	s_mov_b32 m0, s45
	ds_read_b128 v[184:187], v153 offset:16384
	ds_read_b128 v[188:191], v153 offset:17408
	ds_read_b128 v[192:195], v153 offset:18432
	ds_read_b128 v[196:199], v153 offset:19456
	ds_read_b128 v[200:203], v153 offset:20480
	ds_read_b128 v[204:207], v153 offset:21504
	ds_read_b128 v[208:211], v153 offset:22528
	ds_read_b128 v[212:215], v153 offset:23552
	global_load_lds_dwordx4 v[216:217], off
	s_add_i32 m0, s45, 0x2000
	s_add_u32 s46, s24, 0x80000
	v_lshl_add_u64 v[218:219], s[24:25], 0, v[128:129]
	s_addc_u32 s47, s25, 0
	s_add_i32 s45, s37, s0
	global_load_lds_dwordx4 v[218:219], off
	v_lshl_add_u64 v[220:221], s[46:47], 0, v[132:133]
	s_mov_b32 m0, s45
	v_lshl_add_u64 v[222:223], s[26:27], 0, v[130:131]
	global_load_lds_dwordx4 v[220:221], off
	v_lshl_add_u64 v[220:221], s[46:47], 0, v[128:129]
	s_add_i32 m0, s45, 0x2000
	s_nop 0
	global_load_lds_dwordx4 v[220:221], off
	v_lshl_add_u64 v[220:221], s[26:27], 0, v[134:135]
	s_mov_b32 m0, s3
	s_nop 0
	global_load_lds_dwordx4 v[220:221], off
	s_mov_b32 m0, s21
	s_nop 0
	global_load_lds_dwordx4 v[222:223], off
	s_waitcnt vmcnt(24)
	s_waitcnt lgkmcnt(0)
	s_barrier
	s_setprio 1
	s_waitcnt lgkmcnt(0)
	v_mfma_f32_16x16x32_bf16 v[60:63], v[144:147], v[184:187], v[60:63]
	v_mfma_f32_16x16x32_bf16 v[56:59], v[158:161], v[184:187], v[56:59]
	v_mfma_f32_16x16x32_bf16 v[52:55], v[144:147], v[192:195], v[52:55]
	v_mfma_f32_16x16x32_bf16 v[44:47], v[158:161], v[192:195], v[44:47]
	v_mfma_f32_16x16x32_bf16 v[36:39], v[144:147], v[200:203], v[36:39]
	v_mfma_f32_16x16x32_bf16 v[28:31], v[158:161], v[200:203], v[28:31]
	v_mfma_f32_16x16x32_bf16 v[20:23], v[144:147], v[208:211], v[20:23]
	v_mfma_f32_16x16x32_bf16 v[12:15], v[158:161], v[208:211], v[12:15]
	v_mfma_f32_16x16x32_bf16 v[60:63], v[154:157], v[188:191], v[60:63]
	v_mfma_f32_16x16x32_bf16 v[56:59], v[162:165], v[188:191], v[56:59]
	v_mfma_f32_16x16x32_bf16 v[52:55], v[154:157], v[196:199], v[52:55]
	v_mfma_f32_16x16x32_bf16 v[44:47], v[162:165], v[196:199], v[44:47]
	v_mfma_f32_16x16x32_bf16 v[36:39], v[154:157], v[204:207], v[36:39]
	v_mfma_f32_16x16x32_bf16 v[28:31], v[162:165], v[204:207], v[28:31]
	v_mfma_f32_16x16x32_bf16 v[20:23], v[154:157], v[212:215], v[20:23]
	v_mfma_f32_16x16x32_bf16 v[12:15], v[162:165], v[212:215], v[12:15]
	s_setprio 0
	s_setprio 1
	v_mfma_f32_16x16x32_bf16 v[48:51], v[166:169], v[184:187], v[48:51]
	v_mfma_f32_16x16x32_bf16 v[40:43], v[176:179], v[184:187], v[40:43]
	v_mfma_f32_16x16x32_bf16 v[32:35], v[166:169], v[192:195], v[32:35]
	v_mfma_f32_16x16x32_bf16 v[24:27], v[176:179], v[192:195], v[24:27]
	v_mfma_f32_16x16x32_bf16 v[16:19], v[166:169], v[200:203], v[16:19]
	v_mfma_f32_16x16x32_bf16 v[8:11], v[176:179], v[200:203], v[8:11]
	v_mfma_f32_16x16x32_bf16 v[4:7], v[166:169], v[208:211], v[4:7]
	v_mfma_f32_16x16x32_bf16 v[0:3], v[176:179], v[208:211], v[0:3]
	v_mfma_f32_16x16x32_bf16 v[48:51], v[172:175], v[188:191], v[48:51]
	v_mfma_f32_16x16x32_bf16 v[40:43], v[180:183], v[188:191], v[40:43]
	v_mfma_f32_16x16x32_bf16 v[32:35], v[172:175], v[196:199], v[32:35]
	v_mfma_f32_16x16x32_bf16 v[24:27], v[180:183], v[196:199], v[24:27]
	v_mfma_f32_16x16x32_bf16 v[16:19], v[172:175], v[204:207], v[16:19]
	v_mfma_f32_16x16x32_bf16 v[8:11], v[180:183], v[204:207], v[8:11]
	v_mfma_f32_16x16x32_bf16 v[4:7], v[172:175], v[212:215], v[4:7]
	v_mfma_f32_16x16x32_bf16 v[0:3], v[180:183], v[212:215], v[0:3]
	s_setprio 0
	s_barrier
	s_branch .Lpeel_mid_201

; #define PG8_STAGE(bufoff, gbase, voff) do { _Pragma("unroll") for (int _i = 0; _i < 2; ++_i) \
;     __builtin_amdgcn_global_load_lds((const unsigned*)((const char*)(gbase) + (voff)[_i]), (LAS unsigned*)(lds + (bufoff) + ldsw + _i * 8192), 16, 0, 0); } while (0)
; #define PG8_LDA(dst, b, h) do { _Pragma("unroll") for (int m = 0; m < 4; ++m) _Pragma("unroll") for (int k = 0; k < 2; ++k) dst[m][k] = *(const LAS bf16x8*)(lds + PG8_SA(b, h) + aoff + m * 2048 + k * 1024); } while (0)
; #define PG8_LDB(dst, b, h) do { _Pragma("unroll") for (int n = 0; n < 2; ++n) _Pragma("unroll") for (int k = 0; k < 2; ++k) dst[n][k] = *(const LAS bf16x8*)(lds + PG8_SB(b, h) + boff + n * 2048 + k * 1024); } while (0)
; #define PG8_MMA(ai, bj, At, Bt) do { __builtin_amdgcn_s_setprio(1); _Pragma("unroll") for (int m = 0; m < 4; ++m) _Pragma("unroll") for (int n = 0; n < 2; ++n) _Pragma("unroll") for (int k = 0; k < 2; ++k) \
;     acc[ai][bj][m][n] = __builtin_amdgcn_mfma_f32_16x16x32_bf16(Bt[n][k], At[m][k], acc[ai][bj][m][n], 0, 0, 0); __builtin_amdgcn_s_setprio(0); } while (0)
; #define PG8_WAIT_V(n) asm volatile("s_waitcnt vmcnt(" #n ")" ::: "memory")
; #define PG8_WAIT_L(n) asm volatile("s_waitcnt lgkmcnt(" #n ")" ::: "memory")
; #define PG8_BAR __builtin_amdgcn_s_barrier()
; #define PG8_SCHED __builtin_amdgcn_sched_barrier(0)
; template <class Epi, class Sched, bool ALIGN_EPI = true>
; __device__ __forceinline__ void gemm_phase(LAS unsigned char* lds, const Gemm g, const Sched& S, const Epi& E) {
;     ...
;       PG8_LDB(B0, 1, 0); PG8_LDB(B1, 1, 1); PG8_SCHED; PG8_LDA(At, 1, 0); PG8_STAGE(PG8_SA(0, 1), a2 + hstepA, voffA);
;       PG8_WAIT_V(8); PG8_WAIT_L(0); PG8_BAR; PG8_MMA(0, 0, At, B0); PG8_MMA(0, 1, At, B1); PG8_BAR; PG8_SCHED;
.Lpeel_mid_201:
	s_add_i32 s45, 0, 0x18000
	s_add_i32 s46, 0, 0x1c000
	v_add_u32_e32 v162, s45, v149
	v_add_u32_e32 v180, s46, v149
	ds_read_b128 v[144:147], v162
	ds_read_b128 v[154:157], v162 offset:1024
	ds_read_b128 v[158:161], v162 offset:2048
	ds_read_b128 v[162:165], v162 offset:3072
	ds_read_b128 v[166:169], v180
	ds_read_b128 v[172:175], v180 offset:1024
	ds_read_b128 v[176:179], v180 offset:2048
	ds_read_b128 v[180:183], v180 offset:3072
	s_add_u32 s26, s26, 0x80000
	s_addc_u32 s27, s27, 0
	s_mov_b32 m0, s28
	v_lshl_add_u64 v[224:225], s[26:27], 0, v[134:135]
	ds_read_b128 v[184:187], v153 offset:32768
	ds_read_b128 v[188:191], v153 offset:33792
	ds_read_b128 v[192:195], v153 offset:34816
	ds_read_b128 v[196:199], v153 offset:35840
	ds_read_b128 v[200:203], v153 offset:36864
	ds_read_b128 v[204:207], v153 offset:37888
	ds_read_b128 v[208:211], v153 offset:38912
	ds_read_b128 v[212:215], v153 offset:39936
	global_load_lds_dwordx4 v[224:225], off
	v_lshl_add_u64 v[224:225], s[26:27], 0, v[130:131]
	s_mov_b32 m0, s29
	s_nop 0
	global_load_lds_dwordx4 v[224:225], off
	s_waitcnt vmcnt(8)
	s_waitcnt lgkmcnt(0)
	s_barrier
	s_setprio 1
	s_waitcnt lgkmcnt(0)
	v_mfma_f32_16x16x32_bf16 v[124:127], v[144:147], v[184:187], v[124:127]
	v_mfma_f32_16x16x32_bf16 v[120:123], v[158:161], v[184:187], v[120:123]
	v_mfma_f32_16x16x32_bf16 v[116:119], v[144:147], v[192:195], v[116:119]
	v_mfma_f32_16x16x32_bf16 v[108:111], v[158:161], v[192:195], v[108:111]
	v_mfma_f32_16x16x32_bf16 v[100:103], v[144:147], v[200:203], v[100:103]
	v_mfma_f32_16x16x32_bf16 v[92:95], v[158:161], v[200:203], v[92:95]
	v_mfma_f32_16x16x32_bf16 v[84:87], v[144:147], v[208:211], v[84:87]
	v_mfma_f32_16x16x32_bf16 v[76:79], v[158:161], v[208:211], v[76:79]
	v_mfma_f32_16x16x32_bf16 v[124:127], v[154:157], v[188:191], v[124:127]
	v_mfma_f32_16x16x32_bf16 v[120:123], v[162:165], v[188:191], v[120:123]
	v_mfma_f32_16x16x32_bf16 v[116:119], v[154:157], v[196:199], v[116:119]
	v_mfma_f32_16x16x32_bf16 v[108:111], v[162:165], v[196:199], v[108:111]
	v_mfma_f32_16x16x32_bf16 v[100:103], v[154:157], v[204:207], v[100:103]
	v_mfma_f32_16x16x32_bf16 v[92:95], v[162:165], v[204:207], v[92:95]
	v_mfma_f32_16x16x32_bf16 v[84:87], v[154:157], v[212:215], v[84:87]
	v_mfma_f32_16x16x32_bf16 v[76:79], v[162:165], v[212:215], v[76:79]
	s_setprio 0
	s_setprio 1
	v_mfma_f32_16x16x32_bf16 v[112:115], v[166:169], v[184:187], v[112:115]
	v_mfma_f32_16x16x32_bf16 v[104:107], v[176:179], v[184:187], v[104:107]
	v_mfma_f32_16x16x32_bf16 v[96:99], v[166:169], v[192:195], v[96:99]
	v_mfma_f32_16x16x32_bf16 v[88:91], v[176:179], v[192:195], v[88:91]
	v_mfma_f32_16x16x32_bf16 v[80:83], v[166:169], v[200:203], v[80:83]
	v_mfma_f32_16x16x32_bf16 v[72:75], v[176:179], v[200:203], v[72:75]
	v_mfma_f32_16x16x32_bf16 v[68:71], v[166:169], v[208:211], v[68:71]
	v_mfma_f32_16x16x32_bf16 v[64:67], v[176:179], v[208:211], v[64:67]
	v_mfma_f32_16x16x32_bf16 v[112:115], v[172:175], v[188:191], v[112:115]
	v_mfma_f32_16x16x32_bf16 v[104:107], v[180:183], v[188:191], v[104:107]
	v_mfma_f32_16x16x32_bf16 v[96:99], v[172:175], v[196:199], v[96:99]
	v_mfma_f32_16x16x32_bf16 v[88:91], v[180:183], v[196:199], v[88:91]
	v_mfma_f32_16x16x32_bf16 v[80:83], v[172:175], v[204:207], v[80:83]
	v_mfma_f32_16x16x32_bf16 v[72:75], v[180:183], v[204:207], v[72:75]
	v_mfma_f32_16x16x32_bf16 v[68:71], v[172:175], v[212:215], v[68:71]
	v_mfma_f32_16x16x32_bf16 v[64:67], v[180:183], v[212:215], v[64:67]
	s_setprio 0
	s_barrier
; #define PG8_STAGE(bufoff, gbase, voff) do { _Pragma("unroll") for (int _i = 0; _i < 2; ++_i) \
;     __builtin_amdgcn_global_load_lds((const unsigned*)((const char*)(gbase) + (voff)[_i]), (LAS unsigned*)(lds + (bufoff) + ldsw + _i * 8192), 16, 0, 0); } while (0)
; #define PG8_LDA(dst, b, h) do { _Pragma("unroll") for (int m = 0; m < 4; ++m) _Pragma("unroll") for (int k = 0; k < 2; ++k) dst[m][k] = *(const LAS bf16x8*)(lds + PG8_SA(b, h) + aoff + m * 2048 + k * 1024); } while (0)
; #define PG8_MMA(ai, bj, At, Bt) do { __builtin_amdgcn_s_setprio(1); _Pragma("unroll") for (int m = 0; m < 4; ++m) _Pragma("unroll") for (int n = 0; n < 2; ++n) _Pragma("unroll") for (int k = 0; k < 2; ++k) \
;     acc[ai][bj][m][n] = __builtin_amdgcn_mfma_f32_16x16x32_bf16(Bt[n][k], At[m][k], acc[ai][bj][m][n], 0, 0, 0); __builtin_amdgcn_s_setprio(0); } while (0)
; #define PG8_WAIT_V(n) asm volatile("s_waitcnt vmcnt(" #n ")" ::: "memory")
; #define PG8_WAIT_L(n) asm volatile("s_waitcnt lgkmcnt(" #n ")" ::: "memory")
; #define PG8_BAR __builtin_amdgcn_s_barrier()
; #define PG8_SCHED __builtin_amdgcn_sched_barrier(0)
; template <class Epi, class Sched, bool ALIGN_EPI = true>
; __device__ __forceinline__ void gemm_phase(LAS unsigned char* lds, const Gemm g, const Sched& S, const Epi& E) {
;     ...
;       PG8_LDA(At, 1, 1); PG8_STAGE(PG8_SB(1, 0), b3, voffB); PG8_STAGE(PG8_SB(1, 1), b3 + hstepB, voffB); PG8_STAGE(PG8_SA(1, 0), a3, voffA);
;       PG8_WAIT_V(8); PG8_WAIT_L(0); PG8_BAR; PG8_MMA(1, 0, At, B0); PG8_MMA(1, 1, At, B1); PG8_BAR; PG8_SCHED;
;     }
;     if constexpr (ALIGN_EPI) { if (wr == 0) PG8_BAR; }
	s_add_i32 s26, s45, s0
	v_lshl_add_u64 v[216:217], v[216:217], 0, s[8:9]
	s_mov_b32 m0, s26
	ds_read_b128 v[184:187], v153 offset:49152
	ds_read_b128 v[188:191], v153 offset:50176
	ds_read_b128 v[192:195], v153 offset:51200
	ds_read_b128 v[196:199], v153 offset:52224
	ds_read_b128 v[200:203], v153 offset:53248
	ds_read_b128 v[204:207], v153 offset:54272
	ds_read_b128 v[208:211], v153 offset:55296
	ds_read_b128 v[212:215], v153 offset:56320
	global_load_lds_dwordx4 v[216:217], off
	s_add_i32 m0, s26, 0x2000
	s_add_u32 s24, s24, 0x80080
	v_lshl_add_u64 v[216:217], v[218:219], 0, s[8:9]
	s_addc_u32 s25, s25, 0
	s_add_i32 s26, s46, s0
	global_load_lds_dwordx4 v[216:217], off
	v_lshl_add_u64 v[216:217], s[24:25], 0, v[132:133]
	s_mov_b32 m0, s26
	s_nop 0
	global_load_lds_dwordx4 v[216:217], off
	v_lshl_add_u64 v[216:217], s[24:25], 0, v[128:129]
	s_add_i32 m0, s26, 0x2000
	s_nop 0
	global_load_lds_dwordx4 v[216:217], off
	v_lshl_add_u64 v[216:217], v[220:221], 0, s[8:9]
	s_mov_b32 m0, s31
	s_nop 0
	global_load_lds_dwordx4 v[216:217], off
	v_lshl_add_u64 v[216:217], v[222:223], 0, s[8:9]
	s_mov_b32 m0, s33
	s_nop 0
	global_load_lds_dwordx4 v[216:217], off
	s_waitcnt vmcnt(8)
	s_waitcnt lgkmcnt(0)
	s_barrier
	s_setprio 1
	s_waitcnt lgkmcnt(0)
	v_mfma_f32_16x16x32_bf16 v[60:63], v[144:147], v[184:187], v[60:63]
	v_mfma_f32_16x16x32_bf16 v[56:59], v[158:161], v[184:187], v[56:59]
	v_mfma_f32_16x16x32_bf16 v[52:55], v[144:147], v[192:195], v[52:55]
	v_mfma_f32_16x16x32_bf16 v[44:47], v[158:161], v[192:195], v[44:47]
	v_mfma_f32_16x16x32_bf16 v[36:39], v[144:147], v[200:203], v[36:39]
	v_mfma_f32_16x16x32_bf16 v[28:31], v[158:161], v[200:203], v[28:31]
	v_mfma_f32_16x16x32_bf16 v[20:23], v[144:147], v[208:211], v[20:23]
	v_mfma_f32_16x16x32_bf16 v[12:15], v[158:161], v[208:211], v[12:15]
	v_mfma_f32_16x16x32_bf16 v[60:63], v[154:157], v[188:191], v[60:63]
	v_mfma_f32_16x16x32_bf16 v[56:59], v[162:165], v[188:191], v[56:59]
	v_mfma_f32_16x16x32_bf16 v[52:55], v[154:157], v[196:199], v[52:55]
	v_mfma_f32_16x16x32_bf16 v[44:47], v[162:165], v[196:199], v[44:47]
	v_mfma_f32_16x16x32_bf16 v[36:39], v[154:157], v[204:207], v[36:39]
	v_mfma_f32_16x16x32_bf16 v[28:31], v[162:165], v[204:207], v[28:31]
	v_mfma_f32_16x16x32_bf16 v[20:23], v[154:157], v[212:215], v[20:23]
	v_mfma_f32_16x16x32_bf16 v[12:15], v[162:165], v[212:215], v[12:15]
	s_setprio 0
	s_setprio 1
	v_mfma_f32_16x16x32_bf16 v[48:51], v[166:169], v[184:187], v[48:51]
	v_mfma_f32_16x16x32_bf16 v[40:43], v[176:179], v[184:187], v[40:43]
	v_mfma_f32_16x16x32_bf16 v[32:35], v[166:169], v[192:195], v[32:35]
	v_mfma_f32_16x16x32_bf16 v[24:27], v[176:179], v[192:195], v[24:27]
	v_mfma_f32_16x16x32_bf16 v[16:19], v[166:169], v[200:203], v[16:19]
	v_mfma_f32_16x16x32_bf16 v[8:11], v[176:179], v[200:203], v[8:11]
	v_mfma_f32_16x16x32_bf16 v[4:7], v[166:169], v[208:211], v[4:7]
	v_mfma_f32_16x16x32_bf16 v[0:3], v[176:179], v[208:211], v[0:3]
	v_mfma_f32_16x16x32_bf16 v[48:51], v[172:175], v[188:191], v[48:51]
	v_mfma_f32_16x16x32_bf16 v[40:43], v[180:183], v[188:191], v[40:43]
	v_mfma_f32_16x16x32_bf16 v[32:35], v[172:175], v[196:199], v[32:35]
	v_mfma_f32_16x16x32_bf16 v[24:27], v[180:183], v[196:199], v[24:27]
	v_mfma_f32_16x16x32_bf16 v[16:19], v[172:175], v[204:207], v[16:19]
	v_mfma_f32_16x16x32_bf16 v[8:11], v[180:183], v[204:207], v[8:11]
	v_mfma_f32_16x16x32_bf16 v[4:7], v[172:175], v[212:215], v[4:7]
	v_mfma_f32_16x16x32_bf16 v[0:3], v[180:183], v[212:215], v[0:3]
	s_setprio 0
	s_barrier
	s_add_i32 s44, s44, 2
	s_add_u32 s22, s22, 0x100
	s_addc_u32 s23, s23, 0
	s_add_u32 s42, s42, 0x100
	s_addc_u32 s43, s43, 0
	s_cmp_gt_u32 s44, 29
	s_cbranch_scc0 .LBB0_201
	s_mov_b32 s98, 1
	s_and_b64 vcc, exec, s[10:11]
	s_cbranch_vccz .LBB0_204
	s_barrier

; __device__ __forceinline__ int v_st(int k, int c) { const int kk = (k & ~0xC) | ((k & 4) << 1) | ((k & 8) >> 1); return ((kk >> 3) * 4 + (c >> 5)) * 512 + ((kk & 7) * 32 + (c & 31)) * 2; }
; __device__ __forceinline__ int v_rd_base(int lane) { return ((lane & 3) << 3) | (((lane >> 2) & 3) << 6) | (((lane >> 4) & 1) << 5) | (((lane >> 5) & 1) << 8); }
; #define SWAIT() asm volatile("s_waitcnt vmcnt(0)" ::: "memory")
; template <int MODE>
; __device__ __forceinline__ void attn_body(const Job J, char* lds) {
;     ...
;   const bf16_t* Qw = J.Qb + (size_t)(wid * QBLK + r32) * J.ldq + hi * 8;
;   char* ql = lds + 2 * SHM_V + 2 * SHM_K + NW * 256 + (wid * 8 * 64 + lane) * 16;
; #pragma unroll
;   for (int d0 = 0; d0 < NQR; ++d0) qr[d0] = *reinterpret_cast<const bf16x8*>(Qw + d0 * 16);
;     ...
;   const int sr = tid >> 4, sc = (tid & 15) * 8, vst0 = v_st(sr, sc), vst1 = v_st(32 + sr, sc);
;   const int pr = tid >> 3, pc = (tid & 7) * 8;
;   const int vb0 = (int)(uintptr_t)V_lds + v_rd_base(lane);
;   bf16x8 vs0, vs1, ks0, ks1, kp;
;   const int rq = J.qb4 + (wid >> 1), qc = (wid & 1) * 32 + r32;
;   const int rs = min(max(rq - 4, 0), 24), cs_ = min(max(qc - 8, 0), 48);
;     ...
;   f32x16 pA0, pA1, pB0, pB1; float mnA, mnB, alA, alB; bf16x8 pa0, pa1, pa2, pa3; const int NT = J.NT;
;   SLOAD(0); SWAIT(); SWRITE(0); __syncthreads();
;   qkt<DQK>(pA0, pA1, K_lds, qr, ql, r32, hi); MASK(pA0, pA1, 0); partialSM(pA0, pA1, m_reg, mnA, alA, C, THRS);
.LBB0_389:
	s_add_i32 s0, s89, 0xfffffe00
	s_lshl_b32 s1, s0, 5
	s_and_b32 s1, s1, 0x700
	s_or_b32 s3, s1, 0x4000
	s_mul_i32 s4, s3, 0x2800
	s_add_u32 s4, s19, s4
	v_readlane_b32 s5, v248, 35
	s_addc_u32 s5, s5, 0
	s_lshl_b32 s0, s0, 7
	s_and_b32 s0, s0, 0x380
	s_lshl_b32 s0, s0, 1
	s_add_u32 s4, s4, s0
	s_addc_u32 s5, s5, 0
	v_readlane_b32 s6, v248, 36
	s_add_u32 s6, s6, s0
	v_readlane_b32 s7, v248, 37
	s_addc_u32 s7, s7, 0
	v_readlane_b32 s8, v248, 38
	s_add_u32 s8, s8, s0
	v_readlane_b32 s9, v248, 39
	v_mov_b32_e32 v16, v170
	s_waitcnt lgkmcnt(0)
	s_barrier
	s_addc_u32 s9, s9, 0
	s_add_i32 s10, 0, 0x10000
	v_and_b32_e32 v0, 0x3fffffc0, v16
	v_lshl_add_u32 v149, v0, 2, s10
	v_ashrrev_i32_e32 v144, 1, v16
	s_movk_i32 s10, 0xffe0
	v_bfe_u32 v154, v16, 5, 1
	v_bfi_b32 v2, s10, v144, v16
	v_mov_b64_e32 v[0:1], s[4:5]
	v_mad_i64_i32 v[0:1], s[4:5], v2, s81, v[0:1]
	v_lshlrev_b32_e32 v158, 4, v154
	v_ashrrev_i32_e32 v195, 4, v16
	v_lshl_add_u64 v[0:1], v[0:1], 0, v[158:159]
	v_and_b32_e32 v2, 0xfffff0, v195
	v_lshlrev_b32_e32 v3, 1, v195
	global_load_dwordx4 v[124:127], v[0:1], off
	global_load_dwordx4 v[120:123], v[0:1], off offset:32
	global_load_dwordx4 v[116:119], v[0:1], off offset:64
	global_load_dwordx4 v[112:115], v[0:1], off offset:96
	global_load_dwordx4 v[108:111], v[0:1], off offset:128
	global_load_dwordx4 v[104:107], v[0:1], off offset:160
	global_load_dwordx4 v[100:103], v[0:1], off offset:192
	global_load_dwordx4 v[96:99], v[0:1], off offset:224
	v_lshlrev_b32_e32 v0, 3, v16
	v_and_or_b32 v2, v3, 8, v2
	v_and_b32_e32 v1, 0x78, v0
	v_lshrrev_b32_e32 v3, 1, v195
	v_lshrrev_b32_e32 v2, 1, v2
	v_bfe_u32 v0, v0, 5, 2
	v_and_b32_e32 v4, 3, v195
	v_or_b32_e32 v2, v2, v0
	v_and_or_b32 v3, v3, 4, v4
	v_lshlrev_b32_e32 v32, 1, v1
	v_lshlrev_b32_e32 v2, 9, v2
	v_lshlrev_b32_e32 v3, 6, v3
	v_and_b32_e32 v1, 48, v32
	v_add_u32_e32 v197, 32, v195
	v_or3_b32 v17, v2, v3, v1
	v_and_b32_e32 v2, 0xfffff0, v197
	v_lshlrev_b32_e32 v4, 1, v197
	v_and_or_b32 v2, v4, 8, v2
	v_lshrrev_b32_e32 v2, 1, v2
	v_or_b32_e32 v0, v2, v0
	v_and_b32_e32 v38, 63, v16
	v_lshlrev_b32_e32 v0, 9, v0
	v_lshlrev_b32_e32 v19, 4, v16
	v_or3_b32 v18, v0, v3, v1
	v_lshlrev_b32_e32 v0, 3, v38
	v_and_b32_e32 v1, 0xc0, v19
	v_lshlrev_b32_e32 v2, 1, v16
	v_and_or_b32 v1, v0, 24, v1
	v_and_b32_e32 v2, 32, v2
	v_and_b32_e32 v0, 0x100, v0
	s_cmp_lg_u32 0, -1
	v_or3_b32 v145, v1, v2, v0
	s_cselect_b32 s4, 0, 0
	v_add_u32_e32 v55, s3, v195
	v_mov_b64_e32 v[34:35], s[8:9]
	v_add_u32_e32 v161, s4, v145
	v_mad_i64_i32 v[0:1], s[4:5], v55, s81, v[34:35]
	v_mov_b32_e32 v33, v159
	v_lshl_add_u64 v[0:1], v[0:1], 0, v[32:33]
	global_load_dwordx4 v[0:3], v[0:1], off
	v_add_u32_e32 v12, s3, v197
	v_mov_b64_e32 v[36:37], s[6:7]
	v_mad_i64_i32 v[4:5], s[4:5], v12, s81, v[34:35]
	v_mad_i64_i32 v[8:9], s[4:5], v55, s81, v[36:37]
	v_mad_i64_i32 v[12:13], s[4:5], v12, s81, v[36:37]
	v_lshl_add_u64 v[4:5], v[4:5], 0, v[32:33]
	v_lshl_add_u64 v[8:9], v[8:9], 0, v[32:33]
	v_lshl_add_u64 v[12:13], v[12:13], 0, v[32:33]
	global_load_dwordx4 v[4:7], v[4:5], off
	v_add_u32_e32 v191, 0, v17
	global_load_dwordx4 v[8:11], v[8:9], off
	s_movk_i32 s4, 0x70
	global_load_dwordx4 v[12:15], v[12:13], off
	s_waitcnt vmcnt(0)
	v_and_b32_e32 v155, 31, v16
	v_lshl_add_u32 v39, v155, 8, 0
	v_add_u32_e32 v192, 0, v18
	v_and_b32_e32 v48, 0xf0, v19
	v_bitop3_b32 v40, v158, v48, 32 bitop3:0x36
	v_add_u32_e32 v167, v39, v40
	v_lshl_add_u64 v[152:153], s[8:9], 0, v[32:33]
	v_lshl_add_u64 v[150:151], s[6:7], 0, v[32:33]
	v_cmp_gt_u32_e64 s[6:7], 32, v38
	v_lshl_add_u32 v163, v155, 2, v149
	s_waitcnt vmcnt(3)
	ds_write_b128 v191, v[0:3]
	v_lshl_add_u32 v0, v195, 8, 0
	v_and_b32_e32 v1, 0xf0, v16
	v_xor_b32_e32 v1, v32, v1
	v_add_u32_e32 v194, v0, v1
	v_lshl_add_u32 v0, v197, 8, 0
	v_add_u32_e32 v196, v0, v1
	v_xor_b32_e32 v0, v158, v48
	v_add_u32_e32 v166, v39, v0
	s_movk_i32 s4, 0x60
	s_waitcnt vmcnt(2)
	ds_write_b128 v192, v[4:7]
	s_waitcnt vmcnt(1)
	ds_write_b128 v194, v[8:11] offset:32768
	s_waitcnt vmcnt(0)
	ds_write_b128 v196, v[12:15] offset:32768
	s_waitcnt lgkmcnt(0)
	s_barrier
	ds_read_b128 v[0:3], v166 offset:32768
	ds_read_b128 v[4:7], v166 offset:40960
	s_waitcnt lgkmcnt(1)
	v_mfma_f32_32x32x16_bf16 v[16:31], v[0:3], v[124:127], 0
	ds_read_b128 v[40:43], v167 offset:32768
	ds_read_b128 v[44:47], v167 offset:40960
	s_waitcnt lgkmcnt(2)
	v_mfma_f32_32x32x16_bf16 v[0:15], v[4:7], v[124:127], 0
	s_waitcnt lgkmcnt(1)
	v_mfma_f32_32x32x16_bf16 v[16:31], v[40:43], v[120:123], v[16:31]
	v_bitop3_b32 v40, v158, v48, 64 bitop3:0x36
	v_add_u32_e32 v168, v39, v40
	s_waitcnt lgkmcnt(0)
	v_mfma_f32_32x32x16_bf16 v[0:15], v[44:47], v[120:123], v[0:15]
	ds_read_b128 v[40:43], v168 offset:32768
	ds_read_b128 v[44:47], v168 offset:40960
	s_waitcnt lgkmcnt(1)
	v_mfma_f32_32x32x16_bf16 v[16:31], v[40:43], v[116:119], v[16:31]
	v_bitop3_b32 v40, v158, v48, s4 bitop3:0x36
	v_add_u32_e32 v169, v39, v40
	s_movk_i32 s4, 0x80
	s_waitcnt lgkmcnt(0)
	v_mfma_f32_32x32x16_bf16 v[0:15], v[44:47], v[116:119], v[0:15]
	ds_read_b128 v[40:43], v169 offset:32768
	ds_read_b128 v[44:47], v169 offset:40960
	s_waitcnt lgkmcnt(1)
	v_mfma_f32_32x32x16_bf16 v[16:31], v[40:43], v[112:115], v[16:31]
	v_bitop3_b32 v40, v158, v48, s4 bitop3:0x36
	v_add_u32_e32 v188, v39, v40
	s_movk_i32 s4, 0xa0
	s_waitcnt lgkmcnt(0)
	v_mfma_f32_32x32x16_bf16 v[0:15], v[44:47], v[112:115], v[0:15]
	ds_read_b128 v[40:43], v188 offset:32768
	ds_read_b128 v[44:47], v188 offset:40960
	s_waitcnt lgkmcnt(1)
	v_mfma_f32_32x32x16_bf16 v[16:31], v[40:43], v[108:111], v[16:31]
	v_bitop3_b32 v40, v158, v48, s4 bitop3:0x36
	v_add_u32_e32 v189, v39, v40
	s_movk_i32 s4, 0xc0
	s_waitcnt lgkmcnt(0)
; #define SWAIT() asm volatile("s_waitcnt vmcnt(0)" ::: "memory")
; __device__ __forceinline__ void partialSM(f32x16& p0, f32x16& p1, float& m_reg, float& mn, float& alpha, const float C, const float THRS) {
;   float pmax = p0[0];
; #pragma unroll
;   for (int r = 1; r < 16; ++r) pmax = fmaxf(pmax, p0[r]);
; #pragma unroll
;   for (int r = 0; r < 16; ++r) pmax = fmaxf(pmax, p1[r]);
;   { auto rr = __builtin_amdgcn_permlane32_swap(__float_as_uint(pmax), __float_as_uint(pmax), false, false);
;     pmax = fmaxf(__uint_as_float(rr[0]), __uint_as_float(rr[1])); }
;   if (__builtin_expect(__all(pmax - m_reg <= THRS), 1)) { mn = m_reg; alpha = 1.f; }
;   else { mn = fmaxf(m_reg, pmax); alpha = __builtin_amdgcn_exp2f((m_reg - mn) * C); m_reg = mn; }
;   float mnC = -mn * C;
; #pragma unroll
;   for (int r = 0; r < 16; ++r) p0[r] = fmaf(p0[r], C, mnC);
; #pragma unroll
;   for (int r = 0; r < 16; ++r) p1[r] = fmaf(p1[r], C, mnC);
; #pragma unroll
;   for (int r = 0; r < 16; ++r) p0[r] = __builtin_amdgcn_exp2f(p0[r]);
; }
; template <int MODE>
; __device__ __forceinline__ void attn_body(const Job J, char* lds) {
;     ...
;   qkt<DQK>(pA0, pA1, K_lds, qr, ql, r32, hi); MASK(pA0, pA1, 0); partialSM(pA0, pA1, m_reg, mnA, alA, C, THRS);
;   SLOAD(1);
;   SWAIT(); SWRITE(1); __syncthreads();
	v_mfma_f32_32x32x16_bf16 v[0:15], v[44:47], v[108:111], v[0:15]
	ds_read_b128 v[40:43], v189 offset:32768
	ds_read_b128 v[44:47], v189 offset:40960
	s_waitcnt lgkmcnt(1)
	v_mfma_f32_32x32x16_bf16 v[16:31], v[40:43], v[104:107], v[16:31]
	v_bitop3_b32 v40, v158, v48, s4 bitop3:0x36
	v_add_u32_e32 v190, v39, v40
	s_movk_i32 s4, 0xe0
	s_waitcnt lgkmcnt(0)
	v_mfma_f32_32x32x16_bf16 v[0:15], v[44:47], v[104:107], v[0:15]
	ds_read_b128 v[40:43], v190 offset:32768
	ds_read_b128 v[44:47], v190 offset:40960
	s_waitcnt lgkmcnt(1)
	v_mfma_f32_32x32x16_bf16 v[16:31], v[40:43], v[100:103], v[16:31]
	v_bitop3_b32 v40, v158, v48, s4 bitop3:0x36
	v_add_u32_e32 v193, v39, v40
	s_waitcnt lgkmcnt(0)
	v_mfma_f32_32x32x16_bf16 v[0:15], v[44:47], v[100:103], v[0:15]
	ds_read_b128 v[40:43], v193 offset:32768
	ds_read_b128 v[44:47], v193 offset:40960
	s_waitcnt lgkmcnt(1)
	v_mfma_f32_32x32x16_bf16 v[16:31], v[40:43], v[96:99], v[16:31]
	s_waitcnt lgkmcnt(0)
	v_mfma_f32_32x32x16_bf16 v[0:15], v[44:47], v[96:99], v[0:15]
	s_nop 9
	v_max_f32_e32 v39, v17, v17
	v_max_f32_e32 v40, v16, v16
	v_max_f32_e32 v39, v40, v39
	v_max3_f32 v39, v39, v18, v19
	v_max3_f32 v39, v39, v20, v21
	v_max3_f32 v39, v39, v22, v23
	v_max3_f32 v39, v39, v24, v25
	v_max3_f32 v39, v39, v26, v27
	v_max3_f32 v39, v39, v28, v29
	v_max3_f32 v39, v39, v30, v31
	v_max3_f32 v39, v39, v0, v1
	v_max3_f32 v39, v39, v2, v3
	v_max3_f32 v39, v39, v4, v5
	v_max3_f32 v39, v39, v6, v7
	v_max3_f32 v39, v39, v8, v9
	v_max3_f32 v39, v39, v10, v11
	v_max3_f32 v39, v39, v12, v13
	v_max3_f32 v39, v39, v14, v15
	v_mov_b32_e32 v40, v39
	s_nop 1
	v_permlane32_swap_b32_e32 v39, v40
	v_max_f32_e32 v40, v40, v40
	v_max_f32_e32 v39, v39, v39
	v_max_f32_e32 v39, v39, v40
	v_add_f32_e32 v40, 0x7149f2ca, v39
	v_cmp_ge_f32_e32 vcc, s88, v40
	s_cmp_eq_u64 vcc, exec
	s_cselect_b64 s[4:5], -1, 0
	v_max_f32_e32 v147, 0xf149f2ca, v39
	v_cndmask_b32_e64 v146, v147, v187, s[4:5]
	v_mul_f32_e32 v39, 0xbe0293ee, v146
	v_fmamk_f32 v46, v8, 0x3e0293ee, v39
	v_fmamk_f32 v40, v12, 0x3e0293ee, v39
	v_add_u32_e32 v8, 64, v55
	v_add_u32_e32 v12, 0x60, v55
	v_fmamk_f32 v50, v0, 0x3e0293ee, v39
	v_fmamk_f32 v51, v1, 0x3e0293ee, v39
	v_fmamk_f32 v54, v4, 0x3e0293ee, v39
	v_fmamk_f32 v43, v5, 0x3e0293ee, v39
	v_fmamk_f32 v47, v9, 0x3e0293ee, v39
	v_fmamk_f32 v41, v13, 0x3e0293ee, v39
	v_mad_i64_i32 v[0:1], s[10:11], v8, s81, v[34:35]
	v_mad_i64_i32 v[4:5], s[10:11], v12, s81, v[34:35]
	v_mad_i64_i32 v[8:9], s[10:11], v8, s81, v[36:37]
	v_mad_i64_i32 v[12:13], s[10:11], v12, s81, v[36:37]
	v_lshl_add_u64 v[0:1], v[0:1], 0, v[32:33]
	v_lshl_add_u64 v[4:5], v[4:5], 0, v[32:33]
	v_lshl_add_u64 v[8:9], v[8:9], 0, v[32:33]
	v_lshl_add_u64 v[12:13], v[12:13], 0, v[32:33]
	v_fmamk_f32 v16, v16, 0x3e0293ee, v39
	v_fmamk_f32 v17, v17, 0x3e0293ee, v39
	v_fmamk_f32 v18, v18, 0x3e0293ee, v39
	v_fmamk_f32 v19, v19, 0x3e0293ee, v39
	v_fmamk_f32 v20, v20, 0x3e0293ee, v39
	v_fmamk_f32 v21, v21, 0x3e0293ee, v39
	v_fmamk_f32 v22, v22, 0x3e0293ee, v39
	v_fmamk_f32 v23, v23, 0x3e0293ee, v39
	v_fmamk_f32 v56, v24, 0x3e0293ee, v39
	v_fmamk_f32 v57, v25, 0x3e0293ee, v39
	v_fmamk_f32 v58, v26, 0x3e0293ee, v39
	v_fmamk_f32 v59, v27, 0x3e0293ee, v39
	v_fmamk_f32 v60, v28, 0x3e0293ee, v39
	v_fmamk_f32 v61, v29, 0x3e0293ee, v39
	v_fmamk_f32 v62, v30, 0x3e0293ee, v39
	v_fmamk_f32 v63, v31, 0x3e0293ee, v39
	v_fmamk_f32 v52, v2, 0x3e0293ee, v39
	v_fmamk_f32 v53, v3, 0x3e0293ee, v39
	v_fmamk_f32 v44, v6, 0x3e0293ee, v39
	v_fmamk_f32 v45, v7, 0x3e0293ee, v39
	v_fmamk_f32 v48, v10, 0x3e0293ee, v39
	v_fmamk_f32 v49, v11, 0x3e0293ee, v39
	v_fmamk_f32 v42, v14, 0x3e0293ee, v39
	v_fmac_f32_e32 v39, 0x3e0293ee, v15
	global_load_dwordx4 v[0:3], v[0:1], off
	v_exp_f32_e32 v25, v16
	global_load_dwordx4 v[4:7], v[4:5], off
	v_exp_f32_e32 v27, v17
	global_load_dwordx4 v[8:11], v[8:9], off
	v_exp_f32_e32 v28, v18
	global_load_dwordx4 v[12:15], v[12:13], off
	v_exp_f32_e32 v29, v19
	v_exp_f32_e32 v30, v20
	v_exp_f32_e32 v31, v21
	v_exp_f32_e32 v24, v22
	v_exp_f32_e32 v26, v23
	v_exp_f32_e32 v19, v56
	v_exp_f32_e32 v21, v57
	v_exp_f32_e32 v22, v58
	v_exp_f32_e32 v23, v59
	v_exp_f32_e32 v16, v60
	v_exp_f32_e32 v17, v61
	v_exp_f32_e32 v18, v62
	v_exp_f32_e32 v20, v63
	s_waitcnt vmcnt(0)
	s_waitcnt vmcnt(3)
	ds_write_b128 v191, v[0:3] offset:16384
	s_waitcnt vmcnt(2)
	ds_write_b128 v192, v[4:7] offset:16384
	s_waitcnt vmcnt(1)
	ds_write_b128 v194, v[8:11] offset:49152
	s_waitcnt vmcnt(0)
	ds_write_b128 v196, v[12:15] offset:49152
	s_waitcnt lgkmcnt(0)
	s_barrier
; #define SBAR() __builtin_amdgcn_sched_barrier(0)
; __device__ __forceinline__ void finishSM(f32x16& p0, f32x16& p1, float alpha, float& l_reg, bf16x8& pa0, bf16x8& pa1, bf16x8& pa2, bf16x8& pa3) {
; #pragma unroll
;   for (int r = 0; r < 16; ++r) p1[r] = __builtin_amdgcn_exp2f(p1[r]);
;   float ps = 0;
; #pragma unroll
;   for (int r = 0; r < 16; ++r) ps += p0[r];
; #pragma unroll
;   for (int r = 0; r < 16; ++r) ps += p1[r];
;   { auto rr = __builtin_amdgcn_permlane32_swap(__float_as_uint(ps), __float_as_uint(ps), false, false);
;     ps = __uint_as_float(rr[0]) + __uint_as_float(rr[1]); }
;   l_reg = l_reg * alpha + ps;
;     ...
;   PK4(p0, 0, pa0); PK4(p0, 8, pa1); PK4(p1, 0, pa2); PK4(p1, 8, pa3);
;     ...
; }
; template <int DQK>
; __device__ __forceinline__ void qkt(f32x16& p0, f32x16& p1, const char* Ks, const bf16x8* qr, const char* ql, int r32, int hi) {
;   p0 = f32x16{}; p1 = f32x16{};
; #pragma unroll
;   for (int d0 = 0; d0 < DQK / 16; ++d0) { const int cb = (d0 * 16 + hi * 8) * 2;
;     bf16x8 b0 = *reinterpret_cast<const bf16x8*>(Ks + r32 * (DQK * 2) + (cb ^ ((r32 & 7) << 4)));
;     bf16x8 b1 = *reinterpret_cast<const bf16x8*>(Ks + (32 + r32) * (DQK * 2) + (cb ^ ((r32 & 7) << 4)));
;     constexpr int NQR = DQK == 192 ? 4 : 8;
;     bf16x8 qv; if (d0 < NQR) qv = qr[d0 < NQR ? d0 : 0]; else qv = *reinterpret_cast<const bf16x8*>(ql + (d0 - NQR) * 1024);
;     p0 = __builtin_amdgcn_mfma_f32_32x32x16_bf16(b0, qv, p0, 0, 0, 0);
;     p1 = __builtin_amdgcn_mfma_f32_32x32x16_bf16(b1, qv, p1, 0, 0, 0); }
; template <int MODE>
; __device__ __forceinline__ void attn_body(const Job J, char* lds) {
;     ...
;     SBAR(); qkt<DQK>(pB0, pB1, K_lds + SHM_K, qr, ql, r32, hi);
;     finishSM(pA0, pA1, alA, l_reg, pa0, pa1, pa2, pa3); SBAR();
;     SLOAD(j + 1); SBAR();
	ds_read_b128 v[0:3], v166 offset:49152
	ds_read_b128 v[4:7], v166 offset:57344
	v_add_f32_e32 v32, 0, v25
	v_add_f32_e32 v32, v27, v32
	v_add_f32_e32 v32, v28, v32
	s_waitcnt lgkmcnt(1)
	v_mfma_f32_32x32x16_bf16 v[80:95], v[0:3], v[124:127], 0
	v_add_f32_e32 v32, v29, v32
	v_add_f32_e32 v32, v30, v32
	v_add_f32_e32 v32, v31, v32
	v_add_f32_e32 v32, v24, v32
	v_add_f32_e32 v32, v26, v32
	v_add_f32_e32 v32, v19, v32
	v_add_f32_e32 v32, v21, v32
	s_waitcnt lgkmcnt(0)
	v_mfma_f32_32x32x16_bf16 v[64:79], v[4:7], v[124:127], 0
	ds_read_b128 v[0:3], v167 offset:49152
	ds_read_b128 v[4:7], v167 offset:57344
	v_add_f32_e32 v32, v22, v32
	v_add_f32_e32 v32, v23, v32
	v_add_f32_e32 v32, v16, v32
	v_add_f32_e32 v32, v17, v32
	v_add_f32_e32 v32, v18, v32
	v_add_f32_e32 v32, v20, v32
	s_waitcnt lgkmcnt(1)
	v_mfma_f32_32x32x16_bf16 v[80:95], v[0:3], v[120:123], v[80:95]
	v_exp_f32_e32 v8, v46
	v_exp_f32_e32 v9, v47
	v_exp_f32_e32 v10, v48
	v_exp_f32_e32 v11, v49
	v_exp_f32_e32 v12, v40
	v_exp_f32_e32 v13, v41
	v_exp_f32_e32 v14, v42
	s_waitcnt lgkmcnt(0)
	v_mfma_f32_32x32x16_bf16 v[64:79], v[4:7], v[120:123], v[64:79]
	ds_read_b128 v[0:3], v168 offset:49152
	ds_read_b128 v[4:7], v168 offset:57344
	v_exp_f32_e32 v15, v39
	s_waitcnt lgkmcnt(1)
	v_mfma_f32_32x32x16_bf16 v[80:95], v[0:3], v[116:119], v[80:95]
	s_waitcnt lgkmcnt(0)
	v_mfma_f32_32x32x16_bf16 v[64:79], v[4:7], v[116:119], v[64:79]
	ds_read_b128 v[0:3], v169 offset:49152
	ds_read_b128 v[4:7], v169 offset:57344
	s_waitcnt lgkmcnt(1)
	v_mfma_f32_32x32x16_bf16 v[80:95], v[0:3], v[112:115], v[80:95]
	s_waitcnt lgkmcnt(0)
	v_mfma_f32_32x32x16_bf16 v[64:79], v[4:7], v[112:115], v[64:79]
	ds_read_b128 v[0:3], v188 offset:49152
	ds_read_b128 v[4:7], v188 offset:57344
	s_waitcnt lgkmcnt(1)
	v_mfma_f32_32x32x16_bf16 v[80:95], v[0:3], v[108:111], v[80:95]
	s_waitcnt lgkmcnt(0)
	v_mfma_f32_32x32x16_bf16 v[64:79], v[4:7], v[108:111], v[64:79]
	ds_read_b128 v[0:3], v189 offset:49152
	ds_read_b128 v[4:7], v189 offset:57344
	s_waitcnt lgkmcnt(1)
	v_mfma_f32_32x32x16_bf16 v[80:95], v[0:3], v[104:107], v[80:95]
	s_waitcnt lgkmcnt(0)
	v_mfma_f32_32x32x16_bf16 v[64:79], v[4:7], v[104:107], v[64:79]
	ds_read_b128 v[0:3], v190 offset:49152
	ds_read_b128 v[4:7], v190 offset:57344
	s_waitcnt lgkmcnt(1)
	v_mfma_f32_32x32x16_bf16 v[80:95], v[0:3], v[100:103], v[80:95]
	s_waitcnt lgkmcnt(0)
	v_mfma_f32_32x32x16_bf16 v[64:79], v[4:7], v[100:103], v[64:79]
	ds_read_b128 v[0:3], v193 offset:49152
	ds_read_b128 v[4:7], v193 offset:57344
	v_cvt_pk_bf16_f32 v48, v25, v27
	v_cvt_pk_bf16_f32 v49, v28, v29
	s_waitcnt lgkmcnt(1)
	v_mfma_f32_32x32x16_bf16 v[80:95], v[0:3], v[96:99], v[80:95]
	v_exp_f32_e32 v0, v50
	v_exp_f32_e32 v1, v51
	v_exp_f32_e32 v2, v52
	v_exp_f32_e32 v3, v53
	v_add_f32_e32 v32, v0, v32
	v_add_f32_e32 v32, v1, v32
	v_add_f32_e32 v32, v2, v32
	s_waitcnt lgkmcnt(0)
	v_mfma_f32_32x32x16_bf16 v[64:79], v[4:7], v[96:99], v[64:79]
	v_exp_f32_e32 v4, v54
	v_exp_f32_e32 v5, v43
	v_exp_f32_e32 v6, v44
	v_exp_f32_e32 v7, v45
	v_add_f32_e32 v32, v3, v32
	v_add_f32_e32 v32, v4, v32
	v_add_f32_e32 v32, v5, v32
	v_add_f32_e32 v32, v6, v32
	v_add_f32_e32 v32, v7, v32
	v_add_f32_e32 v32, v8, v32
	v_add_f32_e32 v32, v9, v32
	v_add_f32_e32 v32, v10, v32
	v_add_f32_e32 v32, v11, v32
	v_add_f32_e32 v32, v12, v32
	v_add_f32_e32 v32, v13, v32
	v_add_f32_e32 v32, v14, v32
	v_add_f32_e32 v164, v15, v32
	v_mov_b32_e32 v165, v164
	v_cvt_pk_bf16_f32 v50, v30, v31
	v_cvt_pk_bf16_f32 v51, v24, v26
	v_cvt_pk_bf16_f32 v198, v19, v21
	v_cvt_pk_bf16_f32 v199, v22, v23
	v_cvt_pk_bf16_f32 v200, v16, v17
	s_nop 1
	v_permlane32_swap_b32_e32 v164, v165
	v_permlane32_swap_b32_e32 v48, v50
	v_permlane32_swap_b32_e32 v49, v51
	v_cvt_pk_bf16_f32 v201, v18, v20
	v_permlane32_swap_b32_e32 v198, v200
	v_cvt_pk_bf16_f32 v202, v0, v1
	v_cvt_pk_bf16_f32 v203, v2, v3
	v_cvt_pk_bf16_f32 v204, v4, v5
	v_cvt_pk_bf16_f32 v205, v6, v7
	v_cvt_pk_bf16_f32 v206, v8, v9
	v_cvt_pk_bf16_f32 v207, v10, v11
	v_cvt_pk_bf16_f32 v208, v12, v13
	v_cvt_pk_bf16_f32 v209, v14, v15
	v_permlane32_swap_b32_e32 v199, v201
	v_permlane32_swap_b32_e32 v202, v204
	v_permlane32_swap_b32_e32 v203, v205
	v_permlane32_swap_b32_e32 v206, v208
	v_permlane32_swap_b32_e32 v207, v209
	s_or_b32 s10, s1, 0x4080
	v_add_u32_e32 v4, s10, v195
	v_mad_i64_i32 v[0:1], s[8:9], v4, s81, v[152:153]
	v_add_u32_e32 v5, s10, v197
	v_mad_i64_i32 v[2:3], s[8:9], v5, s81, v[152:153]
	global_load_dwordx4 v[128:131], v[0:1], off
	global_load_dwordx4 v[132:135], v[2:3], off
	v_mad_i64_i32 v[0:1], s[8:9], v4, s81, v[150:151]
	v_mad_i64_i32 v[2:3], s[8:9], v5, s81, v[150:151]
	global_load_dwordx4 v[136:139], v[0:1], off
	global_load_dwordx4 v[140:143], v[2:3], off
	ds_read_b64_tr_b16 v[0:1], v161 offset:0
	ds_read_b64_tr_b16 v[2:3], v161 offset:0x800
	ds_read_b64_tr_b16 v[16:17], v161 offset:0x1000
	ds_read_b64_tr_b16 v[18:19], v161 offset:0x1800
	ds_read_b64_tr_b16 v[20:21], v161 offset:0x2000
	ds_read_b64_tr_b16 v[22:23], v161 offset:0x2800
	ds_read_b64_tr_b16 v[24:25], v161 offset:0x3000
	ds_read_b64_tr_b16 v[26:27], v161 offset:0x3800
	s_waitcnt lgkmcnt(0)
; #define SBAR() __builtin_amdgcn_sched_barrier(0)
; #define SWAIT() asm volatile("s_waitcnt vmcnt(0)" ::: "memory")
; #define RESC(a) do { if (__any((a) < 1.f)) { if (hi == 0) al_l[r32] = (a); asm volatile("s_waitcnt lgkmcnt(0)" ::: "memory"); \
;     _Pragma("unroll") for (int d = 0; d < 4; ++d) _Pragma("unroll") for (int r = 0; r < 16; ++r) o[d][r] *= al_l[crow(r, hi)]; } } while (0)
; template <int D0> __device__ __forceinline__ void pv_one(f32x16& od, int vb, bf16x8 pa0, bf16x8 pa1, bf16x8 pa2, bf16x8 pa3) {
;   const s16x4 l0 = tr_read<v_rd_off(D0, 0, 0)>(vb), h0 = tr_read<v_rd_off(D0, 0, 1)>(vb), l1 = tr_read<v_rd_off(D0, 1, 0)>(vb), h1 = tr_read<v_rd_off(D0, 1, 1)>(vb);
;   const s16x4 l2 = tr_read<v_rd_off(D0, 2, 0)>(vb), h2 = tr_read<v_rd_off(D0, 2, 1)>(vb), l3 = tr_read<v_rd_off(D0, 3, 0)>(vb), h3 = tr_read<v_rd_off(D0, 3, 1)>(vb);
;   asm volatile("s_waitcnt lgkmcnt(0)" ::: "memory"); SBAR();
;     ...
;   od = __builtin_amdgcn_mfma_f32_32x32x16_bf16(pa0, PK(l0, h0), od, 0, 0, 0);
;   od = __builtin_amdgcn_mfma_f32_32x32x16_bf16(pa1, PK(l1, h1), od, 0, 0, 0);
;   od = __builtin_amdgcn_mfma_f32_32x32x16_bf16(pa2, PK(l2, h2), od, 0, 0, 0);
;   od = __builtin_amdgcn_mfma_f32_32x32x16_bf16(pa3, PK(l3, h3), od, 0, 0, 0);
;     ...
; }
; __device__ __forceinline__ void pv_d0(f32x16* o, int vb, bf16x8 pa0, bf16x8 pa1, bf16x8 pa2, bf16x8 pa3) {
;   pv_one<0>(o[0], vb, pa0, pa1, pa2, pa3); pv_one<1>(o[1], vb, pa0, pa1, pa2, pa3); pv_one<2>(o[2], vb, pa0, pa1, pa2, pa3); pv_one<3>(o[3], vb, pa0, pa1, pa2, pa3);
; template <int MODE>
; __device__ __forceinline__ void attn_body(const Job J, char* lds) {
;     ...
;   f32x16 pA0, pA1, pB0, pB1; float mnA, mnB, alA, alB; bf16x8 pa0, pa1, pa2, pa3; const int NT = J.NT;
;   SLOAD(0); SWAIT(); SWRITE(0); __syncthreads();
;   qkt<DQK>(pA0, pA1, K_lds, qr, ql, r32, hi); MASK(pA0, pA1, 0); partialSM(pA0, pA1, m_reg, mnA, alA, C, THRS);
;   SLOAD(1);
;   SWAIT(); SWRITE(1); __syncthreads();
;   for (int j = 1; j + 1 < NT; j += 2) {
;     SBAR(); qkt<DQK>(pB0, pB1, K_lds + SHM_K, qr, ql, r32, hi);
;     finishSM(pA0, pA1, alA, l_reg, pa0, pa1, pa2, pa3); SBAR();
;     SLOAD(j + 1); SBAR();
;     pv_d0(o, vb0, pa0, pa1, pa2, pa3); MASK(pB0, pB1, j); partialSM(pB0, pB1, m_reg, mnB, alB, C, THRS);
;     __syncthreads(); SWAIT(); SWRITE(0);
;     RESC(alB); __syncthreads();
	s_nop 0
	v_mfma_f32_32x32x16_bf16 v[0:15], v[48:51], v[0:3], 0
	v_mfma_f32_32x32x16_bf16 v[0:15], v[198:201], v[16:19], v[0:15]
	ds_read_b64_tr_b16 v[16:17], v161 offset:0x200
	ds_read_b64_tr_b16 v[18:19], v161 offset:0xa00
	ds_read_b64_tr_b16 v[32:33], v161 offset:0x1200
	ds_read_b64_tr_b16 v[34:35], v161 offset:0x1a00
	ds_read_b64_tr_b16 v[36:37], v161 offset:0x2200
	ds_read_b64_tr_b16 v[38:39], v161 offset:0x2a00
	ds_read_b64_tr_b16 v[40:41], v161 offset:0x3200
	v_mfma_f32_32x32x16_bf16 v[0:15], v[202:205], v[20:23], v[0:15]
	ds_read_b64_tr_b16 v[42:43], v161 offset:0x3a00
	s_waitcnt lgkmcnt(0)
	v_mfma_f32_32x32x16_bf16 v[0:15], v[206:209], v[24:27], v[0:15]
	v_mfma_f32_32x32x16_bf16 v[16:31], v[48:51], v[16:19], 0
	v_mfma_f32_32x32x16_bf16 v[16:31], v[198:201], v[32:35], v[16:31]
	ds_read_b64_tr_b16 v[32:33], v161 offset:0x400
	ds_read_b64_tr_b16 v[34:35], v161 offset:0xc00
	ds_read_b64_tr_b16 v[52:53], v161 offset:0x1400
	ds_read_b64_tr_b16 v[54:55], v161 offset:0x1c00
	ds_read_b64_tr_b16 v[56:57], v161 offset:0x2400
	ds_read_b64_tr_b16 v[58:59], v161 offset:0x2c00
	ds_read_b64_tr_b16 v[60:61], v161 offset:0x3400
	v_mfma_f32_32x32x16_bf16 v[16:31], v[202:205], v[36:39], v[16:31]
	ds_read_b64_tr_b16 v[62:63], v161 offset:0x3c00
	s_waitcnt lgkmcnt(0)
	v_mfma_f32_32x32x16_bf16 v[16:31], v[206:209], v[40:43], v[16:31]
	v_mfma_f32_32x32x16_bf16 v[32:47], v[48:51], v[32:35], 0
	v_mfma_f32_32x32x16_bf16 v[32:47], v[198:201], v[52:55], v[32:47]
	ds_read_b64_tr_b16 v[52:53], v161 offset:0x600
	ds_read_b64_tr_b16 v[54:55], v161 offset:0xe00
	ds_read_b64_tr_b16 v[210:211], v161 offset:0x1600
	ds_read_b64_tr_b16 v[212:213], v161 offset:0x1e00
	ds_read_b64_tr_b16 v[214:215], v161 offset:0x2600
	ds_read_b64_tr_b16 v[216:217], v161 offset:0x2e00
	ds_read_b64_tr_b16 v[218:219], v161 offset:0x3600
	v_mfma_f32_32x32x16_bf16 v[32:47], v[202:205], v[56:59], v[32:47]
	ds_read_b64_tr_b16 v[220:221], v161 offset:0x3e00
	s_waitcnt lgkmcnt(0)
	v_mfma_f32_32x32x16_bf16 v[32:47], v[206:209], v[60:63], v[32:47]
	v_mfma_f32_32x32x16_bf16 v[48:63], v[48:51], v[52:55], 0
	v_max_f32_e32 v148, v81, v81
	s_barrier
	s_waitcnt vmcnt(0)
	s_waitcnt vmcnt(3)
	ds_write_b128 v191, v[128:131]
	s_waitcnt vmcnt(2)
	ds_write_b128 v192, v[132:135]
	s_waitcnt vmcnt(1)
	ds_write_b128 v194, v[136:139] offset:32768
	s_waitcnt vmcnt(0)
	ds_write_b128 v196, v[140:143] offset:32768
	v_mfma_f32_32x32x16_bf16 v[48:63], v[198:201], v[210:213], v[48:63]
	v_max_f32_e32 v198, v80, v80
	v_max_f32_e32 v148, v198, v148
	v_max3_f32 v148, v148, v82, v83
	v_max3_f32 v148, v148, v84, v85
	v_max3_f32 v148, v148, v86, v87
	v_max3_f32 v148, v148, v88, v89
	v_max3_f32 v148, v148, v90, v91
	v_max3_f32 v148, v148, v92, v93
	v_max3_f32 v148, v148, v94, v95
	v_max3_f32 v148, v148, v64, v65
	v_max3_f32 v148, v148, v66, v67
	v_max3_f32 v148, v148, v68, v69
	v_max3_f32 v148, v148, v70, v71
	v_max3_f32 v148, v148, v72, v73
	v_mfma_f32_32x32x16_bf16 v[48:63], v[202:205], v[214:217], v[48:63]
	v_max3_f32 v148, v148, v74, v75
	v_max3_f32 v148, v148, v76, v77
	v_max3_f32 v148, v148, v78, v79
	v_mov_b32_e32 v198, v148
	s_nop 1
	v_permlane32_swap_b32_e32 v148, v198
	v_max_f32_e32 v198, v198, v198
	v_max_f32_e32 v148, v148, v148
	v_max_f32_e32 v148, v148, v198
	v_max_f32_e32 v200, v146, v148
	v_mfma_f32_32x32x16_bf16 v[48:63], v[206:209], v[218:221], v[48:63]
	v_sub_f32_e32 v198, v148, v146
	v_sub_f32_e32 v148, v146, v200
	v_mul_f32_e32 v148, 0x3e0293ee, v148
	v_exp_f32_e32 v148, v148
	v_cmp_ge_f32_e32 vcc, s88, v198
	s_cmp_eq_u64 vcc, exec
	s_cselect_b64 s[8:9], -1, 0
	v_cndmask_b32_e64 v198, v148, 1.0, s[8:9]
	v_cmp_gt_f32_e32 vcc, 1.0, v198
	s_cbranch_vccz .LBB0_393
	s_and_saveexec_b64 s[10:11], s[6:7]
	ds_write_b32 v163, v198 offset:128
	s_or_b64 exec, exec, s[10:11]
	s_waitcnt lgkmcnt(0)
	v_add_u32_e32 v140, v149, v158
	ds_read_b128 v[128:131], v140 offset:224
	ds_read_b128 v[132:135], v140 offset:192
	ds_read_b128 v[136:139], v140 offset:160
	ds_read_b128 v[140:143], v140 offset:128
	s_waitcnt lgkmcnt(3)
	v_pk_mul_f32 v[12:13], v[12:13], v[128:129]
	s_waitcnt lgkmcnt(2)
	v_pk_mul_f32 v[8:9], v[8:9], v[132:133]
	s_waitcnt lgkmcnt(1)
	v_pk_mul_f32 v[4:5], v[4:5], v[136:137]
	v_pk_mul_f32 v[14:15], v[14:15], v[130:131]
	v_pk_mul_f32 v[10:11], v[10:11], v[134:135]
	v_pk_mul_f32 v[6:7], v[6:7], v[138:139]
	s_waitcnt lgkmcnt(0)
	v_pk_mul_f32 v[2:3], v[2:3], v[142:143]
	v_pk_mul_f32 v[0:1], v[0:1], v[140:141]
	v_pk_mul_f32 v[28:29], v[28:29], v[128:129]
	v_pk_mul_f32 v[24:25], v[24:25], v[132:133]
	v_pk_mul_f32 v[20:21], v[20:21], v[136:137]
	v_pk_mul_f32 v[30:31], v[30:31], v[130:131]
	v_pk_mul_f32 v[26:27], v[26:27], v[134:135]
	v_pk_mul_f32 v[22:23], v[22:23], v[138:139]
	v_pk_mul_f32 v[18:19], v[18:19], v[142:143]
	v_pk_mul_f32 v[16:17], v[16:17], v[140:141]
	v_pk_mul_f32 v[44:45], v[44:45], v[128:129]
	v_pk_mul_f32 v[40:41], v[40:41], v[132:133]
	v_pk_mul_f32 v[36:37], v[36:37], v[136:137]
	v_pk_mul_f32 v[46:47], v[46:47], v[130:131]
	v_pk_mul_f32 v[42:43], v[42:43], v[134:135]
	v_pk_mul_f32 v[38:39], v[38:39], v[138:139]
	v_pk_mul_f32 v[34:35], v[34:35], v[142:143]
	v_pk_mul_f32 v[32:33], v[32:33], v[140:141]
	v_pk_mul_f32 v[60:61], v[60:61], v[128:129]
	v_pk_mul_f32 v[56:57], v[56:57], v[132:133]
	v_pk_mul_f32 v[52:53], v[52:53], v[136:137]
	v_pk_mul_f32 v[62:63], v[62:63], v[130:131]
	v_pk_mul_f32 v[58:59], v[58:59], v[134:135]
	v_pk_mul_f32 v[54:55], v[54:55], v[138:139]
	v_pk_mul_f32 v[50:51], v[50:51], v[142:143]
	v_pk_mul_f32 v[48:49], v[48:49], v[140:141]

; #define PG8_STAGE(bufoff, gbase, voff) do { _Pragma("unroll") for (int _i = 0; _i < 2; ++_i) \
;     __builtin_amdgcn_global_load_lds((const unsigned*)((const char*)(gbase) + (voff)[_i]), (LAS unsigned*)(lds + (bufoff) + ldsw + _i * 8192), 16, 0, 0); } while (0)
; #define PG8_WAIT_V(n) asm volatile("s_waitcnt vmcnt(" #n ")" ::: "memory")
; #define PG8_BAR __builtin_amdgcn_s_barrier()
; template <class Epi, class Sched, bool ALIGN_EPI = true>
; __device__ __forceinline__ void gemm_phase(LAS unsigned char* lds, const Gemm g, const Sched& S, const Epi& E) {
;     ...
;   for (int i = 0; i < 2; ++i) { int R, C; stage_rc(tid * 16 + i * 8192, R, C); const int Rb = Epi::PERM ? ((R & ~31) + perm32(R & 31)) : R;
;     voffA[i] = (unsigned)(R * g.lda + C) * 2u; voffB[i] = (unsigned)(Rb * g.ldb + C) * 2u; }
;   const size_t koffL = (size_t)(nt - 1) * (BK * 2);
;   const size_t hstepA = (size_t)HALF * g.lda * 2, hstepB = (size_t)HALF * g.ldb * 2;
;   const size_t tstepA = 2 * hstepA, tstepB = 2 * hstepB;
;   const unsigned ldsw = (unsigned)wid * 1024u;
;   const int aoff = lds_byte(wr * 64 + fr, fq * 8), boff = lds_byte(wc * 32 + fr, fq * 8);
;     ...
;   Unit cur, nxt; int ui = 0;
;   if (!S.next(0, cur)) return;
;   f32x4 acc[2][2][4][2];
; #pragma unroll
;   for (int a = 0; a < 2; ++a)
; #pragma unroll
;     for (int b = 0; b < 2; ++b)
; #pragma unroll
;       for (int m = 0; m < 4; ++m)
; #pragma unroll
;         for (int n = 0; n < 2; ++n) acc[a][b][m][n] = (f32x4){0.f, 0.f, 0.f, 0.f};
;   bf16x8 At[4][2], B0[2][2], B1[2][2];
;   ptrdiff_t kstep = cur.kr ? -(ptrdiff_t)(BK * 2) : (ptrdiff_t)(BK * 2);
;   const char* cA = (const char*)g.A + (size_t)cur.pm * tstepA + cur.kb + (cur.kr ? koffL : 0); const char* cB = (const char*)g.Bt + (size_t)cur.pn * tstepB + cur.kb + (cur.kr ? koffL : 0);
;   PG8_STAGE(PG8_SB(0, 0), cB, voffB); PG8_STAGE(PG8_SB(0, 1), cB + hstepB, voffB); PG8_STAGE(PG8_SA(0, 0), cA, voffA); PG8_STAGE(PG8_SA(0, 1), cA + hstepA, voffA);
;   if (wr == 1) PG8_BAR;
;   PG8_WAIT_V(2); PG8_BAR;
;   PG8_STAGE(PG8_SB(1, 0), cB + kstep, voffB); PG8_STAGE(PG8_SA(1, 0), cA + kstep, voffA); PG8_STAGE(PG8_SB(1, 1), cB + hstepB + kstep, voffB);
;   PG8_WAIT_V(6); PG8_BAR;
.LBB0_887:
	s_lshl_b32 s16, s16, 5
	s_and_b32 s22, s16, 0x60
	s_mov_b64 s[16:17], 0x80
	s_add_i32 m0, s41, 0x18000
	v_lshl_add_u64 v[6:7], v[6:7], 0, s[16:17]
	s_lshl_b32 s19, s18, 13
	s_lshl_b32 s23, s22, 7
	s_waitcnt vmcnt(2)
	s_barrier
	global_load_lds_dwordx4 v[6:7], off
	v_lshl_add_u64 v[4:5], v[4:5], 0, s[16:17]
	s_add_i32 m0, s41, 0x1a000
	s_add_i32 s52, s41, 0x8000
	s_add_i32 s53, s41, 0xa000
	global_load_lds_dwordx4 v[4:5], off
	v_lshl_add_u64 v[0:1], v[0:1], 0, s[16:17]
	s_mov_b32 m0, s52
	s_add_u32 s20, s44, 0x80080
	global_load_lds_dwordx4 v[0:1], off
	v_lshl_add_u64 v[0:1], v[2:3], 0, s[16:17]
	s_mov_b32 m0, s53
	s_addc_u32 s21, s45, 0
	global_load_lds_dwordx4 v[0:1], off
	s_add_i32 m0, s41, 0x1c000
	v_lshl_add_u64 v[0:1], s[20:21], 0, v[132:133]
	global_load_lds_dwordx4 v[0:1], off
	v_lshl_add_u64 v[0:1], s[20:21], 0, v[128:129]
	s_add_i32 m0, s41, 0x1e000
	s_cmpk_lt_u32 s5, 0x100
	global_load_lds_dwordx4 v[0:1], off
	v_lshrrev_b32_e32 v1, 1, v9
	v_and_b32_e32 v1, 24, v1
	v_and_b32_e32 v0, 15, v9
	v_lshlrev_b32_e32 v2, 1, v1
	v_lshl_or_b32 v146, s18, 6, v0
	v_lshl_or_b32 v0, v0, 6, v2
	v_lshlrev_b32_e32 v2, 2, v9
	v_and_b32_e32 v2, 32, v2
	v_bitop3_b32 v3, v0, s19, v2 bitop3:0xde
	v_bitop3_b32 v147, v0, s23, v2 bitop3:0xde
	v_lshlrev_b32_e32 v0, 15, v13
	v_and_b32_e32 v0, 0xffff0000, v0
	v_or_b32_e32 v148, s22, v1
	v_lshl_add_u32 v0, v12, 12, v0
	v_and_b32_e32 v1, 1, v13
	v_lshl_or_b32 v0, v1, 6, v0
	v_lshl_add_u32 v136, v14, 1, v0
	v_lshlrev_b32_e32 v0, 15, v8
	v_and_b32_e32 v0, 0xffff0000, v0
	s_waitcnt vmcnt(6)
	v_lshl_add_u32 v0, v10, 12, v0
	v_and_b32_e32 v1, 1, v8
	s_cselect_b64 s[18:19], -1, 0
	v_lshl_or_b32 v0, v1, 6, v0
	s_add_i32 s56, 0, 0x10000
	s_add_i32 s57, 0, 0x14000
	s_sext_i32_i16 s62, s4
	s_ashr_i32 s54, s86, 31
	s_mov_b32 s55, s86
	v_mov_b32_e32 v137, v133
	v_lshl_add_u32 v138, v11, 1, v0
	v_mov_b32_e32 v139, v133
	v_mov_b64_e32 v[140:141], 0x900
	v_mov_b64_e32 v[142:143], 0x8ff
	v_add_u32_e32 v149, s56, v147
	v_add_u32_e32 v150, s57, v147
	v_add_u32_e32 v151, 0, v3
	s_mov_b64 s[20:21], 0x200000
	s_mov_b32 s58, 0x200000
	s_mov_b64 s[22:23], 0x240000
	s_mov_b32 s59, 0x240000
	s_mov_b64 s[24:25], 0x280000
	s_mov_b32 s60, 0x280000
	s_mov_b64 s[26:27], 0x2c0000
	s_mov_b32 s61, 0x2c0000
	s_barrier
	s_mov_b32 s98, 0
	s_branch .LBB0_890

; #define PG8_STAGE(bufoff, gbase, voff) do { _Pragma("unroll") for (int _i = 0; _i < 2; ++_i) \
;     __builtin_amdgcn_global_load_lds((const unsigned*)((const char*)(gbase) + (voff)[_i]), (LAS unsigned*)(lds + (bufoff) + ldsw + _i * 8192), 16, 0, 0); } while (0)
; #define PG8_LDA(dst, b, h) do { _Pragma("unroll") for (int m = 0; m < 4; ++m) _Pragma("unroll") for (int k = 0; k < 2; ++k) dst[m][k] = *(const LAS bf16x8*)(lds + PG8_SA(b, h) + aoff + m * 2048 + k * 1024); } while (0)
; #define PG8_LDB(dst, b, h) do { _Pragma("unroll") for (int n = 0; n < 2; ++n) _Pragma("unroll") for (int k = 0; k < 2; ++k) dst[n][k] = *(const LAS bf16x8*)(lds + PG8_SB(b, h) + boff + n * 2048 + k * 1024); } while (0)
; #define PG8_WAIT_V(n) asm volatile("s_waitcnt vmcnt(" #n ")" ::: "memory")
; #define PG8_WAIT_L(n) asm volatile("s_waitcnt lgkmcnt(" #n ")" ::: "memory")
; #define PG8_BAR __builtin_amdgcn_s_barrier()
; template <class Epi, class Sched, bool ALIGN_EPI = true>
; __device__ __forceinline__ void gemm_phase(LAS unsigned char* lds, const Gemm g, const Sched& S, const Epi& E) {
;     ...
;     const bool has_next = S.next(ui + 1, nxt);
;     const ptrdiff_t kstepN = has_next ? (nxt.kr ? -(ptrdiff_t)(BK * 2) : (ptrdiff_t)(BK * 2)) : kstep;
;     const char* nA = has_next ? (const char*)g.A + (size_t)nxt.pm * tstepA + nxt.kb + (nxt.kr ? koffL : 0) : cA; const char* nB = has_next ? (const char*)g.Bt + (size_t)nxt.pn * tstepB + nxt.kb + (nxt.kr ? koffL : 0) : cB;
;     for (int t = 0; t < nt; t += 2) {
;       const bool last = (t == nt - 2);
;       const char* a1 = cA + (ptrdiff_t)(t + 1) * kstep;
;       const char* a2 = last ? nA : cA + (ptrdiff_t)(t + 2) * kstep; const char* b2 = last ? nB : cB + (ptrdiff_t)(t + 2) * kstep;
;       const char* a3 = a2 + (last ? kstepN : kstep); const char* b3 = b2 + (last ? kstepN : kstep);
;       PG8_LDB(B0, 0, 0); PG8_LDB(B1, 0, 1); PG8_SCHED; PG8_LDA(At, 0, 0); PG8_STAGE(PG8_SA(1, 1), a1 + hstepA, voffA);
;       PG8_WAIT_V(8); PG8_WAIT_L(0); PG8_BAR; PG8_MMA(0, 0, At, B0); PG8_MMA(0, 1, At, B1); PG8_BAR; PG8_SCHED;
;     ...
; #pragma unroll
;     for (int a = 0; a < 2; ++a)
; #pragma unroll
;       for (int b = 0; b < 2; ++b)
; #pragma unroll
;         for (int m = 0; m < 4; ++m)
; #pragma unroll
;           for (int n = 0; n < 2; ++n) acc[a][b][m][n] = (f32x4){0.f, 0.f, 0.f, 0.f};
;     cur = nxt; cA = nA; cB = nB; kstep = kstepN; ++ui;
.LBB0_892:
	s_ashr_i32 s35, s34, 31
	s_lshl_b64 s[36:37], s[34:35], 20
	v_readlane_b32 s38, v248, 10
	v_readlane_b32 s39, v248, 11
	s_add_u32 s36, s38, s36
	s_addc_u32 s37, s39, s37
	s_and_b64 s[38:39], s[4:5], exec
	s_cselect_b32 s35, s37, s43
	s_cselect_b32 s63, s36, s42
	s_ashr_i32 s31, s30, 31
	s_lshl_b64 s[38:39], s[30:31], 20
	s_add_u32 s38, s0, s38
	s_addc_u32 s39, s1, s39
	s_and_b64 s[46:47], s[4:5], exec
	s_cselect_b32 s31, s39, s45
	s_cselect_b32 s64, s38, s44
	s_add_u32 s42, s42, 0x80080
	s_addc_u32 s43, s43, 0
	s_add_u32 s65, s44, 0x100
	v_mov_b32_e32 v0, 0
	s_addc_u32 s66, s45, 0
	s_mov_b32 s67, -2
	v_mov_b32_e32 v1, v0
	v_mov_b32_e32 v2, v0
	v_mov_b32_e32 v3, v0
	v_mov_b32_e32 v4, v0
	v_mov_b32_e32 v5, v0
	v_mov_b32_e32 v6, v0
	v_mov_b32_e32 v7, v0
	v_mov_b32_e32 v16, v0
	v_mov_b32_e32 v17, v0
	v_mov_b32_e32 v18, v0
	v_mov_b32_e32 v19, v0
	v_mov_b32_e32 v20, v0
	v_mov_b32_e32 v21, v0
	v_mov_b32_e32 v22, v0
	v_mov_b32_e32 v23, v0
	v_mov_b32_e32 v32, v0
	v_mov_b32_e32 v33, v0
	v_mov_b32_e32 v34, v0
	v_mov_b32_e32 v35, v0
	v_mov_b32_e32 v36, v0
	v_mov_b32_e32 v37, v0
	v_mov_b32_e32 v38, v0
	v_mov_b32_e32 v39, v0
	v_mov_b32_e32 v48, v0
	v_mov_b32_e32 v49, v0
	v_mov_b32_e32 v50, v0
	v_mov_b32_e32 v51, v0
	v_mov_b32_e32 v52, v0
	v_mov_b32_e32 v53, v0
	v_mov_b32_e32 v54, v0
	v_mov_b32_e32 v55, v0
	v_mov_b32_e32 v8, v0
	v_mov_b32_e32 v9, v0
	v_mov_b32_e32 v10, v0
	v_mov_b32_e32 v11, v0
	v_mov_b32_e32 v12, v0
	v_mov_b32_e32 v13, v0
	v_mov_b32_e32 v14, v0
	v_mov_b32_e32 v15, v0
	v_mov_b32_e32 v24, v0
	v_mov_b32_e32 v25, v0
	v_mov_b32_e32 v26, v0
	v_mov_b32_e32 v27, v0
	v_mov_b32_e32 v28, v0
	v_mov_b32_e32 v29, v0
	v_mov_b32_e32 v30, v0
	v_mov_b32_e32 v31, v0
	v_mov_b32_e32 v40, v0
	v_mov_b32_e32 v41, v0
	v_mov_b32_e32 v42, v0
	v_mov_b32_e32 v43, v0
	v_mov_b32_e32 v44, v0
	v_mov_b32_e32 v45, v0
	v_mov_b32_e32 v46, v0
	v_mov_b32_e32 v47, v0
	v_mov_b32_e32 v56, v0
	v_mov_b32_e32 v57, v0
	v_mov_b32_e32 v58, v0
	v_mov_b32_e32 v59, v0
	v_mov_b32_e32 v60, v0
	v_mov_b32_e32 v61, v0
	v_mov_b32_e32 v62, v0
	v_mov_b32_e32 v63, v0
	v_mov_b32_e32 v64, v0
	v_mov_b32_e32 v65, v0
	v_mov_b32_e32 v66, v0
	v_mov_b32_e32 v67, v0
	v_mov_b32_e32 v68, v0
	v_mov_b32_e32 v69, v0
	v_mov_b32_e32 v70, v0
	v_mov_b32_e32 v71, v0
	v_mov_b32_e32 v80, v0
	v_mov_b32_e32 v81, v0
	v_mov_b32_e32 v82, v0
	v_mov_b32_e32 v83, v0
	v_mov_b32_e32 v84, v0
	v_mov_b32_e32 v85, v0
	v_mov_b32_e32 v86, v0
	v_mov_b32_e32 v87, v0
	v_mov_b32_e32 v96, v0
	v_mov_b32_e32 v97, v0
	v_mov_b32_e32 v98, v0
	v_mov_b32_e32 v99, v0
	v_mov_b32_e32 v100, v0
	v_mov_b32_e32 v101, v0
	v_mov_b32_e32 v102, v0
	v_mov_b32_e32 v103, v0
	v_mov_b32_e32 v112, v0
	v_mov_b32_e32 v113, v0
	v_mov_b32_e32 v114, v0
	v_mov_b32_e32 v115, v0
	v_mov_b32_e32 v116, v0
	v_mov_b32_e32 v117, v0
	v_mov_b32_e32 v118, v0
	v_mov_b32_e32 v119, v0
	v_mov_b32_e32 v72, v0
	v_mov_b32_e32 v73, v0
	v_mov_b32_e32 v74, v0
	v_mov_b32_e32 v75, v0
	v_mov_b32_e32 v76, v0
	v_mov_b32_e32 v77, v0
	v_mov_b32_e32 v78, v0
	v_mov_b32_e32 v79, v0
	v_mov_b32_e32 v88, v0
	v_mov_b32_e32 v89, v0
	v_mov_b32_e32 v90, v0
	v_mov_b32_e32 v91, v0
	v_mov_b32_e32 v92, v0
	v_mov_b32_e32 v93, v0
	v_mov_b32_e32 v94, v0
	v_mov_b32_e32 v95, v0
	v_mov_b32_e32 v104, v0
	v_mov_b32_e32 v105, v0
	v_mov_b32_e32 v106, v0
	v_mov_b32_e32 v107, v0
	v_mov_b32_e32 v108, v0
	v_mov_b32_e32 v109, v0
	v_mov_b32_e32 v110, v0
	v_mov_b32_e32 v111, v0
	v_mov_b32_e32 v120, v0
	v_mov_b32_e32 v121, v0
	v_mov_b32_e32 v122, v0
	v_mov_b32_e32 v123, v0
	v_mov_b32_e32 v124, v0
	v_mov_b32_e32 v125, v0
	v_mov_b32_e32 v126, v0
	v_mov_b32_e32 v127, v0
	s_cmp_eq_u32 s98, 0
	s_cbranch_scc1 .LBB0_893
	ds_read_b128 v[152:155], v149
	ds_read_b128 v[156:159], v149 offset:1024
	ds_read_b128 v[160:163], v149 offset:2048
	ds_read_b128 v[164:167], v149 offset:3072
	ds_read_b128 v[172:175], v150
	ds_read_b128 v[176:179], v150 offset:1024
	ds_read_b128 v[180:183], v150 offset:2048
	ds_read_b128 v[184:187], v150 offset:3072
	s_add_u32 s44, s42, 0xfff80080
	s_addc_u32 s45, s43, -1
	s_cmp_eq_u32 s67, 28
	s_cselect_b32 s47, s35, s45
	s_cselect_b32 s46, s63, s44
	s_cselect_b32 s45, s31, s66
	s_cselect_b32 s44, s64, s65
	v_lshl_add_u64 v[144:145], s[42:43], 0, v[136:137]
	s_add_i32 m0, s41, 0xc000
	ds_read_b128 v[188:191], v151
	ds_read_b128 v[192:195], v151 offset:1024
	ds_read_b128 v[196:199], v151 offset:2048
	ds_read_b128 v[200:203], v151 offset:3072
	ds_read_b128 v[204:207], v151 offset:4096
	ds_read_b128 v[208:211], v151 offset:5120
	ds_read_b128 v[212:215], v151 offset:6144
	ds_read_b128 v[216:219], v151 offset:7168
	global_load_lds_dwordx4 v[144:145], off
	v_lshl_add_u64 v[144:145], s[42:43], 0, v[138:139]
	s_add_i32 m0, s41, 0xe000
	s_nop 0
	global_load_lds_dwordx4 v[144:145], off
	s_waitcnt vmcnt(24)
	s_waitcnt lgkmcnt(0)
	s_barrier
; #define PG8_STAGE(bufoff, gbase, voff) do { _Pragma("unroll") for (int _i = 0; _i < 2; ++_i) \
;     __builtin_amdgcn_global_load_lds((const unsigned*)((const char*)(gbase) + (voff)[_i]), (LAS unsigned*)(lds + (bufoff) + ldsw + _i * 8192), 16, 0, 0); } while (0)
; #define PG8_LDA(dst, b, h) do { _Pragma("unroll") for (int m = 0; m < 4; ++m) _Pragma("unroll") for (int k = 0; k < 2; ++k) dst[m][k] = *(const LAS bf16x8*)(lds + PG8_SA(b, h) + aoff + m * 2048 + k * 1024); } while (0)
; #define PG8_MMA(ai, bj, At, Bt) do { __builtin_amdgcn_s_setprio(1); _Pragma("unroll") for (int m = 0; m < 4; ++m) _Pragma("unroll") for (int n = 0; n < 2; ++n) _Pragma("unroll") for (int k = 0; k < 2; ++k) \
;     acc[ai][bj][m][n] = __builtin_amdgcn_mfma_f32_16x16x32_bf16(Bt[n][k], At[m][k], acc[ai][bj][m][n], 0, 0, 0); __builtin_amdgcn_s_setprio(0); } while (0)
; #define PG8_WAIT_V(n) asm volatile("s_waitcnt vmcnt(" #n ")" ::: "memory")
; #define PG8_WAIT_L(n) asm volatile("s_waitcnt lgkmcnt(" #n ")" ::: "memory")
; #define PG8_BAR __builtin_amdgcn_s_barrier()
; #define PG8_SCHED __builtin_amdgcn_sched_barrier(0)
; template <class Epi, class Sched, bool ALIGN_EPI = true>
; __device__ __forceinline__ void gemm_phase(LAS unsigned char* lds, const Gemm g, const Sched& S, const Epi& E) {
;     ...
;       PG8_WAIT_V(8); PG8_WAIT_L(0); PG8_BAR; PG8_MMA(0, 0, At, B0); PG8_MMA(0, 1, At, B1); PG8_BAR; PG8_SCHED;
;       PG8_LDA(At, 0, 1); PG8_STAGE(PG8_SB(0, 0), b2, voffB); PG8_STAGE(PG8_SB(0, 1), b2 + hstepB, voffB); PG8_STAGE(PG8_SA(0, 0), a2, voffA);
;       PG8_WAIT_V(8); PG8_WAIT_L(0); PG8_BAR; PG8_MMA(1, 0, At, B0); PG8_MMA(1, 1, At, B1); PG8_BAR; PG8_SCHED;
	s_setprio 1
	s_waitcnt lgkmcnt(0)
	v_mfma_f32_16x16x32_bf16 v[124:127], v[152:155], v[188:191], v[124:127]
	v_mfma_f32_16x16x32_bf16 v[120:123], v[160:163], v[188:191], v[120:123]
	v_mfma_f32_16x16x32_bf16 v[108:111], v[152:155], v[196:199], v[108:111]
	v_mfma_f32_16x16x32_bf16 v[104:107], v[160:163], v[196:199], v[104:107]
	v_mfma_f32_16x16x32_bf16 v[92:95], v[152:155], v[204:207], v[92:95]
	v_mfma_f32_16x16x32_bf16 v[88:91], v[160:163], v[204:207], v[88:91]
	v_mfma_f32_16x16x32_bf16 v[76:79], v[152:155], v[212:215], v[76:79]
	v_mfma_f32_16x16x32_bf16 v[72:75], v[160:163], v[212:215], v[72:75]
	v_mfma_f32_16x16x32_bf16 v[124:127], v[156:159], v[192:195], v[124:127]
	v_mfma_f32_16x16x32_bf16 v[120:123], v[164:167], v[192:195], v[120:123]
	v_mfma_f32_16x16x32_bf16 v[108:111], v[156:159], v[200:203], v[108:111]
	v_mfma_f32_16x16x32_bf16 v[104:107], v[164:167], v[200:203], v[104:107]
	v_mfma_f32_16x16x32_bf16 v[92:95], v[156:159], v[208:211], v[92:95]
	v_mfma_f32_16x16x32_bf16 v[88:91], v[164:167], v[208:211], v[88:91]
	v_mfma_f32_16x16x32_bf16 v[76:79], v[156:159], v[216:219], v[76:79]
	v_mfma_f32_16x16x32_bf16 v[72:75], v[164:167], v[216:219], v[72:75]
	s_setprio 0
	s_setprio 1
	v_mfma_f32_16x16x32_bf16 v[116:119], v[172:175], v[188:191], v[116:119]
	v_mfma_f32_16x16x32_bf16 v[112:115], v[180:183], v[188:191], v[112:115]
	v_mfma_f32_16x16x32_bf16 v[100:103], v[172:175], v[196:199], v[100:103]
	v_mfma_f32_16x16x32_bf16 v[96:99], v[180:183], v[196:199], v[96:99]
	v_mfma_f32_16x16x32_bf16 v[84:87], v[172:175], v[204:207], v[84:87]
	v_mfma_f32_16x16x32_bf16 v[80:83], v[180:183], v[204:207], v[80:83]
	v_mfma_f32_16x16x32_bf16 v[68:71], v[172:175], v[212:215], v[68:71]
	v_mfma_f32_16x16x32_bf16 v[64:67], v[180:183], v[212:215], v[64:67]
	v_mfma_f32_16x16x32_bf16 v[116:119], v[176:179], v[192:195], v[116:119]
	v_mfma_f32_16x16x32_bf16 v[112:115], v[184:187], v[192:195], v[112:115]
	v_mfma_f32_16x16x32_bf16 v[100:103], v[176:179], v[200:203], v[100:103]
	v_mfma_f32_16x16x32_bf16 v[96:99], v[184:187], v[200:203], v[96:99]
	v_mfma_f32_16x16x32_bf16 v[84:87], v[176:179], v[208:211], v[84:87]
	v_mfma_f32_16x16x32_bf16 v[80:83], v[184:187], v[208:211], v[80:83]
	v_mfma_f32_16x16x32_bf16 v[68:71], v[176:179], v[216:219], v[68:71]
	v_mfma_f32_16x16x32_bf16 v[64:67], v[184:187], v[216:219], v[64:67]
	s_setprio 0
	s_barrier
	s_add_i32 s68, s56, s2
	v_lshl_add_u64 v[144:145], s[44:45], 0, v[132:133]
	s_mov_b32 m0, s68
	ds_read_b128 v[188:191], v151 offset:16384
	ds_read_b128 v[192:195], v151 offset:17408
	ds_read_b128 v[196:199], v151 offset:18432
	ds_read_b128 v[200:203], v151 offset:19456
	ds_read_b128 v[204:207], v151 offset:20480
	ds_read_b128 v[208:211], v151 offset:21504
	ds_read_b128 v[212:215], v151 offset:22528
	ds_read_b128 v[216:219], v151 offset:23552
	global_load_lds_dwordx4 v[144:145], off
	s_add_i32 m0, s68, 0x2000
	s_add_u32 s68, s44, 0x80000
	v_lshl_add_u64 v[168:169], s[44:45], 0, v[128:129]
	s_addc_u32 s69, s45, 0
	s_add_i32 s70, s57, s2
	global_load_lds_dwordx4 v[168:169], off
	v_lshl_add_u64 v[220:221], s[68:69], 0, v[132:133]
	s_mov_b32 m0, s70
	v_lshl_add_u64 v[222:223], s[46:47], 0, v[130:131]
	global_load_lds_dwordx4 v[220:221], off
	v_lshl_add_u64 v[220:221], s[68:69], 0, v[128:129]
	s_add_i32 m0, s70, 0x2000
	s_nop 0
	global_load_lds_dwordx4 v[220:221], off
	v_lshl_add_u64 v[220:221], s[46:47], 0, v[134:135]
	s_mov_b32 m0, s41
	s_nop 0
	global_load_lds_dwordx4 v[220:221], off
	s_mov_b32 m0, s48
	s_nop 0
	global_load_lds_dwordx4 v[222:223], off
	s_waitcnt vmcnt(24)
	s_waitcnt lgkmcnt(0)
	s_barrier
	s_setprio 1
	s_waitcnt lgkmcnt(0)
	v_mfma_f32_16x16x32_bf16 v[60:63], v[152:155], v[188:191], v[60:63]
	v_mfma_f32_16x16x32_bf16 v[56:59], v[160:163], v[188:191], v[56:59]
	v_mfma_f32_16x16x32_bf16 v[44:47], v[152:155], v[196:199], v[44:47]
	v_mfma_f32_16x16x32_bf16 v[40:43], v[160:163], v[196:199], v[40:43]
	v_mfma_f32_16x16x32_bf16 v[28:31], v[152:155], v[204:207], v[28:31]
	v_mfma_f32_16x16x32_bf16 v[24:27], v[160:163], v[204:207], v[24:27]
	v_mfma_f32_16x16x32_bf16 v[12:15], v[152:155], v[212:215], v[12:15]
	v_mfma_f32_16x16x32_bf16 v[8:11], v[160:163], v[212:215], v[8:11]
	v_mfma_f32_16x16x32_bf16 v[60:63], v[156:159], v[192:195], v[60:63]
	v_mfma_f32_16x16x32_bf16 v[56:59], v[164:167], v[192:195], v[56:59]
	v_mfma_f32_16x16x32_bf16 v[44:47], v[156:159], v[200:203], v[44:47]
	v_mfma_f32_16x16x32_bf16 v[40:43], v[164:167], v[200:203], v[40:43]
	v_mfma_f32_16x16x32_bf16 v[28:31], v[156:159], v[208:211], v[28:31]
	v_mfma_f32_16x16x32_bf16 v[24:27], v[164:167], v[208:211], v[24:27]
	v_mfma_f32_16x16x32_bf16 v[12:15], v[156:159], v[216:219], v[12:15]
	v_mfma_f32_16x16x32_bf16 v[8:11], v[164:167], v[216:219], v[8:11]
	s_setprio 0
	s_setprio 1
	v_mfma_f32_16x16x32_bf16 v[52:55], v[172:175], v[188:191], v[52:55]
	v_mfma_f32_16x16x32_bf16 v[48:51], v[180:183], v[188:191], v[48:51]
	v_mfma_f32_16x16x32_bf16 v[36:39], v[172:175], v[196:199], v[36:39]
	v_mfma_f32_16x16x32_bf16 v[32:35], v[180:183], v[196:199], v[32:35]
	v_mfma_f32_16x16x32_bf16 v[20:23], v[172:175], v[204:207], v[20:23]
	v_mfma_f32_16x16x32_bf16 v[16:19], v[180:183], v[204:207], v[16:19]
	v_mfma_f32_16x16x32_bf16 v[4:7], v[172:175], v[212:215], v[4:7]
	v_mfma_f32_16x16x32_bf16 v[0:3], v[180:183], v[212:215], v[0:3]
	v_mfma_f32_16x16x32_bf16 v[52:55], v[176:179], v[192:195], v[52:55]
	v_mfma_f32_16x16x32_bf16 v[48:51], v[184:187], v[192:195], v[48:51]
	v_mfma_f32_16x16x32_bf16 v[36:39], v[176:179], v[200:203], v[36:39]
	v_mfma_f32_16x16x32_bf16 v[32:35], v[184:187], v[200:203], v[32:35]
	v_mfma_f32_16x16x32_bf16 v[20:23], v[176:179], v[208:211], v[20:23]
	v_mfma_f32_16x16x32_bf16 v[16:19], v[184:187], v[208:211], v[16:19]
	v_mfma_f32_16x16x32_bf16 v[4:7], v[176:179], v[216:219], v[4:7]
	v_mfma_f32_16x16x32_bf16 v[0:3], v[184:187], v[216:219], v[0:3]
	s_setprio 0
	s_barrier
	s_branch .Lpeel_mid_893

; #define PG8_STAGE(bufoff, gbase, voff) do { _Pragma("unroll") for (int _i = 0; _i < 2; ++_i) \
;     __builtin_amdgcn_global_load_lds((const unsigned*)((const char*)(gbase) + (voff)[_i]), (LAS unsigned*)(lds + (bufoff) + ldsw + _i * 8192), 16, 0, 0); } while (0)
; #define PG8_LDA(dst, b, h) do { _Pragma("unroll") for (int m = 0; m < 4; ++m) _Pragma("unroll") for (int k = 0; k < 2; ++k) dst[m][k] = *(const LAS bf16x8*)(lds + PG8_SA(b, h) + aoff + m * 2048 + k * 1024); } while (0)
; #define PG8_LDB(dst, b, h) do { _Pragma("unroll") for (int n = 0; n < 2; ++n) _Pragma("unroll") for (int k = 0; k < 2; ++k) dst[n][k] = *(const LAS bf16x8*)(lds + PG8_SB(b, h) + boff + n * 2048 + k * 1024); } while (0)
; #define PG8_MMA(ai, bj, At, Bt) do { __builtin_amdgcn_s_setprio(1); _Pragma("unroll") for (int m = 0; m < 4; ++m) _Pragma("unroll") for (int n = 0; n < 2; ++n) _Pragma("unroll") for (int k = 0; k < 2; ++k) \
;     acc[ai][bj][m][n] = __builtin_amdgcn_mfma_f32_16x16x32_bf16(Bt[n][k], At[m][k], acc[ai][bj][m][n], 0, 0, 0); __builtin_amdgcn_s_setprio(0); } while (0)
; #define PG8_WAIT_V(n) asm volatile("s_waitcnt vmcnt(" #n ")" ::: "memory")
; #define PG8_WAIT_L(n) asm volatile("s_waitcnt lgkmcnt(" #n ")" ::: "memory")
; #define PG8_BAR __builtin_amdgcn_s_barrier()
; #define PG8_SCHED __builtin_amdgcn_sched_barrier(0)
; template <class Epi, class Sched, bool ALIGN_EPI = true>
; __device__ __forceinline__ void gemm_phase(LAS unsigned char* lds, const Gemm g, const Sched& S, const Epi& E) {
;     ...
;       PG8_LDB(B0, 1, 0); PG8_LDB(B1, 1, 1); PG8_SCHED; PG8_LDA(At, 1, 0); PG8_STAGE(PG8_SA(0, 1), a2 + hstepA, voffA);
;       PG8_WAIT_V(8); PG8_WAIT_L(0); PG8_BAR; PG8_MMA(0, 0, At, B0); PG8_MMA(0, 1, At, B1); PG8_BAR; PG8_SCHED;
.Lpeel_mid_893:
	s_add_i32 s68, 0, 0x18000
	s_add_i32 s69, 0, 0x1c000
	v_add_u32_e32 v164, s68, v147
	v_add_u32_e32 v184, s69, v147
	ds_read_b128 v[152:155], v164
	ds_read_b128 v[156:159], v164 offset:1024
	ds_read_b128 v[160:163], v164 offset:2048
	ds_read_b128 v[164:167], v164 offset:3072
	ds_read_b128 v[172:175], v184
	ds_read_b128 v[176:179], v184 offset:1024
	ds_read_b128 v[180:183], v184 offset:2048
	ds_read_b128 v[184:187], v184 offset:3072
	s_add_u32 s46, s46, 0x80000
	s_addc_u32 s47, s47, 0
	s_mov_b32 m0, s49
	v_lshl_add_u64 v[224:225], s[46:47], 0, v[134:135]
	ds_read_b128 v[188:191], v151 offset:32768
	ds_read_b128 v[192:195], v151 offset:33792
	ds_read_b128 v[196:199], v151 offset:34816
	ds_read_b128 v[200:203], v151 offset:35840
	ds_read_b128 v[204:207], v151 offset:36864
	ds_read_b128 v[208:211], v151 offset:37888
	ds_read_b128 v[212:215], v151 offset:38912
	ds_read_b128 v[216:219], v151 offset:39936
	global_load_lds_dwordx4 v[224:225], off
	v_lshl_add_u64 v[224:225], s[46:47], 0, v[130:131]
	s_mov_b32 m0, s50
	s_nop 0
	global_load_lds_dwordx4 v[224:225], off
	s_waitcnt vmcnt(8)
	s_waitcnt lgkmcnt(0)
	s_barrier
	s_setprio 1
	s_waitcnt lgkmcnt(0)
	v_mfma_f32_16x16x32_bf16 v[124:127], v[152:155], v[188:191], v[124:127]
	v_mfma_f32_16x16x32_bf16 v[120:123], v[160:163], v[188:191], v[120:123]
	v_mfma_f32_16x16x32_bf16 v[108:111], v[152:155], v[196:199], v[108:111]
	v_mfma_f32_16x16x32_bf16 v[104:107], v[160:163], v[196:199], v[104:107]
	v_mfma_f32_16x16x32_bf16 v[92:95], v[152:155], v[204:207], v[92:95]
	v_mfma_f32_16x16x32_bf16 v[88:91], v[160:163], v[204:207], v[88:91]
	v_mfma_f32_16x16x32_bf16 v[76:79], v[152:155], v[212:215], v[76:79]
	v_mfma_f32_16x16x32_bf16 v[72:75], v[160:163], v[212:215], v[72:75]
	v_mfma_f32_16x16x32_bf16 v[124:127], v[156:159], v[192:195], v[124:127]
	v_mfma_f32_16x16x32_bf16 v[120:123], v[164:167], v[192:195], v[120:123]
	v_mfma_f32_16x16x32_bf16 v[108:111], v[156:159], v[200:203], v[108:111]
	v_mfma_f32_16x16x32_bf16 v[104:107], v[164:167], v[200:203], v[104:107]
	v_mfma_f32_16x16x32_bf16 v[92:95], v[156:159], v[208:211], v[92:95]
	v_mfma_f32_16x16x32_bf16 v[88:91], v[164:167], v[208:211], v[88:91]
	v_mfma_f32_16x16x32_bf16 v[76:79], v[156:159], v[216:219], v[76:79]
	v_mfma_f32_16x16x32_bf16 v[72:75], v[164:167], v[216:219], v[72:75]
	s_setprio 0
	s_setprio 1
	v_mfma_f32_16x16x32_bf16 v[116:119], v[172:175], v[188:191], v[116:119]
	v_mfma_f32_16x16x32_bf16 v[112:115], v[180:183], v[188:191], v[112:115]
	v_mfma_f32_16x16x32_bf16 v[100:103], v[172:175], v[196:199], v[100:103]
	v_mfma_f32_16x16x32_bf16 v[96:99], v[180:183], v[196:199], v[96:99]
	v_mfma_f32_16x16x32_bf16 v[84:87], v[172:175], v[204:207], v[84:87]
	v_mfma_f32_16x16x32_bf16 v[80:83], v[180:183], v[204:207], v[80:83]
	v_mfma_f32_16x16x32_bf16 v[68:71], v[172:175], v[212:215], v[68:71]
	v_mfma_f32_16x16x32_bf16 v[64:67], v[180:183], v[212:215], v[64:67]
	v_mfma_f32_16x16x32_bf16 v[116:119], v[176:179], v[192:195], v[116:119]
	v_mfma_f32_16x16x32_bf16 v[112:115], v[184:187], v[192:195], v[112:115]
	v_mfma_f32_16x16x32_bf16 v[100:103], v[176:179], v[200:203], v[100:103]
	v_mfma_f32_16x16x32_bf16 v[96:99], v[184:187], v[200:203], v[96:99]
	v_mfma_f32_16x16x32_bf16 v[84:87], v[176:179], v[208:211], v[84:87]
	v_mfma_f32_16x16x32_bf16 v[80:83], v[184:187], v[208:211], v[80:83]
	v_mfma_f32_16x16x32_bf16 v[68:71], v[176:179], v[216:219], v[68:71]
	v_mfma_f32_16x16x32_bf16 v[64:67], v[184:187], v[216:219], v[64:67]
	s_setprio 0
	s_barrier
; #define PG8_STAGE(bufoff, gbase, voff) do { _Pragma("unroll") for (int _i = 0; _i < 2; ++_i) \
;     __builtin_amdgcn_global_load_lds((const unsigned*)((const char*)(gbase) + (voff)[_i]), (LAS unsigned*)(lds + (bufoff) + ldsw + _i * 8192), 16, 0, 0); } while (0)
; #define PG8_LDA(dst, b, h) do { _Pragma("unroll") for (int m = 0; m < 4; ++m) _Pragma("unroll") for (int k = 0; k < 2; ++k) dst[m][k] = *(const LAS bf16x8*)(lds + PG8_SA(b, h) + aoff + m * 2048 + k * 1024); } while (0)
; #define PG8_MMA(ai, bj, At, Bt) do { __builtin_amdgcn_s_setprio(1); _Pragma("unroll") for (int m = 0; m < 4; ++m) _Pragma("unroll") for (int n = 0; n < 2; ++n) _Pragma("unroll") for (int k = 0; k < 2; ++k) \
;     acc[ai][bj][m][n] = __builtin_amdgcn_mfma_f32_16x16x32_bf16(Bt[n][k], At[m][k], acc[ai][bj][m][n], 0, 0, 0); __builtin_amdgcn_s_setprio(0); } while (0)
; #define PG8_WAIT_V(n) asm volatile("s_waitcnt vmcnt(" #n ")" ::: "memory")
; #define PG8_WAIT_L(n) asm volatile("s_waitcnt lgkmcnt(" #n ")" ::: "memory")
; #define PG8_BAR __builtin_amdgcn_s_barrier()
; #define PG8_SCHED __builtin_amdgcn_sched_barrier(0)
; template <class Epi, class Sched, bool ALIGN_EPI = true>
; __device__ __forceinline__ void gemm_phase(LAS unsigned char* lds, const Gemm g, const Sched& S, const Epi& E) {
;     ...
;       PG8_LDA(At, 1, 1); PG8_STAGE(PG8_SB(1, 0), b3, voffB); PG8_STAGE(PG8_SB(1, 1), b3 + hstepB, voffB); PG8_STAGE(PG8_SA(1, 0), a3, voffA);
;       PG8_WAIT_V(8); PG8_WAIT_L(0); PG8_BAR; PG8_MMA(1, 0, At, B0); PG8_MMA(1, 1, At, B1); PG8_BAR; PG8_SCHED;
;     }
;     if constexpr (ALIGN_EPI) { if (wr == 0) PG8_BAR; }
	s_add_i32 s46, s68, s2
	v_lshl_add_u64 v[144:145], v[144:145], 0, s[16:17]
	s_mov_b32 m0, s46
	ds_read_b128 v[188:191], v151 offset:49152
	ds_read_b128 v[192:195], v151 offset:50176
	ds_read_b128 v[196:199], v151 offset:51200
	ds_read_b128 v[200:203], v151 offset:52224
	ds_read_b128 v[204:207], v151 offset:53248
	ds_read_b128 v[208:211], v151 offset:54272
	ds_read_b128 v[212:215], v151 offset:55296
	ds_read_b128 v[216:219], v151 offset:56320
	global_load_lds_dwordx4 v[144:145], off
	s_add_i32 m0, s46, 0x2000
	s_add_u32 s44, s44, 0x80080
	v_lshl_add_u64 v[144:145], v[168:169], 0, s[16:17]
	s_addc_u32 s45, s45, 0
	s_add_i32 s46, s69, s2
	global_load_lds_dwordx4 v[144:145], off
	v_lshl_add_u64 v[144:145], s[44:45], 0, v[132:133]
	s_mov_b32 m0, s46
	s_nop 0
	global_load_lds_dwordx4 v[144:145], off
	v_lshl_add_u64 v[144:145], s[44:45], 0, v[128:129]
	s_add_i32 m0, s46, 0x2000
	s_nop 0
	global_load_lds_dwordx4 v[144:145], off
	v_lshl_add_u64 v[144:145], v[220:221], 0, s[16:17]
	s_mov_b32 m0, s52
	s_nop 0
	global_load_lds_dwordx4 v[144:145], off
	v_lshl_add_u64 v[144:145], v[222:223], 0, s[16:17]
	s_mov_b32 m0, s53
	s_nop 0
	global_load_lds_dwordx4 v[144:145], off
	s_waitcnt vmcnt(8)
	s_waitcnt lgkmcnt(0)
	s_barrier
	s_setprio 1
	s_waitcnt lgkmcnt(0)
	v_mfma_f32_16x16x32_bf16 v[60:63], v[152:155], v[188:191], v[60:63]
	v_mfma_f32_16x16x32_bf16 v[56:59], v[160:163], v[188:191], v[56:59]
	v_mfma_f32_16x16x32_bf16 v[44:47], v[152:155], v[196:199], v[44:47]
	v_mfma_f32_16x16x32_bf16 v[40:43], v[160:163], v[196:199], v[40:43]
	v_mfma_f32_16x16x32_bf16 v[28:31], v[152:155], v[204:207], v[28:31]
	v_mfma_f32_16x16x32_bf16 v[24:27], v[160:163], v[204:207], v[24:27]
	v_mfma_f32_16x16x32_bf16 v[12:15], v[152:155], v[212:215], v[12:15]
	v_mfma_f32_16x16x32_bf16 v[8:11], v[160:163], v[212:215], v[8:11]
	v_mfma_f32_16x16x32_bf16 v[60:63], v[156:159], v[192:195], v[60:63]
	v_mfma_f32_16x16x32_bf16 v[56:59], v[164:167], v[192:195], v[56:59]
	v_mfma_f32_16x16x32_bf16 v[44:47], v[156:159], v[200:203], v[44:47]
	v_mfma_f32_16x16x32_bf16 v[40:43], v[164:167], v[200:203], v[40:43]
	v_mfma_f32_16x16x32_bf16 v[28:31], v[156:159], v[208:211], v[28:31]
	v_mfma_f32_16x16x32_bf16 v[24:27], v[164:167], v[208:211], v[24:27]
	v_mfma_f32_16x16x32_bf16 v[12:15], v[156:159], v[216:219], v[12:15]
	v_mfma_f32_16x16x32_bf16 v[8:11], v[164:167], v[216:219], v[8:11]
	s_setprio 0
	s_setprio 1
	v_mfma_f32_16x16x32_bf16 v[52:55], v[172:175], v[188:191], v[52:55]
	v_mfma_f32_16x16x32_bf16 v[48:51], v[180:183], v[188:191], v[48:51]
	v_mfma_f32_16x16x32_bf16 v[36:39], v[172:175], v[196:199], v[36:39]
	v_mfma_f32_16x16x32_bf16 v[32:35], v[180:183], v[196:199], v[32:35]
	v_mfma_f32_16x16x32_bf16 v[20:23], v[172:175], v[204:207], v[20:23]
	v_mfma_f32_16x16x32_bf16 v[16:19], v[180:183], v[204:207], v[16:19]
	v_mfma_f32_16x16x32_bf16 v[4:7], v[172:175], v[212:215], v[4:7]
	v_mfma_f32_16x16x32_bf16 v[0:3], v[180:183], v[212:215], v[0:3]
	v_mfma_f32_16x16x32_bf16 v[52:55], v[176:179], v[192:195], v[52:55]
	v_mfma_f32_16x16x32_bf16 v[48:51], v[184:187], v[192:195], v[48:51]
	v_mfma_f32_16x16x32_bf16 v[36:39], v[176:179], v[200:203], v[36:39]
	v_mfma_f32_16x16x32_bf16 v[32:35], v[184:187], v[200:203], v[32:35]
	v_mfma_f32_16x16x32_bf16 v[20:23], v[176:179], v[208:211], v[20:23]
	v_mfma_f32_16x16x32_bf16 v[16:19], v[184:187], v[208:211], v[16:19]
	v_mfma_f32_16x16x32_bf16 v[4:7], v[176:179], v[216:219], v[4:7]
	v_mfma_f32_16x16x32_bf16 v[0:3], v[184:187], v[216:219], v[0:3]
	s_setprio 0
	s_barrier
	s_add_i32 s67, s67, 2
	s_add_u32 s42, s42, 0x100
	s_addc_u32 s43, s43, 0
	s_add_u32 s65, s65, 0x100
	s_addc_u32 s66, s66, 0
	s_cmp_gt_u32 s67, 29
	s_cbranch_scc0 .LBB0_893
	s_mov_b32 s98, 1
	s_and_b64 vcc, exec, s[18:19]
	s_cbranch_vccz .LBB0_896
	s_barrier

; #define PG8_STAGE(bufoff, gbase, voff) do { _Pragma("unroll") for (int _i = 0; _i < 2; ++_i) \
;     __builtin_amdgcn_global_load_lds((const unsigned*)((const char*)(gbase) + (voff)[_i]), (LAS unsigned*)(lds + (bufoff) + ldsw + _i * 8192), 16, 0, 0); } while (0)
; #define PG8_WAIT_V(n) asm volatile("s_waitcnt vmcnt(" #n ")" ::: "memory")
; #define PG8_BAR __builtin_amdgcn_s_barrier()
; template <class Epi, class Sched, bool ALIGN_EPI = true>
; __device__ __forceinline__ void gemm_phase(LAS unsigned char* lds, const Gemm g, const Sched& S, const Epi& E) {
;     ...
;   for (int i = 0; i < 2; ++i) { int R, C; stage_rc(tid * 16 + i * 8192, R, C); const int Rb = Epi::PERM ? ((R & ~31) + perm32(R & 31)) : R;
;     voffA[i] = (unsigned)(R * g.lda + C) * 2u; voffB[i] = (unsigned)(Rb * g.ldb + C) * 2u; }
;   const size_t koffL = (size_t)(nt - 1) * (BK * 2);
;   const size_t hstepA = (size_t)HALF * g.lda * 2, hstepB = (size_t)HALF * g.ldb * 2;
;   const size_t tstepA = 2 * hstepA, tstepB = 2 * hstepB;
;   const unsigned ldsw = (unsigned)wid * 1024u;
;   const int aoff = lds_byte(wr * 64 + fr, fq * 8), boff = lds_byte(wc * 32 + fr, fq * 8);
;     ...
;   Unit cur, nxt; int ui = 0;
;   if (!S.next(0, cur)) return;
;   f32x4 acc[2][2][4][2];
; #pragma unroll
;   for (int a = 0; a < 2; ++a)
; #pragma unroll
;     for (int b = 0; b < 2; ++b)
; #pragma unroll
;       for (int m = 0; m < 4; ++m)
; #pragma unroll
;         for (int n = 0; n < 2; ++n) acc[a][b][m][n] = (f32x4){0.f, 0.f, 0.f, 0.f};
;   bf16x8 At[4][2], B0[2][2], B1[2][2];
;   ptrdiff_t kstep = cur.kr ? -(ptrdiff_t)(BK * 2) : (ptrdiff_t)(BK * 2);
;   const char* cA = (const char*)g.A + (size_t)cur.pm * tstepA + cur.kb + (cur.kr ? koffL : 0); const char* cB = (const char*)g.Bt + (size_t)cur.pn * tstepB + cur.kb + (cur.kr ? koffL : 0);
;   PG8_STAGE(PG8_SB(0, 0), cB, voffB); PG8_STAGE(PG8_SB(0, 1), cB + hstepB, voffB); PG8_STAGE(PG8_SA(0, 0), cA, voffA); PG8_STAGE(PG8_SA(0, 1), cA + hstepA, voffA);
;   if (wr == 1) PG8_BAR;
;   PG8_WAIT_V(2); PG8_BAR;
;   PG8_STAGE(PG8_SB(1, 0), cB + kstep, voffB); PG8_STAGE(PG8_SA(1, 0), cA + kstep, voffA); PG8_STAGE(PG8_SB(1, 1), cB + hstepB + kstep, voffB);
;   PG8_WAIT_V(6); PG8_BAR;
.LBB0_1120:
	s_lshl_b32 s10, s10, 5
	s_and_b32 s18, s10, 0x60
	s_mov_b64 s[10:11], 0x80
	s_add_i32 m0, s25, 0x18000
	v_lshl_add_u64 v[6:7], v[6:7], 0, s[10:11]
	s_lshl_b32 s13, s12, 13
	s_lshl_b32 s19, s18, 7
	s_waitcnt vmcnt(2)
	s_barrier
	global_load_lds_dwordx4 v[6:7], off
	v_lshl_add_u64 v[4:5], v[4:5], 0, s[10:11]
	s_add_i32 m0, s25, 0x1a000
	s_add_i32 s39, s25, 0x8000
	s_add_i32 s40, s25, 0xa000
	global_load_lds_dwordx4 v[4:5], off
	v_lshl_add_u64 v[0:1], v[0:1], 0, s[10:11]
	s_mov_b32 m0, s39
	s_add_u32 s16, s30, 0x80080
	global_load_lds_dwordx4 v[0:1], off
	v_lshl_add_u64 v[0:1], v[2:3], 0, s[10:11]
	s_mov_b32 m0, s40
	s_addc_u32 s17, s31, 0
	global_load_lds_dwordx4 v[0:1], off
	s_add_i32 m0, s25, 0x1c000
	v_lshl_add_u64 v[0:1], s[16:17], 0, v[132:133]
	global_load_lds_dwordx4 v[0:1], off
	v_lshl_add_u64 v[0:1], s[16:17], 0, v[128:129]
	s_add_i32 m0, s25, 0x1e000
	s_cmpk_lt_u32 s7, 0x100
	global_load_lds_dwordx4 v[0:1], off
	v_lshrrev_b32_e32 v1, 1, v9
	v_and_b32_e32 v1, 24, v1
	v_and_b32_e32 v0, 15, v9
	v_lshlrev_b32_e32 v2, 1, v1
	v_lshl_or_b32 v148, s12, 6, v0
	v_lshl_or_b32 v0, v0, 6, v2
	v_lshlrev_b32_e32 v2, 2, v9
	v_and_b32_e32 v2, 32, v2
	v_bitop3_b32 v3, v0, s13, v2 bitop3:0xde
	v_bitop3_b32 v149, v0, s19, v2 bitop3:0xde
	v_lshlrev_b32_e32 v0, 15, v13
	v_and_b32_e32 v0, 0xffff0000, v0
	v_or_b32_e32 v150, s18, v1
	v_lshl_add_u32 v0, v12, 12, v0
	v_and_b32_e32 v1, 1, v13
	v_lshl_or_b32 v0, v1, 6, v0
	v_lshl_add_u32 v136, v14, 1, v0
	v_lshlrev_b32_e32 v0, 15, v8
	v_and_b32_e32 v0, 0xffff0000, v0
	s_waitcnt vmcnt(6)
	v_lshl_add_u32 v0, v10, 12, v0
	v_and_b32_e32 v1, 1, v8
	s_cselect_b64 s[12:13], -1, 0
	v_lshl_or_b32 v0, v1, 6, v0
	s_add_i32 s43, 0, 0x10000
	s_add_i32 s44, 0, 0x14000
	s_sext_i32_i8 s46, s6
	s_ashr_i32 s41, s86, 31
	s_mov_b32 s42, s86
	v_mov_b32_e32 v137, v133
	v_lshl_add_u32 v138, v11, 1, v0
	v_mov_b32_e32 v139, v133
	v_mov_b64_e32 v[140:141], 0x168
	v_mov_b64_e32 v[142:143], 0x167
	v_add_u32_e32 v151, s43, v149
	v_add_u32_e32 v152, s44, v149
	v_add_u32_e32 v153, 0, v3
	s_movk_i32 s45, 0xa00
	s_barrier
	s_mov_b32 s98, 0
	s_branch .LBB0_1123

; #define PG8_STAGE(bufoff, gbase, voff) do { _Pragma("unroll") for (int _i = 0; _i < 2; ++_i) \
;     __builtin_amdgcn_global_load_lds((const unsigned*)((const char*)(gbase) + (voff)[_i]), (LAS unsigned*)(lds + (bufoff) + ldsw + _i * 8192), 16, 0, 0); } while (0)
; #define PG8_LDA(dst, b, h) do { _Pragma("unroll") for (int m = 0; m < 4; ++m) _Pragma("unroll") for (int k = 0; k < 2; ++k) dst[m][k] = *(const LAS bf16x8*)(lds + PG8_SA(b, h) + aoff + m * 2048 + k * 1024); } while (0)
; #define PG8_LDB(dst, b, h) do { _Pragma("unroll") for (int n = 0; n < 2; ++n) _Pragma("unroll") for (int k = 0; k < 2; ++k) dst[n][k] = *(const LAS bf16x8*)(lds + PG8_SB(b, h) + boff + n * 2048 + k * 1024); } while (0)
; #define PG8_WAIT_V(n) asm volatile("s_waitcnt vmcnt(" #n ")" ::: "memory")
; #define PG8_WAIT_L(n) asm volatile("s_waitcnt lgkmcnt(" #n ")" ::: "memory")
; #define PG8_BAR __builtin_amdgcn_s_barrier()
; template <class Epi, class Sched, bool ALIGN_EPI = true>
; __device__ __forceinline__ void gemm_phase(LAS unsigned char* lds, const Gemm g, const Sched& S, const Epi& E) {
;     ...
;     const bool has_next = S.next(ui + 1, nxt);
;     const ptrdiff_t kstepN = has_next ? (nxt.kr ? -(ptrdiff_t)(BK * 2) : (ptrdiff_t)(BK * 2)) : kstep;
;     const char* nA = has_next ? (const char*)g.A + (size_t)nxt.pm * tstepA + nxt.kb + (nxt.kr ? koffL : 0) : cA; const char* nB = has_next ? (const char*)g.Bt + (size_t)nxt.pn * tstepB + nxt.kb + (nxt.kr ? koffL : 0) : cB;
;     for (int t = 0; t < nt; t += 2) {
;       const bool last = (t == nt - 2);
;       const char* a1 = cA + (ptrdiff_t)(t + 1) * kstep;
;       const char* a2 = last ? nA : cA + (ptrdiff_t)(t + 2) * kstep; const char* b2 = last ? nB : cB + (ptrdiff_t)(t + 2) * kstep;
;       const char* a3 = a2 + (last ? kstepN : kstep); const char* b3 = b2 + (last ? kstepN : kstep);
;       PG8_LDB(B0, 0, 0); PG8_LDB(B1, 0, 1); PG8_SCHED; PG8_LDA(At, 0, 0); PG8_STAGE(PG8_SA(1, 1), a1 + hstepA, voffA);
;       PG8_WAIT_V(8); PG8_WAIT_L(0); PG8_BAR; PG8_MMA(0, 0, At, B0); PG8_MMA(0, 1, At, B1); PG8_BAR; PG8_SCHED;
;     ...
; #pragma unroll
;     for (int a = 0; a < 2; ++a)
; #pragma unroll
;       for (int b = 0; b < 2; ++b)
; #pragma unroll
;         for (int m = 0; m < 4; ++m)
; #pragma unroll
;           for (int n = 0; n < 2; ++n) acc[a][b][m][n] = (f32x4){0.f, 0.f, 0.f, 0.f};
;     cur = nxt; cA = nA; cB = nB; kstep = kstepN; ++ui;
.LBB0_1125:
	s_ashr_i32 s19, s18, 31
	s_lshl_b64 s[20:21], s[18:19], 20
	v_readlane_b32 s22, v248, 10
	v_readlane_b32 s23, v248, 11
	s_add_u32 s20, s22, s20
	s_addc_u32 s21, s23, s21
	s_and_b64 s[22:23], s[6:7], exec
	s_cselect_b32 s19, s21, s27
	s_cselect_b32 s47, s20, s26
	s_ashr_i32 s17, s16, 31
	s_lshl_b64 s[22:23], s[16:17], 20
	s_add_u32 s22, s0, s22
	s_addc_u32 s23, s1, s23
	s_and_b64 s[34:35], s[6:7], exec
	s_cselect_b32 s17, s23, s31
	s_cselect_b32 s48, s22, s30
	s_add_u32 s26, s26, 0x80080
	s_addc_u32 s27, s27, 0
	s_add_u32 s49, s30, 0x100
	v_mov_b32_e32 v0, 0
	s_addc_u32 s50, s31, 0
	s_mov_b32 s51, -2
	v_mov_b32_e32 v1, v0
	v_mov_b32_e32 v2, v0
	v_mov_b32_e32 v3, v0
	v_mov_b32_e32 v4, v0
	v_mov_b32_e32 v5, v0
	v_mov_b32_e32 v6, v0
	v_mov_b32_e32 v7, v0
	v_mov_b32_e32 v8, v0
	v_mov_b32_e32 v9, v0
	v_mov_b32_e32 v10, v0
	v_mov_b32_e32 v11, v0
	v_mov_b32_e32 v16, v0
	v_mov_b32_e32 v17, v0
	v_mov_b32_e32 v18, v0
	v_mov_b32_e32 v19, v0
	v_mov_b32_e32 v24, v0
	v_mov_b32_e32 v25, v0
	v_mov_b32_e32 v26, v0
	v_mov_b32_e32 v27, v0
	v_mov_b32_e32 v32, v0
	v_mov_b32_e32 v33, v0
	v_mov_b32_e32 v34, v0
	v_mov_b32_e32 v35, v0
	v_mov_b32_e32 v40, v0
	v_mov_b32_e32 v41, v0
	v_mov_b32_e32 v42, v0
	v_mov_b32_e32 v43, v0
	v_mov_b32_e32 v48, v0
	v_mov_b32_e32 v49, v0
	v_mov_b32_e32 v50, v0
	v_mov_b32_e32 v51, v0
	v_mov_b32_e32 v12, v0
	v_mov_b32_e32 v13, v0
	v_mov_b32_e32 v14, v0
	v_mov_b32_e32 v15, v0
	v_mov_b32_e32 v20, v0
	v_mov_b32_e32 v21, v0
	v_mov_b32_e32 v22, v0
	v_mov_b32_e32 v23, v0
	v_mov_b32_e32 v28, v0
	v_mov_b32_e32 v29, v0
	v_mov_b32_e32 v30, v0
	v_mov_b32_e32 v31, v0
	v_mov_b32_e32 v36, v0
	v_mov_b32_e32 v37, v0
	v_mov_b32_e32 v38, v0
	v_mov_b32_e32 v39, v0
	v_mov_b32_e32 v44, v0
	v_mov_b32_e32 v45, v0
	v_mov_b32_e32 v46, v0
	v_mov_b32_e32 v47, v0
	v_mov_b32_e32 v52, v0
	v_mov_b32_e32 v53, v0
	v_mov_b32_e32 v54, v0
	v_mov_b32_e32 v55, v0
	v_mov_b32_e32 v56, v0
	v_mov_b32_e32 v57, v0
	v_mov_b32_e32 v58, v0
	v_mov_b32_e32 v59, v0
	v_mov_b32_e32 v60, v0
	v_mov_b32_e32 v61, v0
	v_mov_b32_e32 v62, v0
	v_mov_b32_e32 v63, v0
	v_mov_b32_e32 v64, v0
	v_mov_b32_e32 v65, v0
	v_mov_b32_e32 v66, v0
	v_mov_b32_e32 v67, v0
	v_mov_b32_e32 v68, v0
	v_mov_b32_e32 v69, v0
	v_mov_b32_e32 v70, v0
	v_mov_b32_e32 v71, v0
	v_mov_b32_e32 v72, v0
	v_mov_b32_e32 v73, v0
	v_mov_b32_e32 v74, v0
	v_mov_b32_e32 v75, v0
	v_mov_b32_e32 v80, v0
	v_mov_b32_e32 v81, v0
	v_mov_b32_e32 v82, v0
	v_mov_b32_e32 v83, v0
	v_mov_b32_e32 v88, v0
	v_mov_b32_e32 v89, v0
	v_mov_b32_e32 v90, v0
	v_mov_b32_e32 v91, v0
	v_mov_b32_e32 v96, v0
	v_mov_b32_e32 v97, v0
	v_mov_b32_e32 v98, v0
	v_mov_b32_e32 v99, v0
	v_mov_b32_e32 v104, v0
	v_mov_b32_e32 v105, v0
	v_mov_b32_e32 v106, v0
	v_mov_b32_e32 v107, v0
	v_mov_b32_e32 v112, v0
	v_mov_b32_e32 v113, v0
	v_mov_b32_e32 v114, v0
	v_mov_b32_e32 v115, v0
	v_mov_b32_e32 v76, v0
	v_mov_b32_e32 v77, v0
	v_mov_b32_e32 v78, v0
	v_mov_b32_e32 v79, v0
	v_mov_b32_e32 v84, v0
	v_mov_b32_e32 v85, v0
	v_mov_b32_e32 v86, v0
	v_mov_b32_e32 v87, v0
	v_mov_b32_e32 v92, v0
	v_mov_b32_e32 v93, v0
	v_mov_b32_e32 v94, v0
	v_mov_b32_e32 v95, v0
	v_mov_b32_e32 v100, v0
	v_mov_b32_e32 v101, v0
	v_mov_b32_e32 v102, v0
	v_mov_b32_e32 v103, v0
	v_mov_b32_e32 v108, v0
	v_mov_b32_e32 v109, v0
	v_mov_b32_e32 v110, v0
	v_mov_b32_e32 v111, v0
	v_mov_b32_e32 v116, v0
	v_mov_b32_e32 v117, v0
	v_mov_b32_e32 v118, v0
	v_mov_b32_e32 v119, v0
	v_mov_b32_e32 v120, v0
	v_mov_b32_e32 v121, v0
	v_mov_b32_e32 v122, v0
	v_mov_b32_e32 v123, v0
	v_mov_b32_e32 v124, v0
	v_mov_b32_e32 v125, v0
	v_mov_b32_e32 v126, v0
	v_mov_b32_e32 v127, v0
	s_cmp_eq_u32 s98, 0
	s_cbranch_scc1 .LBB0_1126
	ds_read_b128 v[144:147], v151
	ds_read_b128 v[154:157], v151 offset:1024
	ds_read_b128 v[158:161], v151 offset:2048
	ds_read_b128 v[162:165], v151 offset:3072
	ds_read_b128 v[166:169], v152
	ds_read_b128 v[172:175], v152 offset:1024
	ds_read_b128 v[176:179], v152 offset:2048
	ds_read_b128 v[180:183], v152 offset:3072
	s_add_u32 s30, s26, 0xfff80080
	s_addc_u32 s31, s27, -1
	s_cmp_eq_u32 s51, 28
	s_cselect_b32 s35, s19, s31
	s_cselect_b32 s34, s47, s30
	s_cselect_b32 s31, s17, s50
	s_cselect_b32 s30, s48, s49
	v_lshl_add_u64 v[216:217], s[26:27], 0, v[136:137]
	s_add_i32 m0, s25, 0xc000
	ds_read_b128 v[184:187], v153
	ds_read_b128 v[188:191], v153 offset:1024
	ds_read_b128 v[192:195], v153 offset:2048
	ds_read_b128 v[196:199], v153 offset:3072
	ds_read_b128 v[200:203], v153 offset:4096
	ds_read_b128 v[204:207], v153 offset:5120
	ds_read_b128 v[208:211], v153 offset:6144
	ds_read_b128 v[212:215], v153 offset:7168
	global_load_lds_dwordx4 v[216:217], off
	v_lshl_add_u64 v[216:217], s[26:27], 0, v[138:139]
	s_add_i32 m0, s25, 0xe000
	s_nop 0
	global_load_lds_dwordx4 v[216:217], off
	s_waitcnt vmcnt(24)
	s_waitcnt lgkmcnt(0)
	s_barrier
; #define PG8_STAGE(bufoff, gbase, voff) do { _Pragma("unroll") for (int _i = 0; _i < 2; ++_i) \
;     __builtin_amdgcn_global_load_lds((const unsigned*)((const char*)(gbase) + (voff)[_i]), (LAS unsigned*)(lds + (bufoff) + ldsw + _i * 8192), 16, 0, 0); } while (0)
; #define PG8_LDA(dst, b, h) do { _Pragma("unroll") for (int m = 0; m < 4; ++m) _Pragma("unroll") for (int k = 0; k < 2; ++k) dst[m][k] = *(const LAS bf16x8*)(lds + PG8_SA(b, h) + aoff + m * 2048 + k * 1024); } while (0)
; #define PG8_MMA(ai, bj, At, Bt) do { __builtin_amdgcn_s_setprio(1); _Pragma("unroll") for (int m = 0; m < 4; ++m) _Pragma("unroll") for (int n = 0; n < 2; ++n) _Pragma("unroll") for (int k = 0; k < 2; ++k) \
;     acc[ai][bj][m][n] = __builtin_amdgcn_mfma_f32_16x16x32_bf16(Bt[n][k], At[m][k], acc[ai][bj][m][n], 0, 0, 0); __builtin_amdgcn_s_setprio(0); } while (0)
; #define PG8_WAIT_V(n) asm volatile("s_waitcnt vmcnt(" #n ")" ::: "memory")
; #define PG8_WAIT_L(n) asm volatile("s_waitcnt lgkmcnt(" #n ")" ::: "memory")
; #define PG8_BAR __builtin_amdgcn_s_barrier()
; #define PG8_SCHED __builtin_amdgcn_sched_barrier(0)
; template <class Epi, class Sched, bool ALIGN_EPI = true>
; __device__ __forceinline__ void gemm_phase(LAS unsigned char* lds, const Gemm g, const Sched& S, const Epi& E) {
;     ...
;       PG8_WAIT_V(8); PG8_WAIT_L(0); PG8_BAR; PG8_MMA(0, 0, At, B0); PG8_MMA(0, 1, At, B1); PG8_BAR; PG8_SCHED;
;       PG8_LDA(At, 0, 1); PG8_STAGE(PG8_SB(0, 0), b2, voffB); PG8_STAGE(PG8_SB(0, 1), b2 + hstepB, voffB); PG8_STAGE(PG8_SA(0, 0), a2, voffA);
;       PG8_WAIT_V(8); PG8_WAIT_L(0); PG8_BAR; PG8_MMA(1, 0, At, B0); PG8_MMA(1, 1, At, B1); PG8_BAR; PG8_SCHED;
	s_setprio 1
	s_waitcnt lgkmcnt(0)
	v_mfma_f32_16x16x32_bf16 v[124:127], v[144:147], v[184:187], v[124:127]
	v_mfma_f32_16x16x32_bf16 v[120:123], v[158:161], v[184:187], v[120:123]
	v_mfma_f32_16x16x32_bf16 v[116:119], v[144:147], v[192:195], v[116:119]
	v_mfma_f32_16x16x32_bf16 v[108:111], v[158:161], v[192:195], v[108:111]
	v_mfma_f32_16x16x32_bf16 v[100:103], v[144:147], v[200:203], v[100:103]
	v_mfma_f32_16x16x32_bf16 v[92:95], v[158:161], v[200:203], v[92:95]
	v_mfma_f32_16x16x32_bf16 v[84:87], v[144:147], v[208:211], v[84:87]
	v_mfma_f32_16x16x32_bf16 v[76:79], v[158:161], v[208:211], v[76:79]
	v_mfma_f32_16x16x32_bf16 v[124:127], v[154:157], v[188:191], v[124:127]
	v_mfma_f32_16x16x32_bf16 v[120:123], v[162:165], v[188:191], v[120:123]
	v_mfma_f32_16x16x32_bf16 v[116:119], v[154:157], v[196:199], v[116:119]
	v_mfma_f32_16x16x32_bf16 v[108:111], v[162:165], v[196:199], v[108:111]
	v_mfma_f32_16x16x32_bf16 v[100:103], v[154:157], v[204:207], v[100:103]
	v_mfma_f32_16x16x32_bf16 v[92:95], v[162:165], v[204:207], v[92:95]
	v_mfma_f32_16x16x32_bf16 v[84:87], v[154:157], v[212:215], v[84:87]
	v_mfma_f32_16x16x32_bf16 v[76:79], v[162:165], v[212:215], v[76:79]
	s_setprio 0
	s_setprio 1
	v_mfma_f32_16x16x32_bf16 v[112:115], v[166:169], v[184:187], v[112:115]
	v_mfma_f32_16x16x32_bf16 v[104:107], v[176:179], v[184:187], v[104:107]
	v_mfma_f32_16x16x32_bf16 v[96:99], v[166:169], v[192:195], v[96:99]
	v_mfma_f32_16x16x32_bf16 v[88:91], v[176:179], v[192:195], v[88:91]
	v_mfma_f32_16x16x32_bf16 v[80:83], v[166:169], v[200:203], v[80:83]
	v_mfma_f32_16x16x32_bf16 v[72:75], v[176:179], v[200:203], v[72:75]
	v_mfma_f32_16x16x32_bf16 v[68:71], v[166:169], v[208:211], v[68:71]
	v_mfma_f32_16x16x32_bf16 v[64:67], v[176:179], v[208:211], v[64:67]
	v_mfma_f32_16x16x32_bf16 v[112:115], v[172:175], v[188:191], v[112:115]
	v_mfma_f32_16x16x32_bf16 v[104:107], v[180:183], v[188:191], v[104:107]
	v_mfma_f32_16x16x32_bf16 v[96:99], v[172:175], v[196:199], v[96:99]
	v_mfma_f32_16x16x32_bf16 v[88:91], v[180:183], v[196:199], v[88:91]
	v_mfma_f32_16x16x32_bf16 v[80:83], v[172:175], v[204:207], v[80:83]
	v_mfma_f32_16x16x32_bf16 v[72:75], v[180:183], v[204:207], v[72:75]
	v_mfma_f32_16x16x32_bf16 v[68:71], v[172:175], v[212:215], v[68:71]
	v_mfma_f32_16x16x32_bf16 v[64:67], v[180:183], v[212:215], v[64:67]
	s_setprio 0
	s_barrier
	s_add_i32 s52, s43, s2
	v_lshl_add_u64 v[216:217], s[30:31], 0, v[132:133]
	s_mov_b32 m0, s52
	ds_read_b128 v[184:187], v153 offset:16384
	ds_read_b128 v[188:191], v153 offset:17408
	ds_read_b128 v[192:195], v153 offset:18432
	ds_read_b128 v[196:199], v153 offset:19456
	ds_read_b128 v[200:203], v153 offset:20480
	ds_read_b128 v[204:207], v153 offset:21504
	ds_read_b128 v[208:211], v153 offset:22528
	ds_read_b128 v[212:215], v153 offset:23552
	global_load_lds_dwordx4 v[216:217], off
	s_add_i32 m0, s52, 0x2000
	s_add_u32 s52, s30, 0x80000
	v_lshl_add_u64 v[218:219], s[30:31], 0, v[128:129]
	s_addc_u32 s53, s31, 0
	s_add_i32 s54, s44, s2
	global_load_lds_dwordx4 v[218:219], off
	v_lshl_add_u64 v[220:221], s[52:53], 0, v[132:133]
	s_mov_b32 m0, s54
	v_lshl_add_u64 v[222:223], s[34:35], 0, v[130:131]
	global_load_lds_dwordx4 v[220:221], off
	v_lshl_add_u64 v[220:221], s[52:53], 0, v[128:129]
	s_add_i32 m0, s54, 0x2000
	s_nop 0
	global_load_lds_dwordx4 v[220:221], off
	v_lshl_add_u64 v[220:221], s[34:35], 0, v[134:135]
	s_mov_b32 m0, s25
	s_nop 0
	global_load_lds_dwordx4 v[220:221], off
	s_mov_b32 m0, s33
	s_nop 0
	global_load_lds_dwordx4 v[222:223], off
	s_waitcnt vmcnt(24)
	s_waitcnt lgkmcnt(0)
	s_barrier
	s_setprio 1
	s_waitcnt lgkmcnt(0)
	v_mfma_f32_16x16x32_bf16 v[60:63], v[144:147], v[184:187], v[60:63]
	v_mfma_f32_16x16x32_bf16 v[56:59], v[158:161], v[184:187], v[56:59]
	v_mfma_f32_16x16x32_bf16 v[52:55], v[144:147], v[192:195], v[52:55]
	v_mfma_f32_16x16x32_bf16 v[44:47], v[158:161], v[192:195], v[44:47]
	v_mfma_f32_16x16x32_bf16 v[36:39], v[144:147], v[200:203], v[36:39]
	v_mfma_f32_16x16x32_bf16 v[28:31], v[158:161], v[200:203], v[28:31]
	v_mfma_f32_16x16x32_bf16 v[20:23], v[144:147], v[208:211], v[20:23]
	v_mfma_f32_16x16x32_bf16 v[12:15], v[158:161], v[208:211], v[12:15]
	v_mfma_f32_16x16x32_bf16 v[60:63], v[154:157], v[188:191], v[60:63]
	v_mfma_f32_16x16x32_bf16 v[56:59], v[162:165], v[188:191], v[56:59]
	v_mfma_f32_16x16x32_bf16 v[52:55], v[154:157], v[196:199], v[52:55]
	v_mfma_f32_16x16x32_bf16 v[44:47], v[162:165], v[196:199], v[44:47]
	v_mfma_f32_16x16x32_bf16 v[36:39], v[154:157], v[204:207], v[36:39]
	v_mfma_f32_16x16x32_bf16 v[28:31], v[162:165], v[204:207], v[28:31]
	v_mfma_f32_16x16x32_bf16 v[20:23], v[154:157], v[212:215], v[20:23]
	v_mfma_f32_16x16x32_bf16 v[12:15], v[162:165], v[212:215], v[12:15]
	s_setprio 0
	s_setprio 1
	v_mfma_f32_16x16x32_bf16 v[48:51], v[166:169], v[184:187], v[48:51]
	v_mfma_f32_16x16x32_bf16 v[40:43], v[176:179], v[184:187], v[40:43]
	v_mfma_f32_16x16x32_bf16 v[32:35], v[166:169], v[192:195], v[32:35]
	v_mfma_f32_16x16x32_bf16 v[24:27], v[176:179], v[192:195], v[24:27]
	v_mfma_f32_16x16x32_bf16 v[16:19], v[166:169], v[200:203], v[16:19]
	v_mfma_f32_16x16x32_bf16 v[8:11], v[176:179], v[200:203], v[8:11]
	v_mfma_f32_16x16x32_bf16 v[4:7], v[166:169], v[208:211], v[4:7]
	v_mfma_f32_16x16x32_bf16 v[0:3], v[176:179], v[208:211], v[0:3]
	v_mfma_f32_16x16x32_bf16 v[48:51], v[172:175], v[188:191], v[48:51]
	v_mfma_f32_16x16x32_bf16 v[40:43], v[180:183], v[188:191], v[40:43]
	v_mfma_f32_16x16x32_bf16 v[32:35], v[172:175], v[196:199], v[32:35]
	v_mfma_f32_16x16x32_bf16 v[24:27], v[180:183], v[196:199], v[24:27]
	v_mfma_f32_16x16x32_bf16 v[16:19], v[172:175], v[204:207], v[16:19]
	v_mfma_f32_16x16x32_bf16 v[8:11], v[180:183], v[204:207], v[8:11]
	v_mfma_f32_16x16x32_bf16 v[4:7], v[172:175], v[212:215], v[4:7]
	v_mfma_f32_16x16x32_bf16 v[0:3], v[180:183], v[212:215], v[0:3]
	s_setprio 0
	s_barrier
	s_branch .Lpeel_mid_1126

; #define PG8_STAGE(bufoff, gbase, voff) do { _Pragma("unroll") for (int _i = 0; _i < 2; ++_i) \
;     __builtin_amdgcn_global_load_lds((const unsigned*)((const char*)(gbase) + (voff)[_i]), (LAS unsigned*)(lds + (bufoff) + ldsw + _i * 8192), 16, 0, 0); } while (0)
; #define PG8_LDA(dst, b, h) do { _Pragma("unroll") for (int m = 0; m < 4; ++m) _Pragma("unroll") for (int k = 0; k < 2; ++k) dst[m][k] = *(const LAS bf16x8*)(lds + PG8_SA(b, h) + aoff + m * 2048 + k * 1024); } while (0)
; #define PG8_LDB(dst, b, h) do { _Pragma("unroll") for (int n = 0; n < 2; ++n) _Pragma("unroll") for (int k = 0; k < 2; ++k) dst[n][k] = *(const LAS bf16x8*)(lds + PG8_SB(b, h) + boff + n * 2048 + k * 1024); } while (0)
; #define PG8_MMA(ai, bj, At, Bt) do { __builtin_amdgcn_s_setprio(1); _Pragma("unroll") for (int m = 0; m < 4; ++m) _Pragma("unroll") for (int n = 0; n < 2; ++n) _Pragma("unroll") for (int k = 0; k < 2; ++k) \
;     acc[ai][bj][m][n] = __builtin_amdgcn_mfma_f32_16x16x32_bf16(Bt[n][k], At[m][k], acc[ai][bj][m][n], 0, 0, 0); __builtin_amdgcn_s_setprio(0); } while (0)
; #define PG8_WAIT_V(n) asm volatile("s_waitcnt vmcnt(" #n ")" ::: "memory")
; #define PG8_WAIT_L(n) asm volatile("s_waitcnt lgkmcnt(" #n ")" ::: "memory")
; #define PG8_BAR __builtin_amdgcn_s_barrier()
; #define PG8_SCHED __builtin_amdgcn_sched_barrier(0)
; template <class Epi, class Sched, bool ALIGN_EPI = true>
; __device__ __forceinline__ void gemm_phase(LAS unsigned char* lds, const Gemm g, const Sched& S, const Epi& E) {
;     ...
;       PG8_LDB(B0, 1, 0); PG8_LDB(B1, 1, 1); PG8_SCHED; PG8_LDA(At, 1, 0); PG8_STAGE(PG8_SA(0, 1), a2 + hstepA, voffA);
;       PG8_WAIT_V(8); PG8_WAIT_L(0); PG8_BAR; PG8_MMA(0, 0, At, B0); PG8_MMA(0, 1, At, B1); PG8_BAR; PG8_SCHED;
.Lpeel_mid_1126:
	s_add_i32 s52, 0, 0x18000
	s_add_i32 s53, 0, 0x1c000
	v_add_u32_e32 v162, s52, v149
	v_add_u32_e32 v180, s53, v149
	ds_read_b128 v[144:147], v162
	ds_read_b128 v[154:157], v162 offset:1024
	ds_read_b128 v[158:161], v162 offset:2048
	ds_read_b128 v[162:165], v162 offset:3072
	ds_read_b128 v[166:169], v180
	ds_read_b128 v[172:175], v180 offset:1024
	ds_read_b128 v[176:179], v180 offset:2048
	ds_read_b128 v[180:183], v180 offset:3072
	s_add_u32 s34, s34, 0x80000
	s_addc_u32 s35, s35, 0
	s_mov_b32 m0, s36
	v_lshl_add_u64 v[224:225], s[34:35], 0, v[134:135]
	ds_read_b128 v[184:187], v153 offset:32768
	ds_read_b128 v[188:191], v153 offset:33792
	ds_read_b128 v[192:195], v153 offset:34816
	ds_read_b128 v[196:199], v153 offset:35840
	ds_read_b128 v[200:203], v153 offset:36864
	ds_read_b128 v[204:207], v153 offset:37888
	ds_read_b128 v[208:211], v153 offset:38912
	ds_read_b128 v[212:215], v153 offset:39936
	global_load_lds_dwordx4 v[224:225], off
	v_lshl_add_u64 v[224:225], s[34:35], 0, v[130:131]
	s_mov_b32 m0, s37
	s_nop 0
	global_load_lds_dwordx4 v[224:225], off
	s_waitcnt vmcnt(8)
	s_waitcnt lgkmcnt(0)
	s_barrier
	s_setprio 1
	s_waitcnt lgkmcnt(0)
	v_mfma_f32_16x16x32_bf16 v[124:127], v[144:147], v[184:187], v[124:127]
	v_mfma_f32_16x16x32_bf16 v[120:123], v[158:161], v[184:187], v[120:123]
	v_mfma_f32_16x16x32_bf16 v[116:119], v[144:147], v[192:195], v[116:119]
	v_mfma_f32_16x16x32_bf16 v[108:111], v[158:161], v[192:195], v[108:111]
	v_mfma_f32_16x16x32_bf16 v[100:103], v[144:147], v[200:203], v[100:103]
	v_mfma_f32_16x16x32_bf16 v[92:95], v[158:161], v[200:203], v[92:95]
	v_mfma_f32_16x16x32_bf16 v[84:87], v[144:147], v[208:211], v[84:87]
	v_mfma_f32_16x16x32_bf16 v[76:79], v[158:161], v[208:211], v[76:79]
	v_mfma_f32_16x16x32_bf16 v[124:127], v[154:157], v[188:191], v[124:127]
	v_mfma_f32_16x16x32_bf16 v[120:123], v[162:165], v[188:191], v[120:123]
	v_mfma_f32_16x16x32_bf16 v[116:119], v[154:157], v[196:199], v[116:119]
	v_mfma_f32_16x16x32_bf16 v[108:111], v[162:165], v[196:199], v[108:111]
	v_mfma_f32_16x16x32_bf16 v[100:103], v[154:157], v[204:207], v[100:103]
	v_mfma_f32_16x16x32_bf16 v[92:95], v[162:165], v[204:207], v[92:95]
	v_mfma_f32_16x16x32_bf16 v[84:87], v[154:157], v[212:215], v[84:87]
	v_mfma_f32_16x16x32_bf16 v[76:79], v[162:165], v[212:215], v[76:79]
	s_setprio 0
	s_setprio 1
	v_mfma_f32_16x16x32_bf16 v[112:115], v[166:169], v[184:187], v[112:115]
	v_mfma_f32_16x16x32_bf16 v[104:107], v[176:179], v[184:187], v[104:107]
	v_mfma_f32_16x16x32_bf16 v[96:99], v[166:169], v[192:195], v[96:99]
	v_mfma_f32_16x16x32_bf16 v[88:91], v[176:179], v[192:195], v[88:91]
	v_mfma_f32_16x16x32_bf16 v[80:83], v[166:169], v[200:203], v[80:83]
	v_mfma_f32_16x16x32_bf16 v[72:75], v[176:179], v[200:203], v[72:75]
	v_mfma_f32_16x16x32_bf16 v[68:71], v[166:169], v[208:211], v[68:71]
	v_mfma_f32_16x16x32_bf16 v[64:67], v[176:179], v[208:211], v[64:67]
	v_mfma_f32_16x16x32_bf16 v[112:115], v[172:175], v[188:191], v[112:115]
	v_mfma_f32_16x16x32_bf16 v[104:107], v[180:183], v[188:191], v[104:107]
	v_mfma_f32_16x16x32_bf16 v[96:99], v[172:175], v[196:199], v[96:99]
	v_mfma_f32_16x16x32_bf16 v[88:91], v[180:183], v[196:199], v[88:91]
	v_mfma_f32_16x16x32_bf16 v[80:83], v[172:175], v[204:207], v[80:83]
	v_mfma_f32_16x16x32_bf16 v[72:75], v[180:183], v[204:207], v[72:75]
	v_mfma_f32_16x16x32_bf16 v[68:71], v[172:175], v[212:215], v[68:71]
	v_mfma_f32_16x16x32_bf16 v[64:67], v[180:183], v[212:215], v[64:67]
	s_setprio 0
	s_barrier
; #define PG8_STAGE(bufoff, gbase, voff) do { _Pragma("unroll") for (int _i = 0; _i < 2; ++_i) \
;     __builtin_amdgcn_global_load_lds((const unsigned*)((const char*)(gbase) + (voff)[_i]), (LAS unsigned*)(lds + (bufoff) + ldsw + _i * 8192), 16, 0, 0); } while (0)
; #define PG8_LDA(dst, b, h) do { _Pragma("unroll") for (int m = 0; m < 4; ++m) _Pragma("unroll") for (int k = 0; k < 2; ++k) dst[m][k] = *(const LAS bf16x8*)(lds + PG8_SA(b, h) + aoff + m * 2048 + k * 1024); } while (0)
; #define PG8_MMA(ai, bj, At, Bt) do { __builtin_amdgcn_s_setprio(1); _Pragma("unroll") for (int m = 0; m < 4; ++m) _Pragma("unroll") for (int n = 0; n < 2; ++n) _Pragma("unroll") for (int k = 0; k < 2; ++k) \
;     acc[ai][bj][m][n] = __builtin_amdgcn_mfma_f32_16x16x32_bf16(Bt[n][k], At[m][k], acc[ai][bj][m][n], 0, 0, 0); __builtin_amdgcn_s_setprio(0); } while (0)
; #define PG8_WAIT_V(n) asm volatile("s_waitcnt vmcnt(" #n ")" ::: "memory")
; #define PG8_WAIT_L(n) asm volatile("s_waitcnt lgkmcnt(" #n ")" ::: "memory")
; #define PG8_BAR __builtin_amdgcn_s_barrier()
; #define PG8_SCHED __builtin_amdgcn_sched_barrier(0)
; template <class Epi, class Sched, bool ALIGN_EPI = true>
; __device__ __forceinline__ void gemm_phase(LAS unsigned char* lds, const Gemm g, const Sched& S, const Epi& E) {
;     ...
;       PG8_LDA(At, 1, 1); PG8_STAGE(PG8_SB(1, 0), b3, voffB); PG8_STAGE(PG8_SB(1, 1), b3 + hstepB, voffB); PG8_STAGE(PG8_SA(1, 0), a3, voffA);
;       PG8_WAIT_V(8); PG8_WAIT_L(0); PG8_BAR; PG8_MMA(1, 0, At, B0); PG8_MMA(1, 1, At, B1); PG8_BAR; PG8_SCHED;
;     }
;     if constexpr (ALIGN_EPI) { if (wr == 0) PG8_BAR; }
	s_add_i32 s34, s52, s2
	v_lshl_add_u64 v[216:217], v[216:217], 0, s[10:11]
	s_mov_b32 m0, s34
	ds_read_b128 v[184:187], v153 offset:49152
	ds_read_b128 v[188:191], v153 offset:50176
	ds_read_b128 v[192:195], v153 offset:51200
	ds_read_b128 v[196:199], v153 offset:52224
	ds_read_b128 v[200:203], v153 offset:53248
	ds_read_b128 v[204:207], v153 offset:54272
	ds_read_b128 v[208:211], v153 offset:55296
	ds_read_b128 v[212:215], v153 offset:56320
	global_load_lds_dwordx4 v[216:217], off
	s_add_i32 m0, s34, 0x2000
	s_add_u32 s30, s30, 0x80080
	v_lshl_add_u64 v[216:217], v[218:219], 0, s[10:11]
	s_addc_u32 s31, s31, 0
	s_add_i32 s34, s53, s2
	global_load_lds_dwordx4 v[216:217], off
	v_lshl_add_u64 v[216:217], s[30:31], 0, v[132:133]
	s_mov_b32 m0, s34
	s_nop 0
	global_load_lds_dwordx4 v[216:217], off
	v_lshl_add_u64 v[216:217], s[30:31], 0, v[128:129]
	s_add_i32 m0, s34, 0x2000
	s_nop 0
	global_load_lds_dwordx4 v[216:217], off
	v_lshl_add_u64 v[216:217], v[220:221], 0, s[10:11]
	s_mov_b32 m0, s39
	s_nop 0
	global_load_lds_dwordx4 v[216:217], off
	v_lshl_add_u64 v[216:217], v[222:223], 0, s[10:11]
	s_mov_b32 m0, s40
	s_nop 0
	global_load_lds_dwordx4 v[216:217], off
	s_waitcnt vmcnt(8)
	s_waitcnt lgkmcnt(0)
	s_barrier
	s_setprio 1
	s_waitcnt lgkmcnt(0)
	v_mfma_f32_16x16x32_bf16 v[60:63], v[144:147], v[184:187], v[60:63]
	v_mfma_f32_16x16x32_bf16 v[56:59], v[158:161], v[184:187], v[56:59]
	v_mfma_f32_16x16x32_bf16 v[52:55], v[144:147], v[192:195], v[52:55]
	v_mfma_f32_16x16x32_bf16 v[44:47], v[158:161], v[192:195], v[44:47]
	v_mfma_f32_16x16x32_bf16 v[36:39], v[144:147], v[200:203], v[36:39]
	v_mfma_f32_16x16x32_bf16 v[28:31], v[158:161], v[200:203], v[28:31]
	v_mfma_f32_16x16x32_bf16 v[20:23], v[144:147], v[208:211], v[20:23]
	v_mfma_f32_16x16x32_bf16 v[12:15], v[158:161], v[208:211], v[12:15]
	v_mfma_f32_16x16x32_bf16 v[60:63], v[154:157], v[188:191], v[60:63]
	v_mfma_f32_16x16x32_bf16 v[56:59], v[162:165], v[188:191], v[56:59]
	v_mfma_f32_16x16x32_bf16 v[52:55], v[154:157], v[196:199], v[52:55]
	v_mfma_f32_16x16x32_bf16 v[44:47], v[162:165], v[196:199], v[44:47]
	v_mfma_f32_16x16x32_bf16 v[36:39], v[154:157], v[204:207], v[36:39]
	v_mfma_f32_16x16x32_bf16 v[28:31], v[162:165], v[204:207], v[28:31]
	v_mfma_f32_16x16x32_bf16 v[20:23], v[154:157], v[212:215], v[20:23]
	v_mfma_f32_16x16x32_bf16 v[12:15], v[162:165], v[212:215], v[12:15]
	s_setprio 0
	s_setprio 1
	v_mfma_f32_16x16x32_bf16 v[48:51], v[166:169], v[184:187], v[48:51]
	v_mfma_f32_16x16x32_bf16 v[40:43], v[176:179], v[184:187], v[40:43]
	v_mfma_f32_16x16x32_bf16 v[32:35], v[166:169], v[192:195], v[32:35]
	v_mfma_f32_16x16x32_bf16 v[24:27], v[176:179], v[192:195], v[24:27]
	v_mfma_f32_16x16x32_bf16 v[16:19], v[166:169], v[200:203], v[16:19]
	v_mfma_f32_16x16x32_bf16 v[8:11], v[176:179], v[200:203], v[8:11]
	v_mfma_f32_16x16x32_bf16 v[4:7], v[166:169], v[208:211], v[4:7]
	v_mfma_f32_16x16x32_bf16 v[0:3], v[176:179], v[208:211], v[0:3]
	v_mfma_f32_16x16x32_bf16 v[48:51], v[172:175], v[188:191], v[48:51]
	v_mfma_f32_16x16x32_bf16 v[40:43], v[180:183], v[188:191], v[40:43]
	v_mfma_f32_16x16x32_bf16 v[32:35], v[172:175], v[196:199], v[32:35]
	v_mfma_f32_16x16x32_bf16 v[24:27], v[180:183], v[196:199], v[24:27]
	v_mfma_f32_16x16x32_bf16 v[16:19], v[172:175], v[204:207], v[16:19]
	v_mfma_f32_16x16x32_bf16 v[8:11], v[180:183], v[204:207], v[8:11]
	v_mfma_f32_16x16x32_bf16 v[4:7], v[172:175], v[212:215], v[4:7]
	v_mfma_f32_16x16x32_bf16 v[0:3], v[180:183], v[212:215], v[0:3]
	s_setprio 0
	s_barrier
	s_add_i32 s51, s51, 2
	s_add_u32 s26, s26, 0x100
	s_addc_u32 s27, s27, 0
	s_add_u32 s49, s49, 0x100
	s_addc_u32 s50, s50, 0
	s_cmp_gt_u32 s51, 29
	s_cbranch_scc0 .LBB0_1126
	s_mov_b32 s98, 1
	s_and_b64 vcc, exec, s[12:13]
	s_cbranch_vccz .LBB0_1129
	s_barrier

; #define PG8_STAGE(bufoff, gbase, voff) do { _Pragma("unroll") for (int _i = 0; _i < 2; ++_i) \
;     __builtin_amdgcn_global_load_lds((const unsigned*)((const char*)(gbase) + (voff)[_i]), (LAS unsigned*)(lds + (bufoff) + ldsw + _i * 8192), 16, 0, 0); } while (0)
; #define PG8_WAIT_V(n) asm volatile("s_waitcnt vmcnt(" #n ")" ::: "memory")
; #define PG8_BAR __builtin_amdgcn_s_barrier()
; template <class Epi, class Sched, bool ALIGN_EPI = true>
; __device__ __forceinline__ void gemm_phase(LAS unsigned char* lds, const Gemm g, const Sched& S, const Epi& E) {
;     ...
;   for (int i = 0; i < 2; ++i) { int R, C; stage_rc(tid * 16 + i * 8192, R, C); const int Rb = Epi::PERM ? ((R & ~31) + perm32(R & 31)) : R;
;     voffA[i] = (unsigned)(R * g.lda + C) * 2u; voffB[i] = (unsigned)(Rb * g.ldb + C) * 2u; }
;   const size_t koffL = (size_t)(nt - 1) * (BK * 2);
;   const size_t hstepA = (size_t)HALF * g.lda * 2, hstepB = (size_t)HALF * g.ldb * 2;
;   const size_t tstepA = 2 * hstepA, tstepB = 2 * hstepB;
;   const unsigned ldsw = (unsigned)wid * 1024u;
;   const int aoff = lds_byte(wr * 64 + fr, fq * 8), boff = lds_byte(wc * 32 + fr, fq * 8);
;     ...
;   Unit cur, nxt; int ui = 0;
;   if (!S.next(0, cur)) return;
;   f32x4 acc[2][2][4][2];
; #pragma unroll
;   for (int a = 0; a < 2; ++a)
; #pragma unroll
;     for (int b = 0; b < 2; ++b)
; #pragma unroll
;       for (int m = 0; m < 4; ++m)
; #pragma unroll
;         for (int n = 0; n < 2; ++n) acc[a][b][m][n] = (f32x4){0.f, 0.f, 0.f, 0.f};
;   bf16x8 At[4][2], B0[2][2], B1[2][2];
;   ptrdiff_t kstep = cur.kr ? -(ptrdiff_t)(BK * 2) : (ptrdiff_t)(BK * 2);
;   const char* cA = (const char*)g.A + (size_t)cur.pm * tstepA + cur.kb + (cur.kr ? koffL : 0); const char* cB = (const char*)g.Bt + (size_t)cur.pn * tstepB + cur.kb + (cur.kr ? koffL : 0);
;   PG8_STAGE(PG8_SB(0, 0), cB, voffB); PG8_STAGE(PG8_SB(0, 1), cB + hstepB, voffB); PG8_STAGE(PG8_SA(0, 0), cA, voffA); PG8_STAGE(PG8_SA(0, 1), cA + hstepA, voffA);
;   if (wr == 1) PG8_BAR;
;   PG8_WAIT_V(2); PG8_BAR;
;   PG8_STAGE(PG8_SB(1, 0), cB + kstep, voffB); PG8_STAGE(PG8_SA(1, 0), cA + kstep, voffA); PG8_STAGE(PG8_SB(1, 1), cB + hstepB + kstep, voffB);
;   PG8_WAIT_V(6); PG8_BAR;
.LBB0_1308:
	s_add_u32 s10, s84, 0x1dd5a000
	s_addc_u32 s11, s85, 0
	s_lshl_b32 s12, s12, 5
	s_and_b32 s20, s12, 0x60
	s_mov_b64 s[12:13], 0x80
	s_add_i32 m0, s27, 0x18000
	v_lshl_add_u64 v[6:7], v[6:7], 0, s[12:13]
	s_lshl_b32 s17, s16, 13
	s_lshl_b32 s21, s20, 7
	s_waitcnt vmcnt(2)
	s_barrier
	global_load_lds_dwordx4 v[6:7], off
	v_lshl_add_u64 v[4:5], v[4:5], 0, s[12:13]
	s_add_i32 m0, s27, 0x1a000
	s_add_i32 s44, s27, 0x8000
	s_add_i32 s45, s27, 0xa000
	global_load_lds_dwordx4 v[4:5], off
	v_lshl_add_u64 v[0:1], v[0:1], 0, s[12:13]
	s_mov_b32 m0, s44
	s_add_u32 s18, s34, 0x20080
	global_load_lds_dwordx4 v[0:1], off
	v_lshl_add_u64 v[0:1], v[2:3], 0, s[12:13]
	s_mov_b32 m0, s45
	s_addc_u32 s19, s35, 0
	global_load_lds_dwordx4 v[0:1], off
	s_add_i32 m0, s27, 0x1c000
	v_lshl_add_u64 v[0:1], s[18:19], 0, v[132:133]
	global_load_lds_dwordx4 v[0:1], off
	v_lshl_add_u64 v[0:1], s[18:19], 0, v[128:129]
	s_add_i32 m0, s27, 0x1e000
	s_cmpk_lt_u32 s7, 0x100
	global_load_lds_dwordx4 v[0:1], off
	v_lshrrev_b32_e32 v1, 1, v9
	v_and_b32_e32 v1, 24, v1
	v_and_b32_e32 v0, 15, v9
	v_lshlrev_b32_e32 v2, 1, v1
	v_lshl_or_b32 v148, s16, 6, v0
	v_lshl_or_b32 v0, v0, 6, v2
	v_lshlrev_b32_e32 v2, 2, v9
	v_and_b32_e32 v2, 32, v2
	v_bitop3_b32 v3, v0, s17, v2 bitop3:0xde
	v_bitop3_b32 v149, v0, s21, v2 bitop3:0xde
	v_lshlrev_b32_e32 v0, 13, v13
	v_and_b32_e32 v0, 0xffffc000, v0
	v_or_b32_e32 v150, s20, v1
	v_lshl_add_u32 v0, v12, 10, v0
	v_and_b32_e32 v1, 1, v13
	v_lshl_or_b32 v0, v1, 6, v0
	v_lshl_add_u32 v136, v14, 1, v0
	v_lshlrev_b32_e32 v0, 13, v8
	v_and_b32_e32 v0, 0xffffc000, v0
	s_waitcnt vmcnt(6)
	v_lshl_add_u32 v0, v10, 10, v0
	v_and_b32_e32 v1, 1, v8
	s_cselect_b64 s[16:17], -1, 0
	v_lshl_or_b32 v0, v1, 6, v0
	s_add_i32 s48, 0, 0x10000
	s_add_i32 s49, 0, 0x14000
	s_sext_i32_i8 s51, s6
	s_ashr_i32 s46, s86, 31
	s_mov_b32 s47, s86
	v_mov_b32_e32 v137, v133
	v_lshl_add_u32 v138, v11, 1, v0
	v_mov_b32_e32 v139, v133
	v_mov_b64_e32 v[140:141], 0x300
	v_mov_b64_e32 v[142:143], 0x2ff
	v_add_u32_e32 v151, s48, v149
	v_add_u32_e32 v152, s49, v149
	v_add_u32_e32 v153, 0, v3
	s_movk_i32 s50, 0x1800
	s_barrier
	s_mov_b32 s98, 0
	s_branch .LBB0_1311

; #define PG8_STAGE(bufoff, gbase, voff) do { _Pragma("unroll") for (int _i = 0; _i < 2; ++_i) \
;     __builtin_amdgcn_global_load_lds((const unsigned*)((const char*)(gbase) + (voff)[_i]), (LAS unsigned*)(lds + (bufoff) + ldsw + _i * 8192), 16, 0, 0); } while (0)
; #define PG8_LDA(dst, b, h) do { _Pragma("unroll") for (int m = 0; m < 4; ++m) _Pragma("unroll") for (int k = 0; k < 2; ++k) dst[m][k] = *(const LAS bf16x8*)(lds + PG8_SA(b, h) + aoff + m * 2048 + k * 1024); } while (0)
; #define PG8_LDB(dst, b, h) do { _Pragma("unroll") for (int n = 0; n < 2; ++n) _Pragma("unroll") for (int k = 0; k < 2; ++k) dst[n][k] = *(const LAS bf16x8*)(lds + PG8_SB(b, h) + boff + n * 2048 + k * 1024); } while (0)
; #define PG8_MMA(ai, bj, At, Bt) do { __builtin_amdgcn_s_setprio(1); _Pragma("unroll") for (int m = 0; m < 4; ++m) _Pragma("unroll") for (int n = 0; n < 2; ++n) _Pragma("unroll") for (int k = 0; k < 2; ++k) \
;     acc[ai][bj][m][n] = __builtin_amdgcn_mfma_f32_16x16x32_bf16(Bt[n][k], At[m][k], acc[ai][bj][m][n], 0, 0, 0); __builtin_amdgcn_s_setprio(0); } while (0)
; #define PG8_WAIT_V(n) asm volatile("s_waitcnt vmcnt(" #n ")" ::: "memory")
; #define PG8_WAIT_L(n) asm volatile("s_waitcnt lgkmcnt(" #n ")" ::: "memory")
; #define PG8_BAR __builtin_amdgcn_s_barrier()
; template <class Epi, class Sched, bool ALIGN_EPI = true>
; __device__ __forceinline__ void gemm_phase(LAS unsigned char* lds, const Gemm g, const Sched& S, const Epi& E) {
;     ...
;     for (int t = 0; t < nt; t += 2) {
;       const bool last = (t == nt - 2);
;       const char* a1 = cA + (ptrdiff_t)(t + 1) * kstep;
;       const char* a2 = last ? nA : cA + (ptrdiff_t)(t + 2) * kstep; const char* b2 = last ? nB : cB + (ptrdiff_t)(t + 2) * kstep;
;       const char* a3 = a2 + (last ? kstepN : kstep); const char* b3 = b2 + (last ? kstepN : kstep);
;       PG8_LDB(B0, 0, 0); PG8_LDB(B1, 0, 1); PG8_SCHED; PG8_LDA(At, 0, 0); PG8_STAGE(PG8_SA(1, 1), a1 + hstepA, voffA);
;       PG8_WAIT_V(8); PG8_WAIT_L(0); PG8_BAR; PG8_MMA(0, 0, At, B0); PG8_MMA(0, 1, At, B1); PG8_BAR; PG8_SCHED;
;     ...
; #pragma unroll
;     for (int a = 0; a < 2; ++a)
; #pragma unroll
;       for (int b = 0; b < 2; ++b)
; #pragma unroll
;         for (int m = 0; m < 4; ++m)
; #pragma unroll
;           for (int n = 0; n < 2; ++n) acc[a][b][m][n] = (f32x4){0.f, 0.f, 0.f, 0.f};
;     cur = nxt; cA = nA; cB = nB; kstep = kstepN; ++ui;
.LBB0_1313:
	s_ashr_i32 s21, s20, 31
	s_lshl_b64 s[22:23], s[20:21], 18
	s_add_u32 s22, s0, s22
	s_addc_u32 s23, s1, s23
	s_and_b64 s[24:25], s[6:7], exec
	s_cselect_b32 s21, s23, s31
	s_cselect_b32 s52, s22, s30
	s_ashr_i32 s19, s18, 31
	s_lshl_b64 s[24:25], s[18:19], 18
	s_add_u32 s24, s2, s24
	s_addc_u32 s25, s3, s25
	s_and_b64 s[36:37], s[6:7], exec
	s_cselect_b32 s19, s25, s35
	s_cselect_b32 s53, s24, s34
	s_add_u32 s30, s30, 0x20080
	s_addc_u32 s31, s31, 0
	s_add_u32 s54, s34, 0x100
	v_mov_b32_e32 v0, 0
	s_addc_u32 s55, s35, 0
	s_mov_b32 s56, -2
	v_mov_b32_e32 v1, v0
	v_mov_b32_e32 v2, v0
	v_mov_b32_e32 v3, v0
	v_mov_b32_e32 v4, v0
	v_mov_b32_e32 v5, v0
	v_mov_b32_e32 v6, v0
	v_mov_b32_e32 v7, v0
	v_mov_b32_e32 v8, v0
	v_mov_b32_e32 v9, v0
	v_mov_b32_e32 v10, v0
	v_mov_b32_e32 v11, v0
	v_mov_b32_e32 v16, v0
	v_mov_b32_e32 v17, v0
	v_mov_b32_e32 v18, v0
	v_mov_b32_e32 v19, v0
	v_mov_b32_e32 v24, v0
	v_mov_b32_e32 v25, v0
	v_mov_b32_e32 v26, v0
	v_mov_b32_e32 v27, v0
	v_mov_b32_e32 v32, v0
	v_mov_b32_e32 v33, v0
	v_mov_b32_e32 v34, v0
	v_mov_b32_e32 v35, v0
	v_mov_b32_e32 v40, v0
	v_mov_b32_e32 v41, v0
	v_mov_b32_e32 v42, v0
	v_mov_b32_e32 v43, v0
	v_mov_b32_e32 v48, v0
	v_mov_b32_e32 v49, v0
	v_mov_b32_e32 v50, v0
	v_mov_b32_e32 v51, v0
	v_mov_b32_e32 v12, v0
	v_mov_b32_e32 v13, v0
	v_mov_b32_e32 v14, v0
	v_mov_b32_e32 v15, v0
	v_mov_b32_e32 v20, v0
	v_mov_b32_e32 v21, v0
	v_mov_b32_e32 v22, v0
	v_mov_b32_e32 v23, v0
	v_mov_b32_e32 v28, v0
	v_mov_b32_e32 v29, v0
	v_mov_b32_e32 v30, v0
	v_mov_b32_e32 v31, v0
	v_mov_b32_e32 v36, v0
	v_mov_b32_e32 v37, v0
	v_mov_b32_e32 v38, v0
	v_mov_b32_e32 v39, v0
	v_mov_b32_e32 v44, v0
	v_mov_b32_e32 v45, v0
	v_mov_b32_e32 v46, v0
	v_mov_b32_e32 v47, v0
	v_mov_b32_e32 v52, v0
	v_mov_b32_e32 v53, v0
	v_mov_b32_e32 v54, v0
	v_mov_b32_e32 v55, v0
	v_mov_b32_e32 v56, v0
	v_mov_b32_e32 v57, v0
	v_mov_b32_e32 v58, v0
	v_mov_b32_e32 v59, v0
	v_mov_b32_e32 v60, v0
	v_mov_b32_e32 v61, v0
	v_mov_b32_e32 v62, v0
	v_mov_b32_e32 v63, v0
	v_mov_b32_e32 v64, v0
	v_mov_b32_e32 v65, v0
	v_mov_b32_e32 v66, v0
	v_mov_b32_e32 v67, v0
	v_mov_b32_e32 v68, v0
	v_mov_b32_e32 v69, v0
	v_mov_b32_e32 v70, v0
	v_mov_b32_e32 v71, v0
	v_mov_b32_e32 v72, v0
	v_mov_b32_e32 v73, v0
	v_mov_b32_e32 v74, v0
	v_mov_b32_e32 v75, v0
	v_mov_b32_e32 v80, v0
	v_mov_b32_e32 v81, v0
	v_mov_b32_e32 v82, v0
	v_mov_b32_e32 v83, v0
	v_mov_b32_e32 v88, v0
	v_mov_b32_e32 v89, v0
	v_mov_b32_e32 v90, v0
	v_mov_b32_e32 v91, v0
	v_mov_b32_e32 v96, v0
	v_mov_b32_e32 v97, v0
	v_mov_b32_e32 v98, v0
	v_mov_b32_e32 v99, v0
	v_mov_b32_e32 v104, v0
	v_mov_b32_e32 v105, v0
	v_mov_b32_e32 v106, v0
	v_mov_b32_e32 v107, v0
	v_mov_b32_e32 v112, v0
	v_mov_b32_e32 v113, v0
	v_mov_b32_e32 v114, v0
	v_mov_b32_e32 v115, v0
	v_mov_b32_e32 v76, v0
	v_mov_b32_e32 v77, v0
	v_mov_b32_e32 v78, v0
	v_mov_b32_e32 v79, v0
	v_mov_b32_e32 v84, v0
	v_mov_b32_e32 v85, v0
	v_mov_b32_e32 v86, v0
	v_mov_b32_e32 v87, v0
	v_mov_b32_e32 v92, v0
	v_mov_b32_e32 v93, v0
	v_mov_b32_e32 v94, v0
	v_mov_b32_e32 v95, v0
	v_mov_b32_e32 v100, v0
	v_mov_b32_e32 v101, v0
	v_mov_b32_e32 v102, v0
	v_mov_b32_e32 v103, v0
	v_mov_b32_e32 v108, v0
	v_mov_b32_e32 v109, v0
	v_mov_b32_e32 v110, v0
	v_mov_b32_e32 v111, v0
	v_mov_b32_e32 v116, v0
	v_mov_b32_e32 v117, v0
	v_mov_b32_e32 v118, v0
	v_mov_b32_e32 v119, v0
	v_mov_b32_e32 v120, v0
	v_mov_b32_e32 v121, v0
	v_mov_b32_e32 v122, v0
	v_mov_b32_e32 v123, v0
	v_mov_b32_e32 v124, v0
	v_mov_b32_e32 v125, v0
	v_mov_b32_e32 v126, v0
	v_mov_b32_e32 v127, v0
	s_cmp_eq_u32 s98, 0
	s_cbranch_scc1 .LBB0_1314
	ds_read_b128 v[144:147], v151
	ds_read_b128 v[154:157], v151 offset:1024
	ds_read_b128 v[158:161], v151 offset:2048
	ds_read_b128 v[162:165], v151 offset:3072
	ds_read_b128 v[166:169], v152
	ds_read_b128 v[172:175], v152 offset:1024
	ds_read_b128 v[176:179], v152 offset:2048
	ds_read_b128 v[180:183], v152 offset:3072
	s_add_u32 s34, s30, 0xfffe0080
	s_addc_u32 s35, s31, -1
	s_cmp_eq_u32 s56, 4
	s_cselect_b32 s37, s21, s35
	s_cselect_b32 s36, s52, s34
	s_cselect_b32 s35, s19, s55
	s_cselect_b32 s34, s53, s54
	v_lshl_add_u64 v[216:217], s[30:31], 0, v[136:137]
	s_add_i32 m0, s27, 0xc000
	ds_read_b128 v[184:187], v153
	ds_read_b128 v[188:191], v153 offset:1024
	ds_read_b128 v[192:195], v153 offset:2048
	ds_read_b128 v[196:199], v153 offset:3072
	ds_read_b128 v[200:203], v153 offset:4096
	ds_read_b128 v[204:207], v153 offset:5120
	ds_read_b128 v[208:211], v153 offset:6144
	ds_read_b128 v[212:215], v153 offset:7168
	global_load_lds_dwordx4 v[216:217], off
	v_lshl_add_u64 v[216:217], s[30:31], 0, v[138:139]
	s_add_i32 m0, s27, 0xe000
	s_nop 0
	global_load_lds_dwordx4 v[216:217], off
	s_waitcnt vmcnt(24)
	s_waitcnt lgkmcnt(0)
	s_barrier
; #define PG8_STAGE(bufoff, gbase, voff) do { _Pragma("unroll") for (int _i = 0; _i < 2; ++_i) \
;     __builtin_amdgcn_global_load_lds((const unsigned*)((const char*)(gbase) + (voff)[_i]), (LAS unsigned*)(lds + (bufoff) + ldsw + _i * 8192), 16, 0, 0); } while (0)
; #define PG8_LDA(dst, b, h) do { _Pragma("unroll") for (int m = 0; m < 4; ++m) _Pragma("unroll") for (int k = 0; k < 2; ++k) dst[m][k] = *(const LAS bf16x8*)(lds + PG8_SA(b, h) + aoff + m * 2048 + k * 1024); } while (0)
; #define PG8_MMA(ai, bj, At, Bt) do { __builtin_amdgcn_s_setprio(1); _Pragma("unroll") for (int m = 0; m < 4; ++m) _Pragma("unroll") for (int n = 0; n < 2; ++n) _Pragma("unroll") for (int k = 0; k < 2; ++k) \
;     acc[ai][bj][m][n] = __builtin_amdgcn_mfma_f32_16x16x32_bf16(Bt[n][k], At[m][k], acc[ai][bj][m][n], 0, 0, 0); __builtin_amdgcn_s_setprio(0); } while (0)
; #define PG8_WAIT_V(n) asm volatile("s_waitcnt vmcnt(" #n ")" ::: "memory")
; #define PG8_WAIT_L(n) asm volatile("s_waitcnt lgkmcnt(" #n ")" ::: "memory")
; #define PG8_BAR __builtin_amdgcn_s_barrier()
; #define PG8_SCHED __builtin_amdgcn_sched_barrier(0)
; template <class Epi, class Sched, bool ALIGN_EPI = true>
; __device__ __forceinline__ void gemm_phase(LAS unsigned char* lds, const Gemm g, const Sched& S, const Epi& E) {
;     ...
;       PG8_WAIT_V(8); PG8_WAIT_L(0); PG8_BAR; PG8_MMA(0, 0, At, B0); PG8_MMA(0, 1, At, B1); PG8_BAR; PG8_SCHED;
;       PG8_LDA(At, 0, 1); PG8_STAGE(PG8_SB(0, 0), b2, voffB); PG8_STAGE(PG8_SB(0, 1), b2 + hstepB, voffB); PG8_STAGE(PG8_SA(0, 0), a2, voffA);
;       PG8_WAIT_V(8); PG8_WAIT_L(0); PG8_BAR; PG8_MMA(1, 0, At, B0); PG8_MMA(1, 1, At, B1); PG8_BAR; PG8_SCHED;
	s_setprio 1
	s_waitcnt lgkmcnt(0)
	v_mfma_f32_16x16x32_bf16 v[124:127], v[144:147], v[184:187], v[124:127]
	v_mfma_f32_16x16x32_bf16 v[120:123], v[158:161], v[184:187], v[120:123]
	v_mfma_f32_16x16x32_bf16 v[116:119], v[144:147], v[192:195], v[116:119]
	v_mfma_f32_16x16x32_bf16 v[108:111], v[158:161], v[192:195], v[108:111]
	v_mfma_f32_16x16x32_bf16 v[100:103], v[144:147], v[200:203], v[100:103]
	v_mfma_f32_16x16x32_bf16 v[92:95], v[158:161], v[200:203], v[92:95]
	v_mfma_f32_16x16x32_bf16 v[84:87], v[144:147], v[208:211], v[84:87]
	v_mfma_f32_16x16x32_bf16 v[76:79], v[158:161], v[208:211], v[76:79]
	v_mfma_f32_16x16x32_bf16 v[124:127], v[154:157], v[188:191], v[124:127]
	v_mfma_f32_16x16x32_bf16 v[120:123], v[162:165], v[188:191], v[120:123]
	v_mfma_f32_16x16x32_bf16 v[116:119], v[154:157], v[196:199], v[116:119]
	v_mfma_f32_16x16x32_bf16 v[108:111], v[162:165], v[196:199], v[108:111]
	v_mfma_f32_16x16x32_bf16 v[100:103], v[154:157], v[204:207], v[100:103]
	v_mfma_f32_16x16x32_bf16 v[92:95], v[162:165], v[204:207], v[92:95]
	v_mfma_f32_16x16x32_bf16 v[84:87], v[154:157], v[212:215], v[84:87]
	v_mfma_f32_16x16x32_bf16 v[76:79], v[162:165], v[212:215], v[76:79]
	s_setprio 0
	s_setprio 1
	v_mfma_f32_16x16x32_bf16 v[112:115], v[166:169], v[184:187], v[112:115]
	v_mfma_f32_16x16x32_bf16 v[104:107], v[176:179], v[184:187], v[104:107]
	v_mfma_f32_16x16x32_bf16 v[96:99], v[166:169], v[192:195], v[96:99]
	v_mfma_f32_16x16x32_bf16 v[88:91], v[176:179], v[192:195], v[88:91]
	v_mfma_f32_16x16x32_bf16 v[80:83], v[166:169], v[200:203], v[80:83]
	v_mfma_f32_16x16x32_bf16 v[72:75], v[176:179], v[200:203], v[72:75]
	v_mfma_f32_16x16x32_bf16 v[68:71], v[166:169], v[208:211], v[68:71]
	v_mfma_f32_16x16x32_bf16 v[64:67], v[176:179], v[208:211], v[64:67]
	v_mfma_f32_16x16x32_bf16 v[112:115], v[172:175], v[188:191], v[112:115]
	v_mfma_f32_16x16x32_bf16 v[104:107], v[180:183], v[188:191], v[104:107]
	v_mfma_f32_16x16x32_bf16 v[96:99], v[172:175], v[196:199], v[96:99]
	v_mfma_f32_16x16x32_bf16 v[88:91], v[180:183], v[196:199], v[88:91]
	v_mfma_f32_16x16x32_bf16 v[80:83], v[172:175], v[204:207], v[80:83]
	v_mfma_f32_16x16x32_bf16 v[72:75], v[180:183], v[204:207], v[72:75]
	v_mfma_f32_16x16x32_bf16 v[68:71], v[172:175], v[212:215], v[68:71]
	v_mfma_f32_16x16x32_bf16 v[64:67], v[180:183], v[212:215], v[64:67]
	s_setprio 0
	s_barrier
	s_add_i32 s57, s48, s33
	v_lshl_add_u64 v[216:217], s[34:35], 0, v[132:133]
	s_mov_b32 m0, s57
	ds_read_b128 v[184:187], v153 offset:16384
	ds_read_b128 v[188:191], v153 offset:17408
	ds_read_b128 v[192:195], v153 offset:18432
	ds_read_b128 v[196:199], v153 offset:19456
	ds_read_b128 v[200:203], v153 offset:20480
	ds_read_b128 v[204:207], v153 offset:21504
	ds_read_b128 v[208:211], v153 offset:22528
	ds_read_b128 v[212:215], v153 offset:23552
	global_load_lds_dwordx4 v[216:217], off
	s_add_i32 m0, s57, 0x2000
	s_add_u32 s58, s34, 0x20000
	v_lshl_add_u64 v[218:219], s[34:35], 0, v[128:129]
	s_addc_u32 s59, s35, 0
	s_add_i32 s57, s49, s33
	global_load_lds_dwordx4 v[218:219], off
	v_lshl_add_u64 v[220:221], s[58:59], 0, v[132:133]
	s_mov_b32 m0, s57
	v_lshl_add_u64 v[222:223], s[36:37], 0, v[130:131]
	global_load_lds_dwordx4 v[220:221], off
	v_lshl_add_u64 v[220:221], s[58:59], 0, v[128:129]
	s_add_i32 m0, s57, 0x2000
	s_nop 0
	global_load_lds_dwordx4 v[220:221], off
	v_lshl_add_u64 v[220:221], s[36:37], 0, v[134:135]
	s_mov_b32 m0, s27
	s_nop 0
	global_load_lds_dwordx4 v[220:221], off
	s_mov_b32 m0, s40
	s_nop 0
	global_load_lds_dwordx4 v[222:223], off
	s_waitcnt vmcnt(24)
	s_waitcnt lgkmcnt(0)
	s_barrier
	s_setprio 1
	s_waitcnt lgkmcnt(0)
	v_mfma_f32_16x16x32_bf16 v[60:63], v[144:147], v[184:187], v[60:63]
	v_mfma_f32_16x16x32_bf16 v[56:59], v[158:161], v[184:187], v[56:59]
	v_mfma_f32_16x16x32_bf16 v[52:55], v[144:147], v[192:195], v[52:55]
	v_mfma_f32_16x16x32_bf16 v[44:47], v[158:161], v[192:195], v[44:47]
	v_mfma_f32_16x16x32_bf16 v[36:39], v[144:147], v[200:203], v[36:39]
	v_mfma_f32_16x16x32_bf16 v[28:31], v[158:161], v[200:203], v[28:31]
	v_mfma_f32_16x16x32_bf16 v[20:23], v[144:147], v[208:211], v[20:23]
	v_mfma_f32_16x16x32_bf16 v[12:15], v[158:161], v[208:211], v[12:15]
	v_mfma_f32_16x16x32_bf16 v[60:63], v[154:157], v[188:191], v[60:63]
	v_mfma_f32_16x16x32_bf16 v[56:59], v[162:165], v[188:191], v[56:59]
	v_mfma_f32_16x16x32_bf16 v[52:55], v[154:157], v[196:199], v[52:55]
	v_mfma_f32_16x16x32_bf16 v[44:47], v[162:165], v[196:199], v[44:47]
	v_mfma_f32_16x16x32_bf16 v[36:39], v[154:157], v[204:207], v[36:39]
	v_mfma_f32_16x16x32_bf16 v[28:31], v[162:165], v[204:207], v[28:31]
	v_mfma_f32_16x16x32_bf16 v[20:23], v[154:157], v[212:215], v[20:23]
	v_mfma_f32_16x16x32_bf16 v[12:15], v[162:165], v[212:215], v[12:15]
	s_setprio 0
	s_setprio 1
	v_mfma_f32_16x16x32_bf16 v[48:51], v[166:169], v[184:187], v[48:51]
	v_mfma_f32_16x16x32_bf16 v[40:43], v[176:179], v[184:187], v[40:43]
	v_mfma_f32_16x16x32_bf16 v[32:35], v[166:169], v[192:195], v[32:35]
	v_mfma_f32_16x16x32_bf16 v[24:27], v[176:179], v[192:195], v[24:27]
	v_mfma_f32_16x16x32_bf16 v[16:19], v[166:169], v[200:203], v[16:19]
	v_mfma_f32_16x16x32_bf16 v[8:11], v[176:179], v[200:203], v[8:11]
	v_mfma_f32_16x16x32_bf16 v[4:7], v[166:169], v[208:211], v[4:7]
	v_mfma_f32_16x16x32_bf16 v[0:3], v[176:179], v[208:211], v[0:3]
	v_mfma_f32_16x16x32_bf16 v[48:51], v[172:175], v[188:191], v[48:51]
	v_mfma_f32_16x16x32_bf16 v[40:43], v[180:183], v[188:191], v[40:43]
	v_mfma_f32_16x16x32_bf16 v[32:35], v[172:175], v[196:199], v[32:35]
	v_mfma_f32_16x16x32_bf16 v[24:27], v[180:183], v[196:199], v[24:27]
	v_mfma_f32_16x16x32_bf16 v[16:19], v[172:175], v[204:207], v[16:19]
	v_mfma_f32_16x16x32_bf16 v[8:11], v[180:183], v[204:207], v[8:11]
	v_mfma_f32_16x16x32_bf16 v[4:7], v[172:175], v[212:215], v[4:7]
	v_mfma_f32_16x16x32_bf16 v[0:3], v[180:183], v[212:215], v[0:3]
	s_setprio 0
	s_barrier
	s_branch .Lpeel_mid_1314

; #define PG8_STAGE(bufoff, gbase, voff) do { _Pragma("unroll") for (int _i = 0; _i < 2; ++_i) \
;     __builtin_amdgcn_global_load_lds((const unsigned*)((const char*)(gbase) + (voff)[_i]), (LAS unsigned*)(lds + (bufoff) + ldsw + _i * 8192), 16, 0, 0); } while (0)
; #define PG8_LDA(dst, b, h) do { _Pragma("unroll") for (int m = 0; m < 4; ++m) _Pragma("unroll") for (int k = 0; k < 2; ++k) dst[m][k] = *(const LAS bf16x8*)(lds + PG8_SA(b, h) + aoff + m * 2048 + k * 1024); } while (0)
; #define PG8_LDB(dst, b, h) do { _Pragma("unroll") for (int n = 0; n < 2; ++n) _Pragma("unroll") for (int k = 0; k < 2; ++k) dst[n][k] = *(const LAS bf16x8*)(lds + PG8_SB(b, h) + boff + n * 2048 + k * 1024); } while (0)
; #define PG8_MMA(ai, bj, At, Bt) do { __builtin_amdgcn_s_setprio(1); _Pragma("unroll") for (int m = 0; m < 4; ++m) _Pragma("unroll") for (int n = 0; n < 2; ++n) _Pragma("unroll") for (int k = 0; k < 2; ++k) \
;     acc[ai][bj][m][n] = __builtin_amdgcn_mfma_f32_16x16x32_bf16(Bt[n][k], At[m][k], acc[ai][bj][m][n], 0, 0, 0); __builtin_amdgcn_s_setprio(0); } while (0)
; #define PG8_WAIT_V(n) asm volatile("s_waitcnt vmcnt(" #n ")" ::: "memory")
; #define PG8_WAIT_L(n) asm volatile("s_waitcnt lgkmcnt(" #n ")" ::: "memory")
; #define PG8_BAR __builtin_amdgcn_s_barrier()
; #define PG8_SCHED __builtin_amdgcn_sched_barrier(0)
; template <class Epi, class Sched, bool ALIGN_EPI = true>
; __device__ __forceinline__ void gemm_phase(LAS unsigned char* lds, const Gemm g, const Sched& S, const Epi& E) {
;     ...
;       PG8_LDB(B0, 1, 0); PG8_LDB(B1, 1, 1); PG8_SCHED; PG8_LDA(At, 1, 0); PG8_STAGE(PG8_SA(0, 1), a2 + hstepA, voffA);
;       PG8_WAIT_V(8); PG8_WAIT_L(0); PG8_BAR; PG8_MMA(0, 0, At, B0); PG8_MMA(0, 1, At, B1); PG8_BAR; PG8_SCHED;
.Lpeel_mid_1314:
	s_add_i32 s57, 0, 0x18000
	s_add_i32 s58, 0, 0x1c000
	v_add_u32_e32 v162, s57, v149
	v_add_u32_e32 v180, s58, v149
	ds_read_b128 v[144:147], v162
	ds_read_b128 v[154:157], v162 offset:1024
	ds_read_b128 v[158:161], v162 offset:2048
	ds_read_b128 v[162:165], v162 offset:3072
	ds_read_b128 v[166:169], v180
	ds_read_b128 v[172:175], v180 offset:1024
	ds_read_b128 v[176:179], v180 offset:2048
	ds_read_b128 v[180:183], v180 offset:3072
	s_add_u32 s36, s36, 0x20000
	s_addc_u32 s37, s37, 0
	s_mov_b32 m0, s41
	v_lshl_add_u64 v[224:225], s[36:37], 0, v[134:135]
	ds_read_b128 v[184:187], v153 offset:32768
	ds_read_b128 v[188:191], v153 offset:33792
	ds_read_b128 v[192:195], v153 offset:34816
	ds_read_b128 v[196:199], v153 offset:35840
	ds_read_b128 v[200:203], v153 offset:36864
	ds_read_b128 v[204:207], v153 offset:37888
	ds_read_b128 v[208:211], v153 offset:38912
	ds_read_b128 v[212:215], v153 offset:39936
	global_load_lds_dwordx4 v[224:225], off
	v_lshl_add_u64 v[224:225], s[36:37], 0, v[130:131]
	s_mov_b32 m0, s42
	s_nop 0
	global_load_lds_dwordx4 v[224:225], off
	s_waitcnt vmcnt(8)
	s_waitcnt lgkmcnt(0)
	s_barrier
	s_setprio 1
	s_waitcnt lgkmcnt(0)
	v_mfma_f32_16x16x32_bf16 v[124:127], v[144:147], v[184:187], v[124:127]
	v_mfma_f32_16x16x32_bf16 v[120:123], v[158:161], v[184:187], v[120:123]
	v_mfma_f32_16x16x32_bf16 v[116:119], v[144:147], v[192:195], v[116:119]
	v_mfma_f32_16x16x32_bf16 v[108:111], v[158:161], v[192:195], v[108:111]
	v_mfma_f32_16x16x32_bf16 v[100:103], v[144:147], v[200:203], v[100:103]
	v_mfma_f32_16x16x32_bf16 v[92:95], v[158:161], v[200:203], v[92:95]
	v_mfma_f32_16x16x32_bf16 v[84:87], v[144:147], v[208:211], v[84:87]
	v_mfma_f32_16x16x32_bf16 v[76:79], v[158:161], v[208:211], v[76:79]
	v_mfma_f32_16x16x32_bf16 v[124:127], v[154:157], v[188:191], v[124:127]
	v_mfma_f32_16x16x32_bf16 v[120:123], v[162:165], v[188:191], v[120:123]
	v_mfma_f32_16x16x32_bf16 v[116:119], v[154:157], v[196:199], v[116:119]
	v_mfma_f32_16x16x32_bf16 v[108:111], v[162:165], v[196:199], v[108:111]
	v_mfma_f32_16x16x32_bf16 v[100:103], v[154:157], v[204:207], v[100:103]
	v_mfma_f32_16x16x32_bf16 v[92:95], v[162:165], v[204:207], v[92:95]
	v_mfma_f32_16x16x32_bf16 v[84:87], v[154:157], v[212:215], v[84:87]
	v_mfma_f32_16x16x32_bf16 v[76:79], v[162:165], v[212:215], v[76:79]
	s_setprio 0
	s_setprio 1
	v_mfma_f32_16x16x32_bf16 v[112:115], v[166:169], v[184:187], v[112:115]
	v_mfma_f32_16x16x32_bf16 v[104:107], v[176:179], v[184:187], v[104:107]
	v_mfma_f32_16x16x32_bf16 v[96:99], v[166:169], v[192:195], v[96:99]
	v_mfma_f32_16x16x32_bf16 v[88:91], v[176:179], v[192:195], v[88:91]
	v_mfma_f32_16x16x32_bf16 v[80:83], v[166:169], v[200:203], v[80:83]
	v_mfma_f32_16x16x32_bf16 v[72:75], v[176:179], v[200:203], v[72:75]
	v_mfma_f32_16x16x32_bf16 v[68:71], v[166:169], v[208:211], v[68:71]
	v_mfma_f32_16x16x32_bf16 v[64:67], v[176:179], v[208:211], v[64:67]
	v_mfma_f32_16x16x32_bf16 v[112:115], v[172:175], v[188:191], v[112:115]
	v_mfma_f32_16x16x32_bf16 v[104:107], v[180:183], v[188:191], v[104:107]
	v_mfma_f32_16x16x32_bf16 v[96:99], v[172:175], v[196:199], v[96:99]
	v_mfma_f32_16x16x32_bf16 v[88:91], v[180:183], v[196:199], v[88:91]
	v_mfma_f32_16x16x32_bf16 v[80:83], v[172:175], v[204:207], v[80:83]
	v_mfma_f32_16x16x32_bf16 v[72:75], v[180:183], v[204:207], v[72:75]
	v_mfma_f32_16x16x32_bf16 v[68:71], v[172:175], v[212:215], v[68:71]
	v_mfma_f32_16x16x32_bf16 v[64:67], v[180:183], v[212:215], v[64:67]
	s_setprio 0
	s_barrier
; #define PG8_STAGE(bufoff, gbase, voff) do { _Pragma("unroll") for (int _i = 0; _i < 2; ++_i) \
;     __builtin_amdgcn_global_load_lds((const unsigned*)((const char*)(gbase) + (voff)[_i]), (LAS unsigned*)(lds + (bufoff) + ldsw + _i * 8192), 16, 0, 0); } while (0)
; #define PG8_LDA(dst, b, h) do { _Pragma("unroll") for (int m = 0; m < 4; ++m) _Pragma("unroll") for (int k = 0; k < 2; ++k) dst[m][k] = *(const LAS bf16x8*)(lds + PG8_SA(b, h) + aoff + m * 2048 + k * 1024); } while (0)
; #define PG8_MMA(ai, bj, At, Bt) do { __builtin_amdgcn_s_setprio(1); _Pragma("unroll") for (int m = 0; m < 4; ++m) _Pragma("unroll") for (int n = 0; n < 2; ++n) _Pragma("unroll") for (int k = 0; k < 2; ++k) \
;     acc[ai][bj][m][n] = __builtin_amdgcn_mfma_f32_16x16x32_bf16(Bt[n][k], At[m][k], acc[ai][bj][m][n], 0, 0, 0); __builtin_amdgcn_s_setprio(0); } while (0)
; #define PG8_WAIT_V(n) asm volatile("s_waitcnt vmcnt(" #n ")" ::: "memory")
; #define PG8_WAIT_L(n) asm volatile("s_waitcnt lgkmcnt(" #n ")" ::: "memory")
; #define PG8_BAR __builtin_amdgcn_s_barrier()
; #define PG8_SCHED __builtin_amdgcn_sched_barrier(0)
; template <class Epi, class Sched, bool ALIGN_EPI = true>
; __device__ __forceinline__ void gemm_phase(LAS unsigned char* lds, const Gemm g, const Sched& S, const Epi& E) {
;     ...
;       PG8_LDA(At, 1, 1); PG8_STAGE(PG8_SB(1, 0), b3, voffB); PG8_STAGE(PG8_SB(1, 1), b3 + hstepB, voffB); PG8_STAGE(PG8_SA(1, 0), a3, voffA);
;       PG8_WAIT_V(8); PG8_WAIT_L(0); PG8_BAR; PG8_MMA(1, 0, At, B0); PG8_MMA(1, 1, At, B1); PG8_BAR; PG8_SCHED;
;     }
;     if constexpr (ALIGN_EPI) { if (wr == 0) PG8_BAR; }
	s_add_i32 s36, s57, s33
	v_lshl_add_u64 v[216:217], v[216:217], 0, s[12:13]
	s_mov_b32 m0, s36
	ds_read_b128 v[184:187], v153 offset:49152
	ds_read_b128 v[188:191], v153 offset:50176
	ds_read_b128 v[192:195], v153 offset:51200
	ds_read_b128 v[196:199], v153 offset:52224
	ds_read_b128 v[200:203], v153 offset:53248
	ds_read_b128 v[204:207], v153 offset:54272
	ds_read_b128 v[208:211], v153 offset:55296
	ds_read_b128 v[212:215], v153 offset:56320
	global_load_lds_dwordx4 v[216:217], off
	s_add_i32 m0, s36, 0x2000
	s_add_u32 s34, s34, 0x20080
	v_lshl_add_u64 v[216:217], v[218:219], 0, s[12:13]
	s_addc_u32 s35, s35, 0
	s_add_i32 s36, s58, s33
	global_load_lds_dwordx4 v[216:217], off
	v_lshl_add_u64 v[216:217], s[34:35], 0, v[132:133]
	s_mov_b32 m0, s36
	s_nop 0
	global_load_lds_dwordx4 v[216:217], off
	v_lshl_add_u64 v[216:217], s[34:35], 0, v[128:129]
	s_add_i32 m0, s36, 0x2000
	s_nop 0
	global_load_lds_dwordx4 v[216:217], off
	v_lshl_add_u64 v[216:217], v[220:221], 0, s[12:13]
	s_mov_b32 m0, s44
	s_nop 0
	global_load_lds_dwordx4 v[216:217], off
	v_lshl_add_u64 v[216:217], v[222:223], 0, s[12:13]
	s_mov_b32 m0, s45
	s_nop 0
	global_load_lds_dwordx4 v[216:217], off
	s_waitcnt vmcnt(8)
	s_waitcnt lgkmcnt(0)
	s_barrier
	s_setprio 1
	s_waitcnt lgkmcnt(0)
	v_mfma_f32_16x16x32_bf16 v[60:63], v[144:147], v[184:187], v[60:63]
	v_mfma_f32_16x16x32_bf16 v[56:59], v[158:161], v[184:187], v[56:59]
	v_mfma_f32_16x16x32_bf16 v[52:55], v[144:147], v[192:195], v[52:55]
	v_mfma_f32_16x16x32_bf16 v[44:47], v[158:161], v[192:195], v[44:47]
	v_mfma_f32_16x16x32_bf16 v[36:39], v[144:147], v[200:203], v[36:39]
	v_mfma_f32_16x16x32_bf16 v[28:31], v[158:161], v[200:203], v[28:31]
	v_mfma_f32_16x16x32_bf16 v[20:23], v[144:147], v[208:211], v[20:23]
	v_mfma_f32_16x16x32_bf16 v[12:15], v[158:161], v[208:211], v[12:15]
	v_mfma_f32_16x16x32_bf16 v[60:63], v[154:157], v[188:191], v[60:63]
	v_mfma_f32_16x16x32_bf16 v[56:59], v[162:165], v[188:191], v[56:59]
	v_mfma_f32_16x16x32_bf16 v[52:55], v[154:157], v[196:199], v[52:55]
	v_mfma_f32_16x16x32_bf16 v[44:47], v[162:165], v[196:199], v[44:47]
	v_mfma_f32_16x16x32_bf16 v[36:39], v[154:157], v[204:207], v[36:39]
	v_mfma_f32_16x16x32_bf16 v[28:31], v[162:165], v[204:207], v[28:31]
	v_mfma_f32_16x16x32_bf16 v[20:23], v[154:157], v[212:215], v[20:23]
	v_mfma_f32_16x16x32_bf16 v[12:15], v[162:165], v[212:215], v[12:15]
	s_setprio 0
	s_setprio 1
	v_mfma_f32_16x16x32_bf16 v[48:51], v[166:169], v[184:187], v[48:51]
	v_mfma_f32_16x16x32_bf16 v[40:43], v[176:179], v[184:187], v[40:43]
	v_mfma_f32_16x16x32_bf16 v[32:35], v[166:169], v[192:195], v[32:35]
	v_mfma_f32_16x16x32_bf16 v[24:27], v[176:179], v[192:195], v[24:27]
	v_mfma_f32_16x16x32_bf16 v[16:19], v[166:169], v[200:203], v[16:19]
	v_mfma_f32_16x16x32_bf16 v[8:11], v[176:179], v[200:203], v[8:11]
	v_mfma_f32_16x16x32_bf16 v[4:7], v[166:169], v[208:211], v[4:7]
	v_mfma_f32_16x16x32_bf16 v[0:3], v[176:179], v[208:211], v[0:3]
	v_mfma_f32_16x16x32_bf16 v[48:51], v[172:175], v[188:191], v[48:51]
	v_mfma_f32_16x16x32_bf16 v[40:43], v[180:183], v[188:191], v[40:43]
	v_mfma_f32_16x16x32_bf16 v[32:35], v[172:175], v[196:199], v[32:35]
	v_mfma_f32_16x16x32_bf16 v[24:27], v[180:183], v[196:199], v[24:27]
	v_mfma_f32_16x16x32_bf16 v[16:19], v[172:175], v[204:207], v[16:19]
	v_mfma_f32_16x16x32_bf16 v[8:11], v[180:183], v[204:207], v[8:11]
	v_mfma_f32_16x16x32_bf16 v[4:7], v[172:175], v[212:215], v[4:7]
	v_mfma_f32_16x16x32_bf16 v[0:3], v[180:183], v[212:215], v[0:3]
	s_setprio 0
	s_barrier
	s_add_i32 s56, s56, 2
	s_add_u32 s30, s30, 0x100
	s_addc_u32 s31, s31, 0
	s_add_u32 s54, s54, 0x100
	s_addc_u32 s55, s55, 0
	s_cmp_gt_u32 s56, 5
	s_cbranch_scc0 .LBB0_1314
	s_mov_b32 s98, 1
	s_and_b64 vcc, exec, s[16:17]
	s_cbranch_vccz .LBB0_1317
	s_barrier

; #define PG8_STAGE(bufoff, gbase, voff) do { _Pragma("unroll") for (int _i = 0; _i < 2; ++_i) \
;     __builtin_amdgcn_global_load_lds((const unsigned*)((const char*)(gbase) + (voff)[_i]), (LAS unsigned*)(lds + (bufoff) + ldsw + _i * 8192), 16, 0, 0); } while (0)
; #define PG8_WAIT_V(n) asm volatile("s_waitcnt vmcnt(" #n ")" ::: "memory")
; #define PG8_BAR __builtin_amdgcn_s_barrier()
; template <class Epi, class Sched, bool ALIGN_EPI = true>
; __device__ __forceinline__ void gemm_phase(LAS unsigned char* lds, const Gemm g, const Sched& S, const Epi& E) {
;     ...
;   for (int i = 0; i < 2; ++i) { int R, C; stage_rc(tid * 16 + i * 8192, R, C); const int Rb = Epi::PERM ? ((R & ~31) + perm32(R & 31)) : R;
;     voffA[i] = (unsigned)(R * g.lda + C) * 2u; voffB[i] = (unsigned)(Rb * g.ldb + C) * 2u; }
;   const size_t koffL = (size_t)(nt - 1) * (BK * 2);
;   const size_t hstepA = (size_t)HALF * g.lda * 2, hstepB = (size_t)HALF * g.ldb * 2;
;   const size_t tstepA = 2 * hstepA, tstepB = 2 * hstepB;
;   const unsigned ldsw = (unsigned)wid * 1024u;
;   const int aoff = lds_byte(wr * 64 + fr, fq * 8), boff = lds_byte(wc * 32 + fr, fq * 8);
;     ...
;   Unit cur, nxt; int ui = 0;
;   if (!S.next(0, cur)) return;
;   f32x4 acc[2][2][4][2];
; #pragma unroll
;   for (int a = 0; a < 2; ++a)
; #pragma unroll
;     for (int b = 0; b < 2; ++b)
; #pragma unroll
;       for (int m = 0; m < 4; ++m)
; #pragma unroll
;         for (int n = 0; n < 2; ++n) acc[a][b][m][n] = (f32x4){0.f, 0.f, 0.f, 0.f};
;   bf16x8 At[4][2], B0[2][2], B1[2][2];
;   ptrdiff_t kstep = cur.kr ? -(ptrdiff_t)(BK * 2) : (ptrdiff_t)(BK * 2);
;   const char* cA = (const char*)g.A + (size_t)cur.pm * tstepA + cur.kb + (cur.kr ? koffL : 0); const char* cB = (const char*)g.Bt + (size_t)cur.pn * tstepB + cur.kb + (cur.kr ? koffL : 0);
;   PG8_STAGE(PG8_SB(0, 0), cB, voffB); PG8_STAGE(PG8_SB(0, 1), cB + hstepB, voffB); PG8_STAGE(PG8_SA(0, 0), cA, voffA); PG8_STAGE(PG8_SA(0, 1), cA + hstepA, voffA);
;   if (wr == 1) PG8_BAR;
;   PG8_WAIT_V(2); PG8_BAR;
;   PG8_STAGE(PG8_SB(1, 0), cB + kstep, voffB); PG8_STAGE(PG8_SA(1, 0), cA + kstep, voffA); PG8_STAGE(PG8_SB(1, 1), cB + hstepB + kstep, voffB);
;   PG8_WAIT_V(6); PG8_BAR;
.LBB0_1324:
	s_add_u32 s10, s84, 0x23d5a000
	s_addc_u32 s11, s85, 0
	s_lshl_b32 s12, s12, 5
	s_and_b32 s18, s12, 0x60
	s_mov_b64 s[12:13], 0x80
	s_add_i32 m0, s37, 0x18000
	v_lshl_add_u64 v[6:7], v[6:7], 0, s[12:13]
	s_lshl_b32 s15, s14, 13
	s_lshl_b32 s19, s18, 7
	s_waitcnt vmcnt(2)
	s_barrier
	global_load_lds_dwordx4 v[6:7], off
	v_lshl_add_u64 v[4:5], v[4:5], 0, s[12:13]
	s_add_i32 m0, s37, 0x1a000
	s_add_i32 s50, s37, 0x8000
	s_add_i32 s51, s37, 0xa000
	global_load_lds_dwordx4 v[4:5], off
	v_lshl_add_u64 v[0:1], v[0:1], 0, s[12:13]
	s_mov_b32 m0, s50
	s_add_u32 s16, s40, 0x20080
	global_load_lds_dwordx4 v[0:1], off
	v_lshl_add_u64 v[0:1], v[2:3], 0, s[12:13]
	s_mov_b32 m0, s51
	s_addc_u32 s17, s41, 0
	global_load_lds_dwordx4 v[0:1], off
	s_add_i32 m0, s37, 0x1c000
	v_lshl_add_u64 v[0:1], s[16:17], 0, v[132:133]
	global_load_lds_dwordx4 v[0:1], off
	v_lshl_add_u64 v[0:1], s[16:17], 0, v[128:129]
	s_add_i32 m0, s37, 0x1e000
	s_cmpk_lt_u32 s7, 0x100
	global_load_lds_dwordx4 v[0:1], off
	v_lshrrev_b32_e32 v1, 1, v9
	v_and_b32_e32 v1, 24, v1
	v_and_b32_e32 v0, 15, v9
	v_lshlrev_b32_e32 v2, 1, v1
	v_lshl_or_b32 v146, s14, 6, v0
	v_lshl_or_b32 v0, v0, 6, v2
	v_lshlrev_b32_e32 v2, 2, v9
	v_and_b32_e32 v2, 32, v2
	v_bitop3_b32 v3, v0, s15, v2 bitop3:0xde
	v_bitop3_b32 v147, v0, s19, v2 bitop3:0xde
	v_lshlrev_b32_e32 v0, 13, v13
	v_and_b32_e32 v0, 0xffffc000, v0
	v_or_b32_e32 v148, s18, v1
	v_lshl_add_u32 v0, v12, 10, v0
	v_and_b32_e32 v1, 1, v13
	v_lshl_or_b32 v0, v1, 6, v0
	v_lshl_add_u32 v136, v14, 1, v0
	v_lshlrev_b32_e32 v0, 13, v8
	v_and_b32_e32 v0, 0xffffc000, v0
	s_waitcnt vmcnt(6)
	v_lshl_add_u32 v0, v10, 10, v0
	v_and_b32_e32 v1, 1, v8
	s_cselect_b64 s[14:15], -1, 0
	v_lshl_or_b32 v0, v1, 6, v0
	s_add_i32 s54, 0, 0x10000
	s_add_i32 s55, 0, 0x14000
	s_sext_i32_i8 s60, s6
	s_ashr_i32 s52, s86, 31
	s_mov_b32 s53, s86
	v_mov_b32_e32 v137, v133
	v_lshl_add_u32 v138, v11, 1, v0
	v_mov_b32_e32 v139, v133
	v_mov_b64_e32 v[140:141], 0x480
	v_mov_b64_e32 v[142:143], 0x47f
	v_add_u32_e32 v149, s54, v147
	v_add_u32_e32 v150, s55, v147
	v_add_u32_e32 v151, 0, v3
	s_mov_b64 s[16:17], 0x100000
	s_mov_b32 s56, 0x100000
	s_mov_b64 s[18:19], 0x120000
	s_mov_b32 s57, 0x120000
	s_mov_b64 s[20:21], 0x140000
	s_mov_b32 s58, 0x140000
	s_mov_b64 s[22:23], 0x160000
	s_mov_b32 s59, 0x160000
	s_barrier
	s_mov_b32 s98, 0
	s_branch .LBB0_1327

; #define PG8_STAGE(bufoff, gbase, voff) do { _Pragma("unroll") for (int _i = 0; _i < 2; ++_i) \
;     __builtin_amdgcn_global_load_lds((const unsigned*)((const char*)(gbase) + (voff)[_i]), (LAS unsigned*)(lds + (bufoff) + ldsw + _i * 8192), 16, 0, 0); } while (0)
; #define PG8_LDA(dst, b, h) do { _Pragma("unroll") for (int m = 0; m < 4; ++m) _Pragma("unroll") for (int k = 0; k < 2; ++k) dst[m][k] = *(const LAS bf16x8*)(lds + PG8_SA(b, h) + aoff + m * 2048 + k * 1024); } while (0)
; #define PG8_LDB(dst, b, h) do { _Pragma("unroll") for (int n = 0; n < 2; ++n) _Pragma("unroll") for (int k = 0; k < 2; ++k) dst[n][k] = *(const LAS bf16x8*)(lds + PG8_SB(b, h) + boff + n * 2048 + k * 1024); } while (0)
; #define PG8_MMA(ai, bj, At, Bt) do { __builtin_amdgcn_s_setprio(1); _Pragma("unroll") for (int m = 0; m < 4; ++m) _Pragma("unroll") for (int n = 0; n < 2; ++n) _Pragma("unroll") for (int k = 0; k < 2; ++k) \
;     acc[ai][bj][m][n] = __builtin_amdgcn_mfma_f32_16x16x32_bf16(Bt[n][k], At[m][k], acc[ai][bj][m][n], 0, 0, 0); __builtin_amdgcn_s_setprio(0); } while (0)
; #define PG8_WAIT_V(n) asm volatile("s_waitcnt vmcnt(" #n ")" ::: "memory")
; #define PG8_WAIT_L(n) asm volatile("s_waitcnt lgkmcnt(" #n ")" ::: "memory")
; #define PG8_BAR __builtin_amdgcn_s_barrier()
; template <class Epi, class Sched, bool ALIGN_EPI = true>
; __device__ __forceinline__ void gemm_phase(LAS unsigned char* lds, const Gemm g, const Sched& S, const Epi& E) {
;     ...
;     for (int t = 0; t < nt; t += 2) {
;       const bool last = (t == nt - 2);
;       const char* a1 = cA + (ptrdiff_t)(t + 1) * kstep;
;       const char* a2 = last ? nA : cA + (ptrdiff_t)(t + 2) * kstep; const char* b2 = last ? nB : cB + (ptrdiff_t)(t + 2) * kstep;
;       const char* a3 = a2 + (last ? kstepN : kstep); const char* b3 = b2 + (last ? kstepN : kstep);
;       PG8_LDB(B0, 0, 0); PG8_LDB(B1, 0, 1); PG8_SCHED; PG8_LDA(At, 0, 0); PG8_STAGE(PG8_SA(1, 1), a1 + hstepA, voffA);
;       PG8_WAIT_V(8); PG8_WAIT_L(0); PG8_BAR; PG8_MMA(0, 0, At, B0); PG8_MMA(0, 1, At, B1); PG8_BAR; PG8_SCHED;
;     ...
; #pragma unroll
;     for (int a = 0; a < 2; ++a)
; #pragma unroll
;       for (int b = 0; b < 2; ++b)
; #pragma unroll
;         for (int m = 0; m < 4; ++m)
; #pragma unroll
;           for (int n = 0; n < 2; ++n) acc[a][b][m][n] = (f32x4){0.f, 0.f, 0.f, 0.f};
;     cur = nxt; cA = nA; cB = nB; kstep = kstepN; ++ui;
.LBB0_1329:
	s_ashr_i32 s27, s26, 31
	s_lshl_b64 s[30:31], s[26:27], 18
	s_add_u32 s30, s0, s30
	s_addc_u32 s31, s1, s31
	s_and_b64 s[34:35], s[6:7], exec
	s_cselect_b32 s27, s31, s39
	s_cselect_b32 s61, s30, s38
	s_ashr_i32 s25, s24, 31
	s_lshl_b64 s[34:35], s[24:25], 18
	s_add_u32 s34, s2, s34
	s_addc_u32 s35, s3, s35
	s_and_b64 s[42:43], s[6:7], exec
	s_cselect_b32 s25, s35, s41
	s_cselect_b32 s62, s34, s40
	s_add_u32 s38, s38, 0x20080
	s_addc_u32 s39, s39, 0
	s_add_u32 s63, s40, 0x100
	v_mov_b32_e32 v0, 0
	s_addc_u32 s64, s41, 0
	s_mov_b32 s65, -2
	v_mov_b32_e32 v1, v0
	v_mov_b32_e32 v2, v0
	v_mov_b32_e32 v3, v0
	v_mov_b32_e32 v4, v0
	v_mov_b32_e32 v5, v0
	v_mov_b32_e32 v6, v0
	v_mov_b32_e32 v7, v0
	v_mov_b32_e32 v8, v0
	v_mov_b32_e32 v9, v0
	v_mov_b32_e32 v10, v0
	v_mov_b32_e32 v11, v0
	v_mov_b32_e32 v16, v0
	v_mov_b32_e32 v17, v0
	v_mov_b32_e32 v18, v0
	v_mov_b32_e32 v19, v0
	v_mov_b32_e32 v24, v0
	v_mov_b32_e32 v25, v0
	v_mov_b32_e32 v26, v0
	v_mov_b32_e32 v27, v0
	v_mov_b32_e32 v32, v0
	v_mov_b32_e32 v33, v0
	v_mov_b32_e32 v34, v0
	v_mov_b32_e32 v35, v0
	v_mov_b32_e32 v40, v0
	v_mov_b32_e32 v41, v0
	v_mov_b32_e32 v42, v0
	v_mov_b32_e32 v43, v0
	v_mov_b32_e32 v48, v0
	v_mov_b32_e32 v49, v0
	v_mov_b32_e32 v50, v0
	v_mov_b32_e32 v51, v0
	v_mov_b32_e32 v12, v0
	v_mov_b32_e32 v13, v0
	v_mov_b32_e32 v14, v0
	v_mov_b32_e32 v15, v0
	v_mov_b32_e32 v20, v0
	v_mov_b32_e32 v21, v0
	v_mov_b32_e32 v22, v0
	v_mov_b32_e32 v23, v0
	v_mov_b32_e32 v28, v0
	v_mov_b32_e32 v29, v0
	v_mov_b32_e32 v30, v0
	v_mov_b32_e32 v31, v0
	v_mov_b32_e32 v36, v0
	v_mov_b32_e32 v37, v0
	v_mov_b32_e32 v38, v0
	v_mov_b32_e32 v39, v0
	v_mov_b32_e32 v44, v0
	v_mov_b32_e32 v45, v0
	v_mov_b32_e32 v46, v0
	v_mov_b32_e32 v47, v0
	v_mov_b32_e32 v52, v0
	v_mov_b32_e32 v53, v0
	v_mov_b32_e32 v54, v0
	v_mov_b32_e32 v55, v0
	v_mov_b32_e32 v56, v0
	v_mov_b32_e32 v57, v0
	v_mov_b32_e32 v58, v0
	v_mov_b32_e32 v59, v0
	v_mov_b32_e32 v60, v0
	v_mov_b32_e32 v61, v0
	v_mov_b32_e32 v62, v0
	v_mov_b32_e32 v63, v0
	v_mov_b32_e32 v64, v0
	v_mov_b32_e32 v65, v0
	v_mov_b32_e32 v66, v0
	v_mov_b32_e32 v67, v0
	v_mov_b32_e32 v68, v0
	v_mov_b32_e32 v69, v0
	v_mov_b32_e32 v70, v0
	v_mov_b32_e32 v71, v0
	v_mov_b32_e32 v72, v0
	v_mov_b32_e32 v73, v0
	v_mov_b32_e32 v74, v0
	v_mov_b32_e32 v75, v0
	v_mov_b32_e32 v80, v0
	v_mov_b32_e32 v81, v0
	v_mov_b32_e32 v82, v0
	v_mov_b32_e32 v83, v0
	v_mov_b32_e32 v88, v0
	v_mov_b32_e32 v89, v0
	v_mov_b32_e32 v90, v0
	v_mov_b32_e32 v91, v0
	v_mov_b32_e32 v96, v0
	v_mov_b32_e32 v97, v0
	v_mov_b32_e32 v98, v0
	v_mov_b32_e32 v99, v0
	v_mov_b32_e32 v104, v0
	v_mov_b32_e32 v105, v0
	v_mov_b32_e32 v106, v0
	v_mov_b32_e32 v107, v0
	v_mov_b32_e32 v112, v0
	v_mov_b32_e32 v113, v0
	v_mov_b32_e32 v114, v0
	v_mov_b32_e32 v115, v0
	v_mov_b32_e32 v76, v0
	v_mov_b32_e32 v77, v0
	v_mov_b32_e32 v78, v0
	v_mov_b32_e32 v79, v0
	v_mov_b32_e32 v84, v0
	v_mov_b32_e32 v85, v0
	v_mov_b32_e32 v86, v0
	v_mov_b32_e32 v87, v0
	v_mov_b32_e32 v92, v0
	v_mov_b32_e32 v93, v0
	v_mov_b32_e32 v94, v0
	v_mov_b32_e32 v95, v0
	v_mov_b32_e32 v100, v0
	v_mov_b32_e32 v101, v0
	v_mov_b32_e32 v102, v0
	v_mov_b32_e32 v103, v0
	v_mov_b32_e32 v108, v0
	v_mov_b32_e32 v109, v0
	v_mov_b32_e32 v110, v0
	v_mov_b32_e32 v111, v0
	v_mov_b32_e32 v116, v0
	v_mov_b32_e32 v117, v0
	v_mov_b32_e32 v118, v0
	v_mov_b32_e32 v119, v0
	v_mov_b32_e32 v120, v0
	v_mov_b32_e32 v121, v0
	v_mov_b32_e32 v122, v0
	v_mov_b32_e32 v123, v0
	v_mov_b32_e32 v124, v0
	v_mov_b32_e32 v125, v0
	v_mov_b32_e32 v126, v0
	v_mov_b32_e32 v127, v0
	s_cmp_eq_u32 s98, 0
	s_cbranch_scc1 .LBB0_1330
	ds_read_b128 v[152:155], v149
	ds_read_b128 v[156:159], v149 offset:1024
	ds_read_b128 v[160:163], v149 offset:2048
	ds_read_b128 v[164:167], v149 offset:3072
	ds_read_b128 v[172:175], v150
	ds_read_b128 v[176:179], v150 offset:1024
	ds_read_b128 v[180:183], v150 offset:2048
	ds_read_b128 v[184:187], v150 offset:3072
	s_add_u32 s40, s38, 0xfffe0080
	s_addc_u32 s41, s39, -1
	s_cmp_eq_u32 s65, 4
	s_cselect_b32 s43, s27, s41
	s_cselect_b32 s42, s61, s40
	s_cselect_b32 s41, s25, s64
	s_cselect_b32 s40, s62, s63
	v_lshl_add_u64 v[144:145], s[38:39], 0, v[136:137]
	s_add_i32 m0, s37, 0xc000
	ds_read_b128 v[188:191], v151
	ds_read_b128 v[192:195], v151 offset:1024
	ds_read_b128 v[196:199], v151 offset:2048
	ds_read_b128 v[200:203], v151 offset:3072
	ds_read_b128 v[204:207], v151 offset:4096
	ds_read_b128 v[208:211], v151 offset:5120
	ds_read_b128 v[212:215], v151 offset:6144
	ds_read_b128 v[216:219], v151 offset:7168
	global_load_lds_dwordx4 v[144:145], off
	v_lshl_add_u64 v[144:145], s[38:39], 0, v[138:139]
	s_add_i32 m0, s37, 0xe000
	s_nop 0
	global_load_lds_dwordx4 v[144:145], off
	s_waitcnt vmcnt(24)
	s_waitcnt lgkmcnt(0)
	s_barrier
; #define PG8_STAGE(bufoff, gbase, voff) do { _Pragma("unroll") for (int _i = 0; _i < 2; ++_i) \
;     __builtin_amdgcn_global_load_lds((const unsigned*)((const char*)(gbase) + (voff)[_i]), (LAS unsigned*)(lds + (bufoff) + ldsw + _i * 8192), 16, 0, 0); } while (0)
; #define PG8_LDA(dst, b, h) do { _Pragma("unroll") for (int m = 0; m < 4; ++m) _Pragma("unroll") for (int k = 0; k < 2; ++k) dst[m][k] = *(const LAS bf16x8*)(lds + PG8_SA(b, h) + aoff + m * 2048 + k * 1024); } while (0)
; #define PG8_MMA(ai, bj, At, Bt) do { __builtin_amdgcn_s_setprio(1); _Pragma("unroll") for (int m = 0; m < 4; ++m) _Pragma("unroll") for (int n = 0; n < 2; ++n) _Pragma("unroll") for (int k = 0; k < 2; ++k) \
;     acc[ai][bj][m][n] = __builtin_amdgcn_mfma_f32_16x16x32_bf16(Bt[n][k], At[m][k], acc[ai][bj][m][n], 0, 0, 0); __builtin_amdgcn_s_setprio(0); } while (0)
; #define PG8_WAIT_V(n) asm volatile("s_waitcnt vmcnt(" #n ")" ::: "memory")
; #define PG8_WAIT_L(n) asm volatile("s_waitcnt lgkmcnt(" #n ")" ::: "memory")
; #define PG8_BAR __builtin_amdgcn_s_barrier()
; #define PG8_SCHED __builtin_amdgcn_sched_barrier(0)
; template <class Epi, class Sched, bool ALIGN_EPI = true>
; __device__ __forceinline__ void gemm_phase(LAS unsigned char* lds, const Gemm g, const Sched& S, const Epi& E) {
;     ...
;       PG8_WAIT_V(8); PG8_WAIT_L(0); PG8_BAR; PG8_MMA(0, 0, At, B0); PG8_MMA(0, 1, At, B1); PG8_BAR; PG8_SCHED;
;       PG8_LDA(At, 0, 1); PG8_STAGE(PG8_SB(0, 0), b2, voffB); PG8_STAGE(PG8_SB(0, 1), b2 + hstepB, voffB); PG8_STAGE(PG8_SA(0, 0), a2, voffA);
;       PG8_WAIT_V(8); PG8_WAIT_L(0); PG8_BAR; PG8_MMA(1, 0, At, B0); PG8_MMA(1, 1, At, B1); PG8_BAR; PG8_SCHED;
	s_setprio 1
	s_waitcnt lgkmcnt(0)
	v_mfma_f32_16x16x32_bf16 v[124:127], v[152:155], v[188:191], v[124:127]
	v_mfma_f32_16x16x32_bf16 v[120:123], v[160:163], v[188:191], v[120:123]
	v_mfma_f32_16x16x32_bf16 v[116:119], v[152:155], v[196:199], v[116:119]
	v_mfma_f32_16x16x32_bf16 v[108:111], v[160:163], v[196:199], v[108:111]
	v_mfma_f32_16x16x32_bf16 v[100:103], v[152:155], v[204:207], v[100:103]
	v_mfma_f32_16x16x32_bf16 v[92:95], v[160:163], v[204:207], v[92:95]
	v_mfma_f32_16x16x32_bf16 v[84:87], v[152:155], v[212:215], v[84:87]
	v_mfma_f32_16x16x32_bf16 v[76:79], v[160:163], v[212:215], v[76:79]
	v_mfma_f32_16x16x32_bf16 v[124:127], v[156:159], v[192:195], v[124:127]
	v_mfma_f32_16x16x32_bf16 v[120:123], v[164:167], v[192:195], v[120:123]
	v_mfma_f32_16x16x32_bf16 v[116:119], v[156:159], v[200:203], v[116:119]
	v_mfma_f32_16x16x32_bf16 v[108:111], v[164:167], v[200:203], v[108:111]
	v_mfma_f32_16x16x32_bf16 v[100:103], v[156:159], v[208:211], v[100:103]
	v_mfma_f32_16x16x32_bf16 v[92:95], v[164:167], v[208:211], v[92:95]
	v_mfma_f32_16x16x32_bf16 v[84:87], v[156:159], v[216:219], v[84:87]
	v_mfma_f32_16x16x32_bf16 v[76:79], v[164:167], v[216:219], v[76:79]
	s_setprio 0
	s_setprio 1
	v_mfma_f32_16x16x32_bf16 v[112:115], v[172:175], v[188:191], v[112:115]
	v_mfma_f32_16x16x32_bf16 v[104:107], v[180:183], v[188:191], v[104:107]
	v_mfma_f32_16x16x32_bf16 v[96:99], v[172:175], v[196:199], v[96:99]
	v_mfma_f32_16x16x32_bf16 v[88:91], v[180:183], v[196:199], v[88:91]
	v_mfma_f32_16x16x32_bf16 v[80:83], v[172:175], v[204:207], v[80:83]
	v_mfma_f32_16x16x32_bf16 v[72:75], v[180:183], v[204:207], v[72:75]
	v_mfma_f32_16x16x32_bf16 v[68:71], v[172:175], v[212:215], v[68:71]
	v_mfma_f32_16x16x32_bf16 v[64:67], v[180:183], v[212:215], v[64:67]
	v_mfma_f32_16x16x32_bf16 v[112:115], v[176:179], v[192:195], v[112:115]
	v_mfma_f32_16x16x32_bf16 v[104:107], v[184:187], v[192:195], v[104:107]
	v_mfma_f32_16x16x32_bf16 v[96:99], v[176:179], v[200:203], v[96:99]
	v_mfma_f32_16x16x32_bf16 v[88:91], v[184:187], v[200:203], v[88:91]
	v_mfma_f32_16x16x32_bf16 v[80:83], v[176:179], v[208:211], v[80:83]
	v_mfma_f32_16x16x32_bf16 v[72:75], v[184:187], v[208:211], v[72:75]
	v_mfma_f32_16x16x32_bf16 v[68:71], v[176:179], v[216:219], v[68:71]
	v_mfma_f32_16x16x32_bf16 v[64:67], v[184:187], v[216:219], v[64:67]
	s_setprio 0
	s_barrier
	s_add_i32 s66, s54, s33
	v_lshl_add_u64 v[144:145], s[40:41], 0, v[132:133]
	s_mov_b32 m0, s66
	ds_read_b128 v[188:191], v151 offset:16384
	ds_read_b128 v[192:195], v151 offset:17408
	ds_read_b128 v[196:199], v151 offset:18432
	ds_read_b128 v[200:203], v151 offset:19456
	ds_read_b128 v[204:207], v151 offset:20480
	ds_read_b128 v[208:211], v151 offset:21504
	ds_read_b128 v[212:215], v151 offset:22528
	ds_read_b128 v[216:219], v151 offset:23552
	global_load_lds_dwordx4 v[144:145], off
	s_add_i32 m0, s66, 0x2000
	s_add_u32 s66, s40, 0x20000
	v_lshl_add_u64 v[168:169], s[40:41], 0, v[128:129]
	s_addc_u32 s67, s41, 0
	s_add_i32 s68, s55, s33
	global_load_lds_dwordx4 v[168:169], off
	v_lshl_add_u64 v[220:221], s[66:67], 0, v[132:133]
	s_mov_b32 m0, s68
	v_lshl_add_u64 v[222:223], s[42:43], 0, v[130:131]
	global_load_lds_dwordx4 v[220:221], off
	v_lshl_add_u64 v[220:221], s[66:67], 0, v[128:129]
	s_add_i32 m0, s68, 0x2000
	s_nop 0
	global_load_lds_dwordx4 v[220:221], off
	v_lshl_add_u64 v[220:221], s[42:43], 0, v[134:135]
	s_mov_b32 m0, s37
	s_nop 0
	global_load_lds_dwordx4 v[220:221], off
	s_mov_b32 m0, s46
	s_nop 0
	global_load_lds_dwordx4 v[222:223], off
	s_waitcnt vmcnt(24)
	s_waitcnt lgkmcnt(0)
	s_barrier
	s_setprio 1
	s_waitcnt lgkmcnt(0)
	v_mfma_f32_16x16x32_bf16 v[60:63], v[152:155], v[188:191], v[60:63]
	v_mfma_f32_16x16x32_bf16 v[56:59], v[160:163], v[188:191], v[56:59]
	v_mfma_f32_16x16x32_bf16 v[52:55], v[152:155], v[196:199], v[52:55]
	v_mfma_f32_16x16x32_bf16 v[44:47], v[160:163], v[196:199], v[44:47]
	v_mfma_f32_16x16x32_bf16 v[36:39], v[152:155], v[204:207], v[36:39]
	v_mfma_f32_16x16x32_bf16 v[28:31], v[160:163], v[204:207], v[28:31]
	v_mfma_f32_16x16x32_bf16 v[20:23], v[152:155], v[212:215], v[20:23]
	v_mfma_f32_16x16x32_bf16 v[12:15], v[160:163], v[212:215], v[12:15]
	v_mfma_f32_16x16x32_bf16 v[60:63], v[156:159], v[192:195], v[60:63]
	v_mfma_f32_16x16x32_bf16 v[56:59], v[164:167], v[192:195], v[56:59]
	v_mfma_f32_16x16x32_bf16 v[52:55], v[156:159], v[200:203], v[52:55]
	v_mfma_f32_16x16x32_bf16 v[44:47], v[164:167], v[200:203], v[44:47]
	v_mfma_f32_16x16x32_bf16 v[36:39], v[156:159], v[208:211], v[36:39]
	v_mfma_f32_16x16x32_bf16 v[28:31], v[164:167], v[208:211], v[28:31]
	v_mfma_f32_16x16x32_bf16 v[20:23], v[156:159], v[216:219], v[20:23]
	v_mfma_f32_16x16x32_bf16 v[12:15], v[164:167], v[216:219], v[12:15]
	s_setprio 0
	s_setprio 1
	v_mfma_f32_16x16x32_bf16 v[48:51], v[172:175], v[188:191], v[48:51]
	v_mfma_f32_16x16x32_bf16 v[40:43], v[180:183], v[188:191], v[40:43]
	v_mfma_f32_16x16x32_bf16 v[32:35], v[172:175], v[196:199], v[32:35]
	v_mfma_f32_16x16x32_bf16 v[24:27], v[180:183], v[196:199], v[24:27]
	v_mfma_f32_16x16x32_bf16 v[16:19], v[172:175], v[204:207], v[16:19]
	v_mfma_f32_16x16x32_bf16 v[8:11], v[180:183], v[204:207], v[8:11]
	v_mfma_f32_16x16x32_bf16 v[4:7], v[172:175], v[212:215], v[4:7]
	v_mfma_f32_16x16x32_bf16 v[0:3], v[180:183], v[212:215], v[0:3]
	v_mfma_f32_16x16x32_bf16 v[48:51], v[176:179], v[192:195], v[48:51]
	v_mfma_f32_16x16x32_bf16 v[40:43], v[184:187], v[192:195], v[40:43]
	v_mfma_f32_16x16x32_bf16 v[32:35], v[176:179], v[200:203], v[32:35]
	v_mfma_f32_16x16x32_bf16 v[24:27], v[184:187], v[200:203], v[24:27]
	v_mfma_f32_16x16x32_bf16 v[16:19], v[176:179], v[208:211], v[16:19]
	v_mfma_f32_16x16x32_bf16 v[8:11], v[184:187], v[208:211], v[8:11]
	v_mfma_f32_16x16x32_bf16 v[4:7], v[176:179], v[216:219], v[4:7]
	v_mfma_f32_16x16x32_bf16 v[0:3], v[184:187], v[216:219], v[0:3]
	s_setprio 0
	s_barrier
	s_branch .Lpeel_mid_1330

; #define PG8_STAGE(bufoff, gbase, voff) do { _Pragma("unroll") for (int _i = 0; _i < 2; ++_i) \
;     __builtin_amdgcn_global_load_lds((const unsigned*)((const char*)(gbase) + (voff)[_i]), (LAS unsigned*)(lds + (bufoff) + ldsw + _i * 8192), 16, 0, 0); } while (0)
; #define PG8_LDA(dst, b, h) do { _Pragma("unroll") for (int m = 0; m < 4; ++m) _Pragma("unroll") for (int k = 0; k < 2; ++k) dst[m][k] = *(const LAS bf16x8*)(lds + PG8_SA(b, h) + aoff + m * 2048 + k * 1024); } while (0)
; #define PG8_LDB(dst, b, h) do { _Pragma("unroll") for (int n = 0; n < 2; ++n) _Pragma("unroll") for (int k = 0; k < 2; ++k) dst[n][k] = *(const LAS bf16x8*)(lds + PG8_SB(b, h) + boff + n * 2048 + k * 1024); } while (0)
; #define PG8_MMA(ai, bj, At, Bt) do { __builtin_amdgcn_s_setprio(1); _Pragma("unroll") for (int m = 0; m < 4; ++m) _Pragma("unroll") for (int n = 0; n < 2; ++n) _Pragma("unroll") for (int k = 0; k < 2; ++k) \
;     acc[ai][bj][m][n] = __builtin_amdgcn_mfma_f32_16x16x32_bf16(Bt[n][k], At[m][k], acc[ai][bj][m][n], 0, 0, 0); __builtin_amdgcn_s_setprio(0); } while (0)
; #define PG8_WAIT_V(n) asm volatile("s_waitcnt vmcnt(" #n ")" ::: "memory")
; #define PG8_WAIT_L(n) asm volatile("s_waitcnt lgkmcnt(" #n ")" ::: "memory")
; #define PG8_BAR __builtin_amdgcn_s_barrier()
; #define PG8_SCHED __builtin_amdgcn_sched_barrier(0)
; template <class Epi, class Sched, bool ALIGN_EPI = true>
; __device__ __forceinline__ void gemm_phase(LAS unsigned char* lds, const Gemm g, const Sched& S, const Epi& E) {
;     ...
;       PG8_LDB(B0, 1, 0); PG8_LDB(B1, 1, 1); PG8_SCHED; PG8_LDA(At, 1, 0); PG8_STAGE(PG8_SA(0, 1), a2 + hstepA, voffA);
;       PG8_WAIT_V(8); PG8_WAIT_L(0); PG8_BAR; PG8_MMA(0, 0, At, B0); PG8_MMA(0, 1, At, B1); PG8_BAR; PG8_SCHED;
.Lpeel_mid_1330:
	s_add_i32 s66, 0, 0x18000
	s_add_i32 s67, 0, 0x1c000
	v_add_u32_e32 v164, s66, v147
	v_add_u32_e32 v184, s67, v147
	ds_read_b128 v[152:155], v164
	ds_read_b128 v[156:159], v164 offset:1024
	ds_read_b128 v[160:163], v164 offset:2048
	ds_read_b128 v[164:167], v164 offset:3072
	ds_read_b128 v[172:175], v184
	ds_read_b128 v[176:179], v184 offset:1024
	ds_read_b128 v[180:183], v184 offset:2048
	ds_read_b128 v[184:187], v184 offset:3072
	s_add_u32 s42, s42, 0x20000
	s_addc_u32 s43, s43, 0
	s_mov_b32 m0, s47
	v_lshl_add_u64 v[224:225], s[42:43], 0, v[134:135]
	ds_read_b128 v[188:191], v151 offset:32768
	ds_read_b128 v[192:195], v151 offset:33792
	ds_read_b128 v[196:199], v151 offset:34816
	ds_read_b128 v[200:203], v151 offset:35840
	ds_read_b128 v[204:207], v151 offset:36864
	ds_read_b128 v[208:211], v151 offset:37888
	ds_read_b128 v[212:215], v151 offset:38912
	ds_read_b128 v[216:219], v151 offset:39936
	global_load_lds_dwordx4 v[224:225], off
	v_lshl_add_u64 v[224:225], s[42:43], 0, v[130:131]
	s_mov_b32 m0, s48
	s_nop 0
	global_load_lds_dwordx4 v[224:225], off
	s_waitcnt vmcnt(8)
	s_waitcnt lgkmcnt(0)
	s_barrier
	s_setprio 1
	s_waitcnt lgkmcnt(0)
	v_mfma_f32_16x16x32_bf16 v[124:127], v[152:155], v[188:191], v[124:127]
	v_mfma_f32_16x16x32_bf16 v[120:123], v[160:163], v[188:191], v[120:123]
	v_mfma_f32_16x16x32_bf16 v[116:119], v[152:155], v[196:199], v[116:119]
	v_mfma_f32_16x16x32_bf16 v[108:111], v[160:163], v[196:199], v[108:111]
	v_mfma_f32_16x16x32_bf16 v[100:103], v[152:155], v[204:207], v[100:103]
	v_mfma_f32_16x16x32_bf16 v[92:95], v[160:163], v[204:207], v[92:95]
	v_mfma_f32_16x16x32_bf16 v[84:87], v[152:155], v[212:215], v[84:87]
	v_mfma_f32_16x16x32_bf16 v[76:79], v[160:163], v[212:215], v[76:79]
	v_mfma_f32_16x16x32_bf16 v[124:127], v[156:159], v[192:195], v[124:127]
	v_mfma_f32_16x16x32_bf16 v[120:123], v[164:167], v[192:195], v[120:123]
	v_mfma_f32_16x16x32_bf16 v[116:119], v[156:159], v[200:203], v[116:119]
	v_mfma_f32_16x16x32_bf16 v[108:111], v[164:167], v[200:203], v[108:111]
	v_mfma_f32_16x16x32_bf16 v[100:103], v[156:159], v[208:211], v[100:103]
	v_mfma_f32_16x16x32_bf16 v[92:95], v[164:167], v[208:211], v[92:95]
	v_mfma_f32_16x16x32_bf16 v[84:87], v[156:159], v[216:219], v[84:87]
	v_mfma_f32_16x16x32_bf16 v[76:79], v[164:167], v[216:219], v[76:79]
	s_setprio 0
	s_setprio 1
	v_mfma_f32_16x16x32_bf16 v[112:115], v[172:175], v[188:191], v[112:115]
	v_mfma_f32_16x16x32_bf16 v[104:107], v[180:183], v[188:191], v[104:107]
	v_mfma_f32_16x16x32_bf16 v[96:99], v[172:175], v[196:199], v[96:99]
	v_mfma_f32_16x16x32_bf16 v[88:91], v[180:183], v[196:199], v[88:91]
	v_mfma_f32_16x16x32_bf16 v[80:83], v[172:175], v[204:207], v[80:83]
	v_mfma_f32_16x16x32_bf16 v[72:75], v[180:183], v[204:207], v[72:75]
	v_mfma_f32_16x16x32_bf16 v[68:71], v[172:175], v[212:215], v[68:71]
	v_mfma_f32_16x16x32_bf16 v[64:67], v[180:183], v[212:215], v[64:67]
	v_mfma_f32_16x16x32_bf16 v[112:115], v[176:179], v[192:195], v[112:115]
	v_mfma_f32_16x16x32_bf16 v[104:107], v[184:187], v[192:195], v[104:107]
	v_mfma_f32_16x16x32_bf16 v[96:99], v[176:179], v[200:203], v[96:99]
	v_mfma_f32_16x16x32_bf16 v[88:91], v[184:187], v[200:203], v[88:91]
	v_mfma_f32_16x16x32_bf16 v[80:83], v[176:179], v[208:211], v[80:83]
	v_mfma_f32_16x16x32_bf16 v[72:75], v[184:187], v[208:211], v[72:75]
	v_mfma_f32_16x16x32_bf16 v[68:71], v[176:179], v[216:219], v[68:71]
	v_mfma_f32_16x16x32_bf16 v[64:67], v[184:187], v[216:219], v[64:67]
	s_setprio 0
	s_barrier
; #define PG8_STAGE(bufoff, gbase, voff) do { _Pragma("unroll") for (int _i = 0; _i < 2; ++_i) \
;     __builtin_amdgcn_global_load_lds((const unsigned*)((const char*)(gbase) + (voff)[_i]), (LAS unsigned*)(lds + (bufoff) + ldsw + _i * 8192), 16, 0, 0); } while (0)
; #define PG8_LDA(dst, b, h) do { _Pragma("unroll") for (int m = 0; m < 4; ++m) _Pragma("unroll") for (int k = 0; k < 2; ++k) dst[m][k] = *(const LAS bf16x8*)(lds + PG8_SA(b, h) + aoff + m * 2048 + k * 1024); } while (0)
; #define PG8_MMA(ai, bj, At, Bt) do { __builtin_amdgcn_s_setprio(1); _Pragma("unroll") for (int m = 0; m < 4; ++m) _Pragma("unroll") for (int n = 0; n < 2; ++n) _Pragma("unroll") for (int k = 0; k < 2; ++k) \
;     acc[ai][bj][m][n] = __builtin_amdgcn_mfma_f32_16x16x32_bf16(Bt[n][k], At[m][k], acc[ai][bj][m][n], 0, 0, 0); __builtin_amdgcn_s_setprio(0); } while (0)
; #define PG8_WAIT_V(n) asm volatile("s_waitcnt vmcnt(" #n ")" ::: "memory")
; #define PG8_WAIT_L(n) asm volatile("s_waitcnt lgkmcnt(" #n ")" ::: "memory")
; #define PG8_BAR __builtin_amdgcn_s_barrier()
; #define PG8_SCHED __builtin_amdgcn_sched_barrier(0)
; template <class Epi, class Sched, bool ALIGN_EPI = true>
; __device__ __forceinline__ void gemm_phase(LAS unsigned char* lds, const Gemm g, const Sched& S, const Epi& E) {
;     ...
;       PG8_LDA(At, 1, 1); PG8_STAGE(PG8_SB(1, 0), b3, voffB); PG8_STAGE(PG8_SB(1, 1), b3 + hstepB, voffB); PG8_STAGE(PG8_SA(1, 0), a3, voffA);
;       PG8_WAIT_V(8); PG8_WAIT_L(0); PG8_BAR; PG8_MMA(1, 0, At, B0); PG8_MMA(1, 1, At, B1); PG8_BAR; PG8_SCHED;
;     }
;     if constexpr (ALIGN_EPI) { if (wr == 0) PG8_BAR; }
	s_add_i32 s42, s66, s33
	v_lshl_add_u64 v[144:145], v[144:145], 0, s[12:13]
	s_mov_b32 m0, s42
	ds_read_b128 v[188:191], v151 offset:49152
	ds_read_b128 v[192:195], v151 offset:50176
	ds_read_b128 v[196:199], v151 offset:51200
	ds_read_b128 v[200:203], v151 offset:52224
	ds_read_b128 v[204:207], v151 offset:53248
	ds_read_b128 v[208:211], v151 offset:54272
	ds_read_b128 v[212:215], v151 offset:55296
	ds_read_b128 v[216:219], v151 offset:56320
	global_load_lds_dwordx4 v[144:145], off
	s_add_i32 m0, s42, 0x2000
	s_add_u32 s40, s40, 0x20080
	v_lshl_add_u64 v[144:145], v[168:169], 0, s[12:13]
	s_addc_u32 s41, s41, 0
	s_add_i32 s42, s67, s33
	global_load_lds_dwordx4 v[144:145], off
	v_lshl_add_u64 v[144:145], s[40:41], 0, v[132:133]
	s_mov_b32 m0, s42
	s_nop 0
	global_load_lds_dwordx4 v[144:145], off
	v_lshl_add_u64 v[144:145], s[40:41], 0, v[128:129]
	s_add_i32 m0, s42, 0x2000
	s_nop 0
	global_load_lds_dwordx4 v[144:145], off
	v_lshl_add_u64 v[144:145], v[220:221], 0, s[12:13]
	s_mov_b32 m0, s50
	s_nop 0
	global_load_lds_dwordx4 v[144:145], off
	v_lshl_add_u64 v[144:145], v[222:223], 0, s[12:13]
	s_mov_b32 m0, s51
	s_nop 0
	global_load_lds_dwordx4 v[144:145], off
	s_waitcnt vmcnt(8)
	s_waitcnt lgkmcnt(0)
	s_barrier
	s_setprio 1
	s_waitcnt lgkmcnt(0)
	v_mfma_f32_16x16x32_bf16 v[60:63], v[152:155], v[188:191], v[60:63]
	v_mfma_f32_16x16x32_bf16 v[56:59], v[160:163], v[188:191], v[56:59]
	v_mfma_f32_16x16x32_bf16 v[52:55], v[152:155], v[196:199], v[52:55]
	v_mfma_f32_16x16x32_bf16 v[44:47], v[160:163], v[196:199], v[44:47]
	v_mfma_f32_16x16x32_bf16 v[36:39], v[152:155], v[204:207], v[36:39]
	v_mfma_f32_16x16x32_bf16 v[28:31], v[160:163], v[204:207], v[28:31]
	v_mfma_f32_16x16x32_bf16 v[20:23], v[152:155], v[212:215], v[20:23]
	v_mfma_f32_16x16x32_bf16 v[12:15], v[160:163], v[212:215], v[12:15]
	v_mfma_f32_16x16x32_bf16 v[60:63], v[156:159], v[192:195], v[60:63]
	v_mfma_f32_16x16x32_bf16 v[56:59], v[164:167], v[192:195], v[56:59]
	v_mfma_f32_16x16x32_bf16 v[52:55], v[156:159], v[200:203], v[52:55]
	v_mfma_f32_16x16x32_bf16 v[44:47], v[164:167], v[200:203], v[44:47]
	v_mfma_f32_16x16x32_bf16 v[36:39], v[156:159], v[208:211], v[36:39]
	v_mfma_f32_16x16x32_bf16 v[28:31], v[164:167], v[208:211], v[28:31]
	v_mfma_f32_16x16x32_bf16 v[20:23], v[156:159], v[216:219], v[20:23]
	v_mfma_f32_16x16x32_bf16 v[12:15], v[164:167], v[216:219], v[12:15]
	s_setprio 0
	s_setprio 1
	v_mfma_f32_16x16x32_bf16 v[48:51], v[172:175], v[188:191], v[48:51]
	v_mfma_f32_16x16x32_bf16 v[40:43], v[180:183], v[188:191], v[40:43]
	v_mfma_f32_16x16x32_bf16 v[32:35], v[172:175], v[196:199], v[32:35]
	v_mfma_f32_16x16x32_bf16 v[24:27], v[180:183], v[196:199], v[24:27]
	v_mfma_f32_16x16x32_bf16 v[16:19], v[172:175], v[204:207], v[16:19]
	v_mfma_f32_16x16x32_bf16 v[8:11], v[180:183], v[204:207], v[8:11]
	v_mfma_f32_16x16x32_bf16 v[4:7], v[172:175], v[212:215], v[4:7]
	v_mfma_f32_16x16x32_bf16 v[0:3], v[180:183], v[212:215], v[0:3]
	v_mfma_f32_16x16x32_bf16 v[48:51], v[176:179], v[192:195], v[48:51]
	v_mfma_f32_16x16x32_bf16 v[40:43], v[184:187], v[192:195], v[40:43]
	v_mfma_f32_16x16x32_bf16 v[32:35], v[176:179], v[200:203], v[32:35]
	v_mfma_f32_16x16x32_bf16 v[24:27], v[184:187], v[200:203], v[24:27]
	v_mfma_f32_16x16x32_bf16 v[16:19], v[176:179], v[208:211], v[16:19]
	v_mfma_f32_16x16x32_bf16 v[8:11], v[184:187], v[208:211], v[8:11]
	v_mfma_f32_16x16x32_bf16 v[4:7], v[176:179], v[216:219], v[4:7]
	v_mfma_f32_16x16x32_bf16 v[0:3], v[184:187], v[216:219], v[0:3]
	s_setprio 0
	s_barrier
	s_add_i32 s65, s65, 2
	s_add_u32 s38, s38, 0x100
	s_addc_u32 s39, s39, 0
	s_add_u32 s63, s63, 0x100
	s_addc_u32 s64, s64, 0
	s_cmp_gt_u32 s65, 5
	s_cbranch_scc0 .LBB0_1330
	s_mov_b32 s98, 1
	s_and_b64 vcc, exec, s[14:15]
	s_cbranch_vccz .LBB0_1333
	s_barrier

; #define PG8_STAGE(bufoff, gbase, voff) do { _Pragma("unroll") for (int _i = 0; _i < 2; ++_i) \
;     __builtin_amdgcn_global_load_lds((const unsigned*)((const char*)(gbase) + (voff)[_i]), (LAS unsigned*)(lds + (bufoff) + ldsw + _i * 8192), 16, 0, 0); } while (0)
; #define PG8_WAIT_V(n) asm volatile("s_waitcnt vmcnt(" #n ")" ::: "memory")
; #define PG8_BAR __builtin_amdgcn_s_barrier()
; template <class Epi, class Sched, bool ALIGN_EPI = true>
; __device__ __forceinline__ void gemm_phase(LAS unsigned char* lds, const Gemm g, const Sched& S, const Epi& E) {
;     ...
;   for (int i = 0; i < 2; ++i) { int R, C; stage_rc(tid * 16 + i * 8192, R, C); const int Rb = Epi::PERM ? ((R & ~31) + perm32(R & 31)) : R;
;     voffA[i] = (unsigned)(R * g.lda + C) * 2u; voffB[i] = (unsigned)(Rb * g.ldb + C) * 2u; }
;   const size_t koffL = (size_t)(nt - 1) * (BK * 2);
;   const size_t hstepA = (size_t)HALF * g.lda * 2, hstepB = (size_t)HALF * g.ldb * 2;
;   const size_t tstepA = 2 * hstepA, tstepB = 2 * hstepB;
;   const unsigned ldsw = (unsigned)wid * 1024u;
;   const int aoff = lds_byte(wr * 64 + fr, fq * 8), boff = lds_byte(wc * 32 + fr, fq * 8);
;     ...
;   Unit cur, nxt; int ui = 0;
;   if (!S.next(0, cur)) return;
;   f32x4 acc[2][2][4][2];
; #pragma unroll
;   for (int a = 0; a < 2; ++a)
; #pragma unroll
;     for (int b = 0; b < 2; ++b)
; #pragma unroll
;       for (int m = 0; m < 4; ++m)
; #pragma unroll
;         for (int n = 0; n < 2; ++n) acc[a][b][m][n] = (f32x4){0.f, 0.f, 0.f, 0.f};
;   bf16x8 At[4][2], B0[2][2], B1[2][2];
;   ptrdiff_t kstep = cur.kr ? -(ptrdiff_t)(BK * 2) : (ptrdiff_t)(BK * 2);
;   const char* cA = (const char*)g.A + (size_t)cur.pm * tstepA + cur.kb + (cur.kr ? koffL : 0); const char* cB = (const char*)g.Bt + (size_t)cur.pn * tstepB + cur.kb + (cur.kr ? koffL : 0);
;   PG8_STAGE(PG8_SB(0, 0), cB, voffB); PG8_STAGE(PG8_SB(0, 1), cB + hstepB, voffB); PG8_STAGE(PG8_SA(0, 0), cA, voffA); PG8_STAGE(PG8_SA(0, 1), cA + hstepA, voffA);
;   if (wr == 1) PG8_BAR;
;   PG8_WAIT_V(2); PG8_BAR;
;   PG8_STAGE(PG8_SB(1, 0), cB + kstep, voffB); PG8_STAGE(PG8_SA(1, 0), cA + kstep, voffA); PG8_STAGE(PG8_SB(1, 1), cB + hstepB + kstep, voffB);
;   PG8_WAIT_V(6); PG8_BAR;
.LBB0_1595:
	s_lshl_b32 s10, s10, 5
	s_and_b32 s16, s10, 0x60
	s_mov_b64 s[10:11], 0x80
	s_add_i32 m0, s35, 0x18000
	v_lshl_add_u64 v[6:7], v[6:7], 0, s[10:11]
	s_lshl_b32 s13, s12, 13
	s_lshl_b32 s17, s16, 7
	s_waitcnt vmcnt(2)
	s_barrier
	global_load_lds_dwordx4 v[6:7], off
	v_lshl_add_u64 v[4:5], v[4:5], 0, s[10:11]
	s_add_i32 m0, s35, 0x1a000
	s_add_i32 s46, s35, 0x8000
	s_add_i32 s47, s35, 0xa000
	global_load_lds_dwordx4 v[4:5], off
	v_lshl_add_u64 v[0:1], v[0:1], 0, s[10:11]
	s_mov_b32 m0, s46
	s_add_u32 s14, s38, 0x80080
	global_load_lds_dwordx4 v[0:1], off
	v_lshl_add_u64 v[0:1], v[2:3], 0, s[10:11]
	s_mov_b32 m0, s47
	s_addc_u32 s15, s39, 0
	global_load_lds_dwordx4 v[0:1], off
	s_add_i32 m0, s35, 0x1c000
	v_lshl_add_u64 v[0:1], s[14:15], 0, v[132:133]
	global_load_lds_dwordx4 v[0:1], off
	v_lshl_add_u64 v[0:1], s[14:15], 0, v[128:129]
	s_add_i32 m0, s35, 0x1e000
	s_cmpk_lt_u32 s7, 0x100
	global_load_lds_dwordx4 v[0:1], off
	v_lshrrev_b32_e32 v1, 1, v9
	v_and_b32_e32 v1, 24, v1
	v_and_b32_e32 v0, 15, v9
	v_lshlrev_b32_e32 v2, 1, v1
	v_lshl_or_b32 v146, s12, 6, v0
	v_lshl_or_b32 v0, v0, 6, v2
	v_lshlrev_b32_e32 v2, 2, v9
	v_and_b32_e32 v2, 32, v2
	v_bitop3_b32 v3, v0, s13, v2 bitop3:0xde
	v_bitop3_b32 v147, v0, s17, v2 bitop3:0xde
	v_lshlrev_b32_e32 v0, 15, v13
	v_and_b32_e32 v0, 0xffff0000, v0
	v_or_b32_e32 v148, s16, v1
	v_lshl_add_u32 v0, v12, 12, v0
	v_and_b32_e32 v1, 1, v13
	v_lshl_or_b32 v0, v1, 6, v0
	v_lshl_add_u32 v136, v14, 1, v0
	v_lshlrev_b32_e32 v0, 15, v8
	v_and_b32_e32 v0, 0xffff0000, v0
	s_waitcnt vmcnt(6)
	v_lshl_add_u32 v0, v10, 12, v0
	v_and_b32_e32 v1, 1, v8
	s_cselect_b64 s[12:13], -1, 0
	v_lshl_or_b32 v0, v1, 6, v0
	s_add_i32 s50, 0, 0x10000
	s_add_i32 s51, 0, 0x14000
	s_sext_i32_i16 s56, s6
	s_ashr_i32 s48, s86, 31
	s_mov_b32 s49, s86
	v_mov_b32_e32 v137, v133
	v_lshl_add_u32 v138, v11, 1, v0
	v_mov_b32_e32 v139, v133
	v_mov_b64_e32 v[140:141], 0x800
	v_mov_b64_e32 v[142:143], 0x7ff
	v_add_u32_e32 v149, s50, v147
	v_add_u32_e32 v150, s51, v147
	v_add_u32_e32 v151, 0, v3
	s_mov_b64 s[14:15], 0x200000
	s_mov_b32 s52, 0x200000
	s_mov_b64 s[16:17], 0x240000
	s_mov_b32 s53, 0x240000
	s_mov_b64 s[18:19], 0x280000
	s_mov_b32 s54, 0x280000
	s_mov_b64 s[20:21], 0x2c0000
	s_mov_b32 s55, 0x2c0000
	s_barrier
	s_mov_b32 s98, 0
	s_branch .LBB0_1598

; #define PG8_STAGE(bufoff, gbase, voff) do { _Pragma("unroll") for (int _i = 0; _i < 2; ++_i) \
;     __builtin_amdgcn_global_load_lds((const unsigned*)((const char*)(gbase) + (voff)[_i]), (LAS unsigned*)(lds + (bufoff) + ldsw + _i * 8192), 16, 0, 0); } while (0)
; #define PG8_LDA(dst, b, h) do { _Pragma("unroll") for (int m = 0; m < 4; ++m) _Pragma("unroll") for (int k = 0; k < 2; ++k) dst[m][k] = *(const LAS bf16x8*)(lds + PG8_SA(b, h) + aoff + m * 2048 + k * 1024); } while (0)
; #define PG8_LDB(dst, b, h) do { _Pragma("unroll") for (int n = 0; n < 2; ++n) _Pragma("unroll") for (int k = 0; k < 2; ++k) dst[n][k] = *(const LAS bf16x8*)(lds + PG8_SB(b, h) + boff + n * 2048 + k * 1024); } while (0)
; #define PG8_MMA(ai, bj, At, Bt) do { __builtin_amdgcn_s_setprio(1); _Pragma("unroll") for (int m = 0; m < 4; ++m) _Pragma("unroll") for (int n = 0; n < 2; ++n) _Pragma("unroll") for (int k = 0; k < 2; ++k) \
;     acc[ai][bj][m][n] = __builtin_amdgcn_mfma_f32_16x16x32_bf16(Bt[n][k], At[m][k], acc[ai][bj][m][n], 0, 0, 0); __builtin_amdgcn_s_setprio(0); } while (0)
; #define PG8_WAIT_V(n) asm volatile("s_waitcnt vmcnt(" #n ")" ::: "memory")
; #define PG8_WAIT_L(n) asm volatile("s_waitcnt lgkmcnt(" #n ")" ::: "memory")
; #define PG8_BAR __builtin_amdgcn_s_barrier()
; template <class Epi, class Sched, bool ALIGN_EPI = true>
; __device__ __forceinline__ void gemm_phase(LAS unsigned char* lds, const Gemm g, const Sched& S, const Epi& E) {
;     ...
;     for (int t = 0; t < nt; t += 2) {
;       const bool last = (t == nt - 2);
;       const char* a1 = cA + (ptrdiff_t)(t + 1) * kstep;
;       const char* a2 = last ? nA : cA + (ptrdiff_t)(t + 2) * kstep; const char* b2 = last ? nB : cB + (ptrdiff_t)(t + 2) * kstep;
;       const char* a3 = a2 + (last ? kstepN : kstep); const char* b3 = b2 + (last ? kstepN : kstep);
;       PG8_LDB(B0, 0, 0); PG8_LDB(B1, 0, 1); PG8_SCHED; PG8_LDA(At, 0, 0); PG8_STAGE(PG8_SA(1, 1), a1 + hstepA, voffA);
;       PG8_WAIT_V(8); PG8_WAIT_L(0); PG8_BAR; PG8_MMA(0, 0, At, B0); PG8_MMA(0, 1, At, B1); PG8_BAR; PG8_SCHED;
;     ...
; #pragma unroll
;     for (int a = 0; a < 2; ++a)
; #pragma unroll
;       for (int b = 0; b < 2; ++b)
; #pragma unroll
;         for (int m = 0; m < 4; ++m)
; #pragma unroll
;           for (int n = 0; n < 2; ++n) acc[a][b][m][n] = (f32x4){0.f, 0.f, 0.f, 0.f};
;     cur = nxt; cA = nA; cB = nB; kstep = kstepN; ++ui;
.LBB0_1600:
	s_ashr_i32 s25, s24, 31
	s_lshl_b64 s[26:27], s[24:25], 20
	v_readlane_b32 s30, v248, 10
	v_readlane_b32 s31, v248, 11
	s_add_u32 s26, s30, s26
	s_addc_u32 s27, s31, s27
	s_and_b64 s[30:31], s[6:7], exec
	s_cselect_b32 s25, s27, s37
	s_cselect_b32 s57, s26, s36
	s_ashr_i32 s23, s22, 31
	s_lshl_b64 s[30:31], s[22:23], 20
	s_add_u32 s30, s0, s30
	s_addc_u32 s31, s1, s31
	s_and_b64 s[40:41], s[6:7], exec
	s_cselect_b32 s23, s31, s39
	s_cselect_b32 s58, s30, s38
	s_add_u32 s36, s36, 0x80080
	s_addc_u32 s37, s37, 0
	s_add_u32 s59, s38, 0x100
	v_mov_b32_e32 v0, 0
	s_addc_u32 s60, s39, 0
	s_mov_b32 s61, -2
	v_mov_b32_e32 v1, v0
	v_mov_b32_e32 v2, v0
	v_mov_b32_e32 v3, v0
	v_mov_b32_e32 v4, v0
	v_mov_b32_e32 v5, v0
	v_mov_b32_e32 v6, v0
	v_mov_b32_e32 v7, v0
	v_mov_b32_e32 v16, v0
	v_mov_b32_e32 v17, v0
	v_mov_b32_e32 v18, v0
	v_mov_b32_e32 v19, v0
	v_mov_b32_e32 v20, v0
	v_mov_b32_e32 v21, v0
	v_mov_b32_e32 v22, v0
	v_mov_b32_e32 v23, v0
	v_mov_b32_e32 v32, v0
	v_mov_b32_e32 v33, v0
	v_mov_b32_e32 v34, v0
	v_mov_b32_e32 v35, v0
	v_mov_b32_e32 v36, v0
	v_mov_b32_e32 v37, v0
	v_mov_b32_e32 v38, v0
	v_mov_b32_e32 v39, v0
	v_mov_b32_e32 v48, v0
	v_mov_b32_e32 v49, v0
	v_mov_b32_e32 v50, v0
	v_mov_b32_e32 v51, v0
	v_mov_b32_e32 v52, v0
	v_mov_b32_e32 v53, v0
	v_mov_b32_e32 v54, v0
	v_mov_b32_e32 v55, v0
	v_mov_b32_e32 v8, v0
	v_mov_b32_e32 v9, v0
	v_mov_b32_e32 v10, v0
	v_mov_b32_e32 v11, v0
	v_mov_b32_e32 v12, v0
	v_mov_b32_e32 v13, v0
	v_mov_b32_e32 v14, v0
	v_mov_b32_e32 v15, v0
	v_mov_b32_e32 v24, v0
	v_mov_b32_e32 v25, v0
	v_mov_b32_e32 v26, v0
	v_mov_b32_e32 v27, v0
	v_mov_b32_e32 v28, v0
	v_mov_b32_e32 v29, v0
	v_mov_b32_e32 v30, v0
	v_mov_b32_e32 v31, v0
	v_mov_b32_e32 v40, v0
	v_mov_b32_e32 v41, v0
	v_mov_b32_e32 v42, v0
	v_mov_b32_e32 v43, v0
	v_mov_b32_e32 v44, v0
	v_mov_b32_e32 v45, v0
	v_mov_b32_e32 v46, v0
	v_mov_b32_e32 v47, v0
	v_mov_b32_e32 v56, v0
	v_mov_b32_e32 v57, v0
	v_mov_b32_e32 v58, v0
	v_mov_b32_e32 v59, v0
	v_mov_b32_e32 v60, v0
	v_mov_b32_e32 v61, v0
	v_mov_b32_e32 v62, v0
	v_mov_b32_e32 v63, v0
	v_mov_b32_e32 v64, v0
	v_mov_b32_e32 v65, v0
	v_mov_b32_e32 v66, v0
	v_mov_b32_e32 v67, v0
	v_mov_b32_e32 v68, v0
	v_mov_b32_e32 v69, v0
	v_mov_b32_e32 v70, v0
	v_mov_b32_e32 v71, v0
	v_mov_b32_e32 v80, v0
	v_mov_b32_e32 v81, v0
	v_mov_b32_e32 v82, v0
	v_mov_b32_e32 v83, v0
	v_mov_b32_e32 v84, v0
	v_mov_b32_e32 v85, v0
	v_mov_b32_e32 v86, v0
	v_mov_b32_e32 v87, v0
	v_mov_b32_e32 v96, v0
	v_mov_b32_e32 v97, v0
	v_mov_b32_e32 v98, v0
	v_mov_b32_e32 v99, v0
	v_mov_b32_e32 v100, v0
	v_mov_b32_e32 v101, v0
	v_mov_b32_e32 v102, v0
	v_mov_b32_e32 v103, v0
	v_mov_b32_e32 v112, v0
	v_mov_b32_e32 v113, v0
	v_mov_b32_e32 v114, v0
	v_mov_b32_e32 v115, v0
	v_mov_b32_e32 v116, v0
	v_mov_b32_e32 v117, v0
	v_mov_b32_e32 v118, v0
	v_mov_b32_e32 v119, v0
	v_mov_b32_e32 v72, v0
	v_mov_b32_e32 v73, v0
	v_mov_b32_e32 v74, v0
	v_mov_b32_e32 v75, v0
	v_mov_b32_e32 v76, v0
	v_mov_b32_e32 v77, v0
	v_mov_b32_e32 v78, v0
	v_mov_b32_e32 v79, v0
	v_mov_b32_e32 v88, v0
	v_mov_b32_e32 v89, v0
	v_mov_b32_e32 v90, v0
	v_mov_b32_e32 v91, v0
	v_mov_b32_e32 v92, v0
	v_mov_b32_e32 v93, v0
	v_mov_b32_e32 v94, v0
	v_mov_b32_e32 v95, v0
	v_mov_b32_e32 v104, v0
	v_mov_b32_e32 v105, v0
	v_mov_b32_e32 v106, v0
	v_mov_b32_e32 v107, v0
	v_mov_b32_e32 v108, v0
	v_mov_b32_e32 v109, v0
	v_mov_b32_e32 v110, v0
	v_mov_b32_e32 v111, v0
	v_mov_b32_e32 v120, v0
	v_mov_b32_e32 v121, v0
	v_mov_b32_e32 v122, v0
	v_mov_b32_e32 v123, v0
	v_mov_b32_e32 v124, v0
	v_mov_b32_e32 v125, v0
	v_mov_b32_e32 v126, v0
	v_mov_b32_e32 v127, v0
	s_cmp_eq_u32 s98, 0
	s_cbranch_scc1 .LBB0_1601
	ds_read_b128 v[152:155], v149
	ds_read_b128 v[156:159], v149 offset:1024
	ds_read_b128 v[160:163], v149 offset:2048
	ds_read_b128 v[164:167], v149 offset:3072
	ds_read_b128 v[172:175], v150
	ds_read_b128 v[176:179], v150 offset:1024
	ds_read_b128 v[180:183], v150 offset:2048
	ds_read_b128 v[184:187], v150 offset:3072
	s_add_u32 s38, s36, 0xfff80080
	s_addc_u32 s39, s37, -1
	s_cmp_eq_u32 s61, 28
	s_cselect_b32 s41, s25, s39
	s_cselect_b32 s40, s57, s38
	s_cselect_b32 s39, s23, s60
	s_cselect_b32 s38, s58, s59
	v_lshl_add_u64 v[144:145], s[36:37], 0, v[136:137]
	s_add_i32 m0, s35, 0xc000
	ds_read_b128 v[188:191], v151
	ds_read_b128 v[192:195], v151 offset:1024
	ds_read_b128 v[196:199], v151 offset:2048
	ds_read_b128 v[200:203], v151 offset:3072
	ds_read_b128 v[204:207], v151 offset:4096
	ds_read_b128 v[208:211], v151 offset:5120
	ds_read_b128 v[212:215], v151 offset:6144
	ds_read_b128 v[216:219], v151 offset:7168
	global_load_lds_dwordx4 v[144:145], off
	v_lshl_add_u64 v[144:145], s[36:37], 0, v[138:139]
	s_add_i32 m0, s35, 0xe000
	s_nop 0
	global_load_lds_dwordx4 v[144:145], off
	s_waitcnt vmcnt(24)
	s_waitcnt lgkmcnt(0)
	s_barrier
; #define PG8_STAGE(bufoff, gbase, voff) do { _Pragma("unroll") for (int _i = 0; _i < 2; ++_i) \
;     __builtin_amdgcn_global_load_lds((const unsigned*)((const char*)(gbase) + (voff)[_i]), (LAS unsigned*)(lds + (bufoff) + ldsw + _i * 8192), 16, 0, 0); } while (0)
; #define PG8_LDA(dst, b, h) do { _Pragma("unroll") for (int m = 0; m < 4; ++m) _Pragma("unroll") for (int k = 0; k < 2; ++k) dst[m][k] = *(const LAS bf16x8*)(lds + PG8_SA(b, h) + aoff + m * 2048 + k * 1024); } while (0)
; #define PG8_MMA(ai, bj, At, Bt) do { __builtin_amdgcn_s_setprio(1); _Pragma("unroll") for (int m = 0; m < 4; ++m) _Pragma("unroll") for (int n = 0; n < 2; ++n) _Pragma("unroll") for (int k = 0; k < 2; ++k) \
;     acc[ai][bj][m][n] = __builtin_amdgcn_mfma_f32_16x16x32_bf16(Bt[n][k], At[m][k], acc[ai][bj][m][n], 0, 0, 0); __builtin_amdgcn_s_setprio(0); } while (0)
; #define PG8_WAIT_V(n) asm volatile("s_waitcnt vmcnt(" #n ")" ::: "memory")
; #define PG8_WAIT_L(n) asm volatile("s_waitcnt lgkmcnt(" #n ")" ::: "memory")
; #define PG8_BAR __builtin_amdgcn_s_barrier()
; #define PG8_SCHED __builtin_amdgcn_sched_barrier(0)
; template <class Epi, class Sched, bool ALIGN_EPI = true>
; __device__ __forceinline__ void gemm_phase(LAS unsigned char* lds, const Gemm g, const Sched& S, const Epi& E) {
;     ...
;       PG8_WAIT_V(8); PG8_WAIT_L(0); PG8_BAR; PG8_MMA(0, 0, At, B0); PG8_MMA(0, 1, At, B1); PG8_BAR; PG8_SCHED;
;       PG8_LDA(At, 0, 1); PG8_STAGE(PG8_SB(0, 0), b2, voffB); PG8_STAGE(PG8_SB(0, 1), b2 + hstepB, voffB); PG8_STAGE(PG8_SA(0, 0), a2, voffA);
;       PG8_WAIT_V(8); PG8_WAIT_L(0); PG8_BAR; PG8_MMA(1, 0, At, B0); PG8_MMA(1, 1, At, B1); PG8_BAR; PG8_SCHED;
	s_setprio 1
	s_waitcnt lgkmcnt(0)
	v_mfma_f32_16x16x32_bf16 v[124:127], v[152:155], v[188:191], v[124:127]
	v_mfma_f32_16x16x32_bf16 v[120:123], v[160:163], v[188:191], v[120:123]
	v_mfma_f32_16x16x32_bf16 v[108:111], v[152:155], v[196:199], v[108:111]
	v_mfma_f32_16x16x32_bf16 v[104:107], v[160:163], v[196:199], v[104:107]
	v_mfma_f32_16x16x32_bf16 v[92:95], v[152:155], v[204:207], v[92:95]
	v_mfma_f32_16x16x32_bf16 v[88:91], v[160:163], v[204:207], v[88:91]
	v_mfma_f32_16x16x32_bf16 v[76:79], v[152:155], v[212:215], v[76:79]
	v_mfma_f32_16x16x32_bf16 v[72:75], v[160:163], v[212:215], v[72:75]
	v_mfma_f32_16x16x32_bf16 v[124:127], v[156:159], v[192:195], v[124:127]
	v_mfma_f32_16x16x32_bf16 v[120:123], v[164:167], v[192:195], v[120:123]
	v_mfma_f32_16x16x32_bf16 v[108:111], v[156:159], v[200:203], v[108:111]
	v_mfma_f32_16x16x32_bf16 v[104:107], v[164:167], v[200:203], v[104:107]
	v_mfma_f32_16x16x32_bf16 v[92:95], v[156:159], v[208:211], v[92:95]
	v_mfma_f32_16x16x32_bf16 v[88:91], v[164:167], v[208:211], v[88:91]
	v_mfma_f32_16x16x32_bf16 v[76:79], v[156:159], v[216:219], v[76:79]
	v_mfma_f32_16x16x32_bf16 v[72:75], v[164:167], v[216:219], v[72:75]
	s_setprio 0
	s_setprio 1
	v_mfma_f32_16x16x32_bf16 v[116:119], v[172:175], v[188:191], v[116:119]
	v_mfma_f32_16x16x32_bf16 v[112:115], v[180:183], v[188:191], v[112:115]
	v_mfma_f32_16x16x32_bf16 v[100:103], v[172:175], v[196:199], v[100:103]
	v_mfma_f32_16x16x32_bf16 v[96:99], v[180:183], v[196:199], v[96:99]
	v_mfma_f32_16x16x32_bf16 v[84:87], v[172:175], v[204:207], v[84:87]
	v_mfma_f32_16x16x32_bf16 v[80:83], v[180:183], v[204:207], v[80:83]
	v_mfma_f32_16x16x32_bf16 v[68:71], v[172:175], v[212:215], v[68:71]
	v_mfma_f32_16x16x32_bf16 v[64:67], v[180:183], v[212:215], v[64:67]
	v_mfma_f32_16x16x32_bf16 v[116:119], v[176:179], v[192:195], v[116:119]
	v_mfma_f32_16x16x32_bf16 v[112:115], v[184:187], v[192:195], v[112:115]
	v_mfma_f32_16x16x32_bf16 v[100:103], v[176:179], v[200:203], v[100:103]
	v_mfma_f32_16x16x32_bf16 v[96:99], v[184:187], v[200:203], v[96:99]
	v_mfma_f32_16x16x32_bf16 v[84:87], v[176:179], v[208:211], v[84:87]
	v_mfma_f32_16x16x32_bf16 v[80:83], v[184:187], v[208:211], v[80:83]
	v_mfma_f32_16x16x32_bf16 v[68:71], v[176:179], v[216:219], v[68:71]
	v_mfma_f32_16x16x32_bf16 v[64:67], v[184:187], v[216:219], v[64:67]
	s_setprio 0
	s_barrier
	s_add_i32 s62, s50, s2
	v_lshl_add_u64 v[144:145], s[38:39], 0, v[132:133]
	s_mov_b32 m0, s62
	ds_read_b128 v[188:191], v151 offset:16384
	ds_read_b128 v[192:195], v151 offset:17408
	ds_read_b128 v[196:199], v151 offset:18432
	ds_read_b128 v[200:203], v151 offset:19456
	ds_read_b128 v[204:207], v151 offset:20480
	ds_read_b128 v[208:211], v151 offset:21504
	ds_read_b128 v[212:215], v151 offset:22528
	ds_read_b128 v[216:219], v151 offset:23552
	global_load_lds_dwordx4 v[144:145], off
	s_add_i32 m0, s62, 0x2000
	s_add_u32 s62, s38, 0x80000
	v_lshl_add_u64 v[168:169], s[38:39], 0, v[128:129]
	s_addc_u32 s63, s39, 0
	s_add_i32 s64, s51, s2
	global_load_lds_dwordx4 v[168:169], off
	v_lshl_add_u64 v[220:221], s[62:63], 0, v[132:133]
	s_mov_b32 m0, s64
	v_lshl_add_u64 v[222:223], s[40:41], 0, v[130:131]
	global_load_lds_dwordx4 v[220:221], off
	v_lshl_add_u64 v[220:221], s[62:63], 0, v[128:129]
	s_add_i32 m0, s64, 0x2000
	s_nop 0
	global_load_lds_dwordx4 v[220:221], off
	v_lshl_add_u64 v[220:221], s[40:41], 0, v[134:135]
	s_mov_b32 m0, s35
	s_nop 0
	global_load_lds_dwordx4 v[220:221], off
	s_mov_b32 m0, s42
	s_nop 0
	global_load_lds_dwordx4 v[222:223], off
	s_waitcnt vmcnt(24)
	s_waitcnt lgkmcnt(0)
	s_barrier
	s_setprio 1
	s_waitcnt lgkmcnt(0)
	v_mfma_f32_16x16x32_bf16 v[60:63], v[152:155], v[188:191], v[60:63]
	v_mfma_f32_16x16x32_bf16 v[56:59], v[160:163], v[188:191], v[56:59]
	v_mfma_f32_16x16x32_bf16 v[44:47], v[152:155], v[196:199], v[44:47]
	v_mfma_f32_16x16x32_bf16 v[40:43], v[160:163], v[196:199], v[40:43]
	v_mfma_f32_16x16x32_bf16 v[28:31], v[152:155], v[204:207], v[28:31]
	v_mfma_f32_16x16x32_bf16 v[24:27], v[160:163], v[204:207], v[24:27]
	v_mfma_f32_16x16x32_bf16 v[12:15], v[152:155], v[212:215], v[12:15]
	v_mfma_f32_16x16x32_bf16 v[8:11], v[160:163], v[212:215], v[8:11]
	v_mfma_f32_16x16x32_bf16 v[60:63], v[156:159], v[192:195], v[60:63]
	v_mfma_f32_16x16x32_bf16 v[56:59], v[164:167], v[192:195], v[56:59]
	v_mfma_f32_16x16x32_bf16 v[44:47], v[156:159], v[200:203], v[44:47]
	v_mfma_f32_16x16x32_bf16 v[40:43], v[164:167], v[200:203], v[40:43]
	v_mfma_f32_16x16x32_bf16 v[28:31], v[156:159], v[208:211], v[28:31]
	v_mfma_f32_16x16x32_bf16 v[24:27], v[164:167], v[208:211], v[24:27]
	v_mfma_f32_16x16x32_bf16 v[12:15], v[156:159], v[216:219], v[12:15]
	v_mfma_f32_16x16x32_bf16 v[8:11], v[164:167], v[216:219], v[8:11]
	s_setprio 0
	s_setprio 1
	v_mfma_f32_16x16x32_bf16 v[52:55], v[172:175], v[188:191], v[52:55]
	v_mfma_f32_16x16x32_bf16 v[48:51], v[180:183], v[188:191], v[48:51]
	v_mfma_f32_16x16x32_bf16 v[36:39], v[172:175], v[196:199], v[36:39]
	v_mfma_f32_16x16x32_bf16 v[32:35], v[180:183], v[196:199], v[32:35]
	v_mfma_f32_16x16x32_bf16 v[20:23], v[172:175], v[204:207], v[20:23]
	v_mfma_f32_16x16x32_bf16 v[16:19], v[180:183], v[204:207], v[16:19]
	v_mfma_f32_16x16x32_bf16 v[4:7], v[172:175], v[212:215], v[4:7]
	v_mfma_f32_16x16x32_bf16 v[0:3], v[180:183], v[212:215], v[0:3]
	v_mfma_f32_16x16x32_bf16 v[52:55], v[176:179], v[192:195], v[52:55]
	v_mfma_f32_16x16x32_bf16 v[48:51], v[184:187], v[192:195], v[48:51]
	v_mfma_f32_16x16x32_bf16 v[36:39], v[176:179], v[200:203], v[36:39]
	v_mfma_f32_16x16x32_bf16 v[32:35], v[184:187], v[200:203], v[32:35]
	v_mfma_f32_16x16x32_bf16 v[20:23], v[176:179], v[208:211], v[20:23]
	v_mfma_f32_16x16x32_bf16 v[16:19], v[184:187], v[208:211], v[16:19]
	v_mfma_f32_16x16x32_bf16 v[4:7], v[176:179], v[216:219], v[4:7]
	v_mfma_f32_16x16x32_bf16 v[0:3], v[184:187], v[216:219], v[0:3]
	s_setprio 0
	s_barrier
	s_branch .Lpeel_mid_1601

; #define PG8_STAGE(bufoff, gbase, voff) do { _Pragma("unroll") for (int _i = 0; _i < 2; ++_i) \
;     __builtin_amdgcn_global_load_lds((const unsigned*)((const char*)(gbase) + (voff)[_i]), (LAS unsigned*)(lds + (bufoff) + ldsw + _i * 8192), 16, 0, 0); } while (0)
; #define PG8_LDA(dst, b, h) do { _Pragma("unroll") for (int m = 0; m < 4; ++m) _Pragma("unroll") for (int k = 0; k < 2; ++k) dst[m][k] = *(const LAS bf16x8*)(lds + PG8_SA(b, h) + aoff + m * 2048 + k * 1024); } while (0)
; #define PG8_LDB(dst, b, h) do { _Pragma("unroll") for (int n = 0; n < 2; ++n) _Pragma("unroll") for (int k = 0; k < 2; ++k) dst[n][k] = *(const LAS bf16x8*)(lds + PG8_SB(b, h) + boff + n * 2048 + k * 1024); } while (0)
; #define PG8_MMA(ai, bj, At, Bt) do { __builtin_amdgcn_s_setprio(1); _Pragma("unroll") for (int m = 0; m < 4; ++m) _Pragma("unroll") for (int n = 0; n < 2; ++n) _Pragma("unroll") for (int k = 0; k < 2; ++k) \
;     acc[ai][bj][m][n] = __builtin_amdgcn_mfma_f32_16x16x32_bf16(Bt[n][k], At[m][k], acc[ai][bj][m][n], 0, 0, 0); __builtin_amdgcn_s_setprio(0); } while (0)
; #define PG8_WAIT_V(n) asm volatile("s_waitcnt vmcnt(" #n ")" ::: "memory")
; #define PG8_WAIT_L(n) asm volatile("s_waitcnt lgkmcnt(" #n ")" ::: "memory")
; #define PG8_BAR __builtin_amdgcn_s_barrier()
; #define PG8_SCHED __builtin_amdgcn_sched_barrier(0)
; template <class Epi, class Sched, bool ALIGN_EPI = true>
; __device__ __forceinline__ void gemm_phase(LAS unsigned char* lds, const Gemm g, const Sched& S, const Epi& E) {
;     ...
;       PG8_LDB(B0, 1, 0); PG8_LDB(B1, 1, 1); PG8_SCHED; PG8_LDA(At, 1, 0); PG8_STAGE(PG8_SA(0, 1), a2 + hstepA, voffA);
;       PG8_WAIT_V(8); PG8_WAIT_L(0); PG8_BAR; PG8_MMA(0, 0, At, B0); PG8_MMA(0, 1, At, B1); PG8_BAR; PG8_SCHED;
.Lpeel_mid_1601:
	s_add_i32 s62, 0, 0x18000
	s_add_i32 s63, 0, 0x1c000
	v_add_u32_e32 v164, s62, v147
	v_add_u32_e32 v184, s63, v147
	ds_read_b128 v[152:155], v164
	ds_read_b128 v[156:159], v164 offset:1024
	ds_read_b128 v[160:163], v164 offset:2048
	ds_read_b128 v[164:167], v164 offset:3072
	ds_read_b128 v[172:175], v184
	ds_read_b128 v[176:179], v184 offset:1024
	ds_read_b128 v[180:183], v184 offset:2048
	ds_read_b128 v[184:187], v184 offset:3072
	s_add_u32 s40, s40, 0x80000
	s_addc_u32 s41, s41, 0
	s_mov_b32 m0, s43
	v_lshl_add_u64 v[224:225], s[40:41], 0, v[134:135]
	ds_read_b128 v[188:191], v151 offset:32768
	ds_read_b128 v[192:195], v151 offset:33792
	ds_read_b128 v[196:199], v151 offset:34816
	ds_read_b128 v[200:203], v151 offset:35840
	ds_read_b128 v[204:207], v151 offset:36864
	ds_read_b128 v[208:211], v151 offset:37888
	ds_read_b128 v[212:215], v151 offset:38912
	ds_read_b128 v[216:219], v151 offset:39936
	global_load_lds_dwordx4 v[224:225], off
	v_lshl_add_u64 v[224:225], s[40:41], 0, v[130:131]
	s_mov_b32 m0, s44
	s_nop 0
	global_load_lds_dwordx4 v[224:225], off
	s_waitcnt vmcnt(8)
	s_waitcnt lgkmcnt(0)
	s_barrier
	s_setprio 1
	s_waitcnt lgkmcnt(0)
	v_mfma_f32_16x16x32_bf16 v[124:127], v[152:155], v[188:191], v[124:127]
	v_mfma_f32_16x16x32_bf16 v[120:123], v[160:163], v[188:191], v[120:123]
	v_mfma_f32_16x16x32_bf16 v[108:111], v[152:155], v[196:199], v[108:111]
	v_mfma_f32_16x16x32_bf16 v[104:107], v[160:163], v[196:199], v[104:107]
	v_mfma_f32_16x16x32_bf16 v[92:95], v[152:155], v[204:207], v[92:95]
	v_mfma_f32_16x16x32_bf16 v[88:91], v[160:163], v[204:207], v[88:91]
	v_mfma_f32_16x16x32_bf16 v[76:79], v[152:155], v[212:215], v[76:79]
	v_mfma_f32_16x16x32_bf16 v[72:75], v[160:163], v[212:215], v[72:75]
	v_mfma_f32_16x16x32_bf16 v[124:127], v[156:159], v[192:195], v[124:127]
	v_mfma_f32_16x16x32_bf16 v[120:123], v[164:167], v[192:195], v[120:123]
	v_mfma_f32_16x16x32_bf16 v[108:111], v[156:159], v[200:203], v[108:111]
	v_mfma_f32_16x16x32_bf16 v[104:107], v[164:167], v[200:203], v[104:107]
	v_mfma_f32_16x16x32_bf16 v[92:95], v[156:159], v[208:211], v[92:95]
	v_mfma_f32_16x16x32_bf16 v[88:91], v[164:167], v[208:211], v[88:91]
	v_mfma_f32_16x16x32_bf16 v[76:79], v[156:159], v[216:219], v[76:79]
	v_mfma_f32_16x16x32_bf16 v[72:75], v[164:167], v[216:219], v[72:75]
	s_setprio 0
	s_setprio 1
	v_mfma_f32_16x16x32_bf16 v[116:119], v[172:175], v[188:191], v[116:119]
	v_mfma_f32_16x16x32_bf16 v[112:115], v[180:183], v[188:191], v[112:115]
	v_mfma_f32_16x16x32_bf16 v[100:103], v[172:175], v[196:199], v[100:103]
	v_mfma_f32_16x16x32_bf16 v[96:99], v[180:183], v[196:199], v[96:99]
	v_mfma_f32_16x16x32_bf16 v[84:87], v[172:175], v[204:207], v[84:87]
	v_mfma_f32_16x16x32_bf16 v[80:83], v[180:183], v[204:207], v[80:83]
	v_mfma_f32_16x16x32_bf16 v[68:71], v[172:175], v[212:215], v[68:71]
	v_mfma_f32_16x16x32_bf16 v[64:67], v[180:183], v[212:215], v[64:67]
	v_mfma_f32_16x16x32_bf16 v[116:119], v[176:179], v[192:195], v[116:119]
	v_mfma_f32_16x16x32_bf16 v[112:115], v[184:187], v[192:195], v[112:115]
	v_mfma_f32_16x16x32_bf16 v[100:103], v[176:179], v[200:203], v[100:103]
	v_mfma_f32_16x16x32_bf16 v[96:99], v[184:187], v[200:203], v[96:99]
	v_mfma_f32_16x16x32_bf16 v[84:87], v[176:179], v[208:211], v[84:87]
	v_mfma_f32_16x16x32_bf16 v[80:83], v[184:187], v[208:211], v[80:83]
	v_mfma_f32_16x16x32_bf16 v[68:71], v[176:179], v[216:219], v[68:71]
	v_mfma_f32_16x16x32_bf16 v[64:67], v[184:187], v[216:219], v[64:67]
	s_setprio 0
	s_barrier
; #define PG8_STAGE(bufoff, gbase, voff) do { _Pragma("unroll") for (int _i = 0; _i < 2; ++_i) \
;     __builtin_amdgcn_global_load_lds((const unsigned*)((const char*)(gbase) + (voff)[_i]), (LAS unsigned*)(lds + (bufoff) + ldsw + _i * 8192), 16, 0, 0); } while (0)
; #define PG8_LDA(dst, b, h) do { _Pragma("unroll") for (int m = 0; m < 4; ++m) _Pragma("unroll") for (int k = 0; k < 2; ++k) dst[m][k] = *(const LAS bf16x8*)(lds + PG8_SA(b, h) + aoff + m * 2048 + k * 1024); } while (0)
; #define PG8_MMA(ai, bj, At, Bt) do { __builtin_amdgcn_s_setprio(1); _Pragma("unroll") for (int m = 0; m < 4; ++m) _Pragma("unroll") for (int n = 0; n < 2; ++n) _Pragma("unroll") for (int k = 0; k < 2; ++k) \
;     acc[ai][bj][m][n] = __builtin_amdgcn_mfma_f32_16x16x32_bf16(Bt[n][k], At[m][k], acc[ai][bj][m][n], 0, 0, 0); __builtin_amdgcn_s_setprio(0); } while (0)
; #define PG8_WAIT_V(n) asm volatile("s_waitcnt vmcnt(" #n ")" ::: "memory")
; #define PG8_WAIT_L(n) asm volatile("s_waitcnt lgkmcnt(" #n ")" ::: "memory")
; #define PG8_BAR __builtin_amdgcn_s_barrier()
; #define PG8_SCHED __builtin_amdgcn_sched_barrier(0)
; template <class Epi, class Sched, bool ALIGN_EPI = true>
; __device__ __forceinline__ void gemm_phase(LAS unsigned char* lds, const Gemm g, const Sched& S, const Epi& E) {
;     ...
;       PG8_LDA(At, 1, 1); PG8_STAGE(PG8_SB(1, 0), b3, voffB); PG8_STAGE(PG8_SB(1, 1), b3 + hstepB, voffB); PG8_STAGE(PG8_SA(1, 0), a3, voffA);
;       PG8_WAIT_V(8); PG8_WAIT_L(0); PG8_BAR; PG8_MMA(1, 0, At, B0); PG8_MMA(1, 1, At, B1); PG8_BAR; PG8_SCHED;
;     }
;     if constexpr (ALIGN_EPI) { if (wr == 0) PG8_BAR; }
	s_add_i32 s40, s62, s2
	v_lshl_add_u64 v[144:145], v[144:145], 0, s[10:11]
	s_mov_b32 m0, s40
	ds_read_b128 v[188:191], v151 offset:49152
	ds_read_b128 v[192:195], v151 offset:50176
	ds_read_b128 v[196:199], v151 offset:51200
	ds_read_b128 v[200:203], v151 offset:52224
	ds_read_b128 v[204:207], v151 offset:53248
	ds_read_b128 v[208:211], v151 offset:54272
	ds_read_b128 v[212:215], v151 offset:55296
	ds_read_b128 v[216:219], v151 offset:56320
	global_load_lds_dwordx4 v[144:145], off
	s_add_i32 m0, s40, 0x2000
	s_add_u32 s38, s38, 0x80080
	v_lshl_add_u64 v[144:145], v[168:169], 0, s[10:11]
	s_addc_u32 s39, s39, 0
	s_add_i32 s40, s63, s2
	global_load_lds_dwordx4 v[144:145], off
	v_lshl_add_u64 v[144:145], s[38:39], 0, v[132:133]
	s_mov_b32 m0, s40
	s_nop 0
	global_load_lds_dwordx4 v[144:145], off
	v_lshl_add_u64 v[144:145], s[38:39], 0, v[128:129]
	s_add_i32 m0, s40, 0x2000
	s_nop 0
	global_load_lds_dwordx4 v[144:145], off
	v_lshl_add_u64 v[144:145], v[220:221], 0, s[10:11]
	s_mov_b32 m0, s46
	s_nop 0
	global_load_lds_dwordx4 v[144:145], off
	v_lshl_add_u64 v[144:145], v[222:223], 0, s[10:11]
	s_mov_b32 m0, s47
	s_nop 0
	global_load_lds_dwordx4 v[144:145], off
	s_waitcnt vmcnt(8)
	s_waitcnt lgkmcnt(0)
	s_barrier
	s_setprio 1
	s_waitcnt lgkmcnt(0)
	v_mfma_f32_16x16x32_bf16 v[60:63], v[152:155], v[188:191], v[60:63]
	v_mfma_f32_16x16x32_bf16 v[56:59], v[160:163], v[188:191], v[56:59]
	v_mfma_f32_16x16x32_bf16 v[44:47], v[152:155], v[196:199], v[44:47]
	v_mfma_f32_16x16x32_bf16 v[40:43], v[160:163], v[196:199], v[40:43]
	v_mfma_f32_16x16x32_bf16 v[28:31], v[152:155], v[204:207], v[28:31]
	v_mfma_f32_16x16x32_bf16 v[24:27], v[160:163], v[204:207], v[24:27]
	v_mfma_f32_16x16x32_bf16 v[12:15], v[152:155], v[212:215], v[12:15]
	v_mfma_f32_16x16x32_bf16 v[8:11], v[160:163], v[212:215], v[8:11]
	v_mfma_f32_16x16x32_bf16 v[60:63], v[156:159], v[192:195], v[60:63]
	v_mfma_f32_16x16x32_bf16 v[56:59], v[164:167], v[192:195], v[56:59]
	v_mfma_f32_16x16x32_bf16 v[44:47], v[156:159], v[200:203], v[44:47]
	v_mfma_f32_16x16x32_bf16 v[40:43], v[164:167], v[200:203], v[40:43]
	v_mfma_f32_16x16x32_bf16 v[28:31], v[156:159], v[208:211], v[28:31]
	v_mfma_f32_16x16x32_bf16 v[24:27], v[164:167], v[208:211], v[24:27]
	v_mfma_f32_16x16x32_bf16 v[12:15], v[156:159], v[216:219], v[12:15]
	v_mfma_f32_16x16x32_bf16 v[8:11], v[164:167], v[216:219], v[8:11]
	s_setprio 0
	s_setprio 1
	v_mfma_f32_16x16x32_bf16 v[52:55], v[172:175], v[188:191], v[52:55]
	v_mfma_f32_16x16x32_bf16 v[48:51], v[180:183], v[188:191], v[48:51]
	v_mfma_f32_16x16x32_bf16 v[36:39], v[172:175], v[196:199], v[36:39]
	v_mfma_f32_16x16x32_bf16 v[32:35], v[180:183], v[196:199], v[32:35]
	v_mfma_f32_16x16x32_bf16 v[20:23], v[172:175], v[204:207], v[20:23]
	v_mfma_f32_16x16x32_bf16 v[16:19], v[180:183], v[204:207], v[16:19]
	v_mfma_f32_16x16x32_bf16 v[4:7], v[172:175], v[212:215], v[4:7]
	v_mfma_f32_16x16x32_bf16 v[0:3], v[180:183], v[212:215], v[0:3]
	v_mfma_f32_16x16x32_bf16 v[52:55], v[176:179], v[192:195], v[52:55]
	v_mfma_f32_16x16x32_bf16 v[48:51], v[184:187], v[192:195], v[48:51]
	v_mfma_f32_16x16x32_bf16 v[36:39], v[176:179], v[200:203], v[36:39]
	v_mfma_f32_16x16x32_bf16 v[32:35], v[184:187], v[200:203], v[32:35]
	v_mfma_f32_16x16x32_bf16 v[20:23], v[176:179], v[208:211], v[20:23]
	v_mfma_f32_16x16x32_bf16 v[16:19], v[184:187], v[208:211], v[16:19]
	v_mfma_f32_16x16x32_bf16 v[4:7], v[176:179], v[216:219], v[4:7]
	v_mfma_f32_16x16x32_bf16 v[0:3], v[184:187], v[216:219], v[0:3]
	s_setprio 0
	s_barrier
	s_add_i32 s61, s61, 2
	s_add_u32 s36, s36, 0x100
	s_addc_u32 s37, s37, 0
	s_add_u32 s59, s59, 0x100
	s_addc_u32 s60, s60, 0
	s_cmp_gt_u32 s61, 29
	s_cbranch_scc0 .LBB0_1601
	s_mov_b32 s98, 1
	s_and_b64 vcc, exec, s[12:13]
	s_cbranch_vccz .LBB0_1604
	s_barrier

; __global__ void __launch_bounds__(512, 2) fwd_megakernel(Params p) {
;   extern __shared__ __attribute__((aligned(16))) char shm[];
;   cg::grid_group grid = cg::this_grid();
	.amdhsa_kernel _Z14fwd_megakernel6Params
		.amdhsa_group_segment_fixed_size 0
		.amdhsa_private_segment_fixed_size 0
		.amdhsa_kernarg_size 560
		.amdhsa_user_sgpr_count 2
		.amdhsa_user_sgpr_dispatch_ptr 0
		.amdhsa_user_sgpr_queue_ptr 0
		.amdhsa_user_sgpr_kernarg_segment_ptr 1
		.amdhsa_user_sgpr_dispatch_id 0
		.amdhsa_user_sgpr_kernarg_preload_length 0
		.amdhsa_user_sgpr_kernarg_preload_offset 0
		.amdhsa_user_sgpr_private_segment_size 0
		.amdhsa_uses_dynamic_stack 0
		.amdhsa_enable_private_segment 0
		.amdhsa_system_sgpr_workgroup_id_x 1
		.amdhsa_system_sgpr_workgroup_id_y 0
		.amdhsa_system_sgpr_workgroup_id_z 0
		.amdhsa_system_sgpr_workgroup_info 0
		.amdhsa_system_vgpr_workitem_id 2
		.amdhsa_next_free_vgpr 252
		.amdhsa_next_free_sgpr 102
		.amdhsa_accum_offset 252
		.amdhsa_reserve_vcc 1
		.amdhsa_float_round_mode_32 0
		.amdhsa_float_round_mode_16_64 0
		.amdhsa_float_denorm_mode_32 3
		.amdhsa_float_denorm_mode_16_64 3
		.amdhsa_dx10_clamp 1
		.amdhsa_ieee_mode 1
		.amdhsa_fp16_overflow 0
		.amdhsa_tg_split 0
		.amdhsa_exception_fp_ieee_invalid_op 0
		.amdhsa_exception_fp_denorm_src 0
		.amdhsa_exception_fp_ieee_div_zero 0
		.amdhsa_exception_fp_ieee_overflow 0
		.amdhsa_exception_fp_ieee_underflow 0
		.amdhsa_exception_fp_ieee_inexact 0
		.amdhsa_exception_int_div_zero 0
	.end_amdhsa_kernel

; __global__ void __launch_bounds__(512, 2) fwd_megakernel(Params p) {
;   extern __shared__ __attribute__((aligned(16))) char shm[];
amdhsa.kernels:
  - .agpr_count:     0
    .args:
      - .offset:         0
        .size:           304
        .value_kind:     by_value
      - .offset:         304
        .size:           4
        .value_kind:     hidden_block_count_x
      - .offset:         308
        .size:           4
        .value_kind:     hidden_block_count_y
      - .offset:         312
        .size:           4
        .value_kind:     hidden_block_count_z
      - .offset:         316
        .size:           2
        .value_kind:     hidden_group_size_x
      - .offset:         318
        .size:           2
        .value_kind:     hidden_group_size_y
      - .offset:         320
        .size:           2
        .value_kind:     hidden_group_size_z
      - .offset:         322
        .size:           2
        .value_kind:     hidden_remainder_x
      - .offset:         324
        .size:           2
        .value_kind:     hidden_remainder_y
      - .offset:         326
        .size:           2
        .value_kind:     hidden_remainder_z
      - .offset:         344
        .size:           8
        .value_kind:     hidden_global_offset_x
      - .offset:         352
        .size:           8
        .value_kind:     hidden_global_offset_y
      - .offset:         360
        .size:           8
        .value_kind:     hidden_global_offset_z
      - .offset:         368
        .size:           2
        .value_kind:     hidden_grid_dims
      - .offset:         392
        .size:           8
        .value_kind:     hidden_multigrid_sync_arg
      - .offset:         424
        .size:           4
        .value_kind:     hidden_dynamic_lds_size
    .group_segment_fixed_size: 0
    .kernarg_segment_align: 8
    .kernarg_segment_size: 560
    .language:       OpenCL C
    .language_version:
      - 2
      - 0
    .max_flat_workgroup_size: 512
    .name:           _Z14fwd_megakernel6Params
    .private_segment_fixed_size: 0
    .sgpr_count:     108
    .sgpr_spill_count: 50
    .symbol:         _Z14fwd_megakernel6Params.kd
    .uniform_work_group_size: 1
    .uses_dynamic_stack: false
    .vgpr_count:     252
    .vgpr_spill_count: 0
    .wavefront_size: 64
